# mlp1 epilogue loads hoisted + coalesced stores; attention QK/PV LDS fragment reads issued up front; prep composed-gate aux loads hoisted; G2 LRU cross-chunk scan loads batched
# speedup vs baseline: 1.0181x; 1.0181x over previous
.LBB0_126:
	s_mov_b64 s[38:39], 0x1000
	v_add_co_u32_e32 v10, vcc, 0x1a500000, v4
	s_nop 1
	v_addc_co_u32_e32 v11, vcc, 0, v5, vcc
	v_add_co_u32_e32 v12, vcc, 0x1a600000, v4
	s_nop 1
	v_addc_co_u32_e32 v13, vcc, 0, v5, vcc
	v_add_co_u32_e32 v14, vcc, 0x1a700000, v4
	s_nop 1
	v_addc_co_u32_e32 v15, vcc, 0, v5, vcc
	global_load_dword v64, v[10:11], off
	global_load_dword v65, v[10:11], off offset:2048
	global_load_dword v80, v[12:13], off
	global_load_dword v81, v[12:13], off offset:2048
	v_lshl_add_u64 v[10:11], v[10:11], 0, s[38:39]
	v_lshl_add_u64 v[12:13], v[12:13], 0, s[38:39]
	global_load_dword v66, v[10:11], off
	global_load_dword v67, v[10:11], off offset:2048
	global_load_dword v82, v[12:13], off
	global_load_dword v83, v[12:13], off offset:2048
	v_lshl_add_u64 v[10:11], v[10:11], 0, s[38:39]
	v_lshl_add_u64 v[12:13], v[12:13], 0, s[38:39]
	global_load_dword v68, v[10:11], off
	global_load_dword v69, v[10:11], off offset:2048
	global_load_dword v84, v[12:13], off
	global_load_dword v85, v[12:13], off offset:2048
	v_lshl_add_u64 v[10:11], v[10:11], 0, s[38:39]
	v_lshl_add_u64 v[12:13], v[12:13], 0, s[38:39]
	global_load_dword v70, v[10:11], off
	global_load_dword v71, v[10:11], off offset:2048
	global_load_dword v86, v[12:13], off
	global_load_dword v87, v[12:13], off offset:2048
	v_lshl_add_u64 v[10:11], v[10:11], 0, s[38:39]
	v_lshl_add_u64 v[12:13], v[12:13], 0, s[38:39]
	global_load_dword v72, v[10:11], off
	global_load_dword v73, v[10:11], off offset:2048
	global_load_dword v88, v[12:13], off
	global_load_dword v89, v[12:13], off offset:2048
	v_lshl_add_u64 v[10:11], v[10:11], 0, s[38:39]
	v_lshl_add_u64 v[12:13], v[12:13], 0, s[38:39]
	global_load_dword v74, v[10:11], off
	global_load_dword v75, v[10:11], off offset:2048
	global_load_dword v90, v[12:13], off
	global_load_dword v91, v[12:13], off offset:2048
	v_lshl_add_u64 v[10:11], v[10:11], 0, s[38:39]
	v_lshl_add_u64 v[12:13], v[12:13], 0, s[38:39]
	global_load_dword v76, v[10:11], off
	global_load_dword v77, v[10:11], off offset:2048
	global_load_dword v92, v[12:13], off
	global_load_dword v93, v[12:13], off offset:2048
	v_lshl_add_u64 v[10:11], v[10:11], 0, s[38:39]
	v_lshl_add_u64 v[12:13], v[12:13], 0, s[38:39]
	global_load_dword v78, v[10:11], off
	global_load_dword v79, v[10:11], off offset:2048
	global_load_dword v94, v[12:13], off
	global_load_dword v95, v[12:13], off offset:2048
	v_lshl_add_u64 v[10:11], v[10:11], 0, s[38:39]
	v_lshl_add_u64 v[12:13], v[12:13], 0, s[38:39]
	s_waitcnt vmcnt(0)
	global_store_dword v[14:15], v8, off
	v_fmac_f32_e32 v80, v8, v64
	global_store_dword v[14:15], v80, off offset:2048
	v_fmac_f32_e32 v81, v80, v65
	v_mov_b32_e32 v8, v81
	v_lshl_add_u64 v[14:15], v[14:15], 0, s[38:39]
	global_store_dword v[14:15], v8, off
	v_fmac_f32_e32 v82, v8, v66
	global_store_dword v[14:15], v82, off offset:2048
	v_fmac_f32_e32 v83, v82, v67
	v_mov_b32_e32 v8, v83
	v_lshl_add_u64 v[14:15], v[14:15], 0, s[38:39]
	global_store_dword v[14:15], v8, off
	v_fmac_f32_e32 v84, v8, v68
	global_store_dword v[14:15], v84, off offset:2048
	v_fmac_f32_e32 v85, v84, v69
	v_mov_b32_e32 v8, v85
	v_lshl_add_u64 v[14:15], v[14:15], 0, s[38:39]
	global_store_dword v[14:15], v8, off
	v_fmac_f32_e32 v86, v8, v70
	global_store_dword v[14:15], v86, off offset:2048
	v_fmac_f32_e32 v87, v86, v71
	v_mov_b32_e32 v8, v87
	v_lshl_add_u64 v[14:15], v[14:15], 0, s[38:39]
	global_store_dword v[14:15], v8, off
	v_fmac_f32_e32 v88, v8, v72
	global_store_dword v[14:15], v88, off offset:2048
	v_fmac_f32_e32 v89, v88, v73
	v_mov_b32_e32 v8, v89
	v_lshl_add_u64 v[14:15], v[14:15], 0, s[38:39]
	global_store_dword v[14:15], v8, off
	v_fmac_f32_e32 v90, v8, v74
	global_store_dword v[14:15], v90, off offset:2048
	v_fmac_f32_e32 v91, v90, v75
	v_mov_b32_e32 v8, v91
	v_lshl_add_u64 v[14:15], v[14:15], 0, s[38:39]
	global_store_dword v[14:15], v8, off
	v_fmac_f32_e32 v92, v8, v76
	global_store_dword v[14:15], v92, off offset:2048
	v_fmac_f32_e32 v93, v92, v77
	v_mov_b32_e32 v8, v93
	v_lshl_add_u64 v[14:15], v[14:15], 0, s[38:39]
	global_store_dword v[14:15], v8, off
	v_fmac_f32_e32 v94, v8, v78
	global_store_dword v[14:15], v94, off offset:2048
	v_fmac_f32_e32 v95, v94, v79
	v_mov_b32_e32 v8, v95
	v_lshl_add_u64 v[14:15], v[14:15], 0, s[38:39]
	s_waitcnt vmcnt(24)
	global_load_dword v64, v[10:11], off
	global_load_dword v65, v[10:11], off offset:2048
	global_load_dword v80, v[12:13], off
	global_load_dword v81, v[12:13], off offset:2048
	v_lshl_add_u64 v[10:11], v[10:11], 0, s[38:39]
	v_lshl_add_u64 v[12:13], v[12:13], 0, s[38:39]
	global_load_dword v66, v[10:11], off
	global_load_dword v67, v[10:11], off offset:2048
	global_load_dword v82, v[12:13], off
	global_load_dword v83, v[12:13], off offset:2048
	v_lshl_add_u64 v[10:11], v[10:11], 0, s[38:39]
	v_lshl_add_u64 v[12:13], v[12:13], 0, s[38:39]
	global_load_dword v68, v[10:11], off
	global_load_dword v69, v[10:11], off offset:2048
	global_load_dword v84, v[12:13], off
	global_load_dword v85, v[12:13], off offset:2048
	v_lshl_add_u64 v[10:11], v[10:11], 0, s[38:39]
	v_lshl_add_u64 v[12:13], v[12:13], 0, s[38:39]
	global_load_dword v70, v[10:11], off
	global_load_dword v71, v[10:11], off offset:2048
	global_load_dword v86, v[12:13], off
	global_load_dword v87, v[12:13], off offset:2048
	v_lshl_add_u64 v[10:11], v[10:11], 0, s[38:39]
	v_lshl_add_u64 v[12:13], v[12:13], 0, s[38:39]
	global_load_dword v72, v[10:11], off
	global_load_dword v73, v[10:11], off offset:2048
	global_load_dword v88, v[12:13], off
	global_load_dword v89, v[12:13], off offset:2048
	v_lshl_add_u64 v[10:11], v[10:11], 0, s[38:39]
	v_lshl_add_u64 v[12:13], v[12:13], 0, s[38:39]
	global_load_dword v74, v[10:11], off
	global_load_dword v75, v[10:11], off offset:2048
	global_load_dword v90, v[12:13], off
	global_load_dword v91, v[12:13], off offset:2048
	v_lshl_add_u64 v[10:11], v[10:11], 0, s[38:39]
	v_lshl_add_u64 v[12:13], v[12:13], 0, s[38:39]
	global_load_dword v76, v[10:11], off
	global_load_dword v77, v[10:11], off offset:2048
	global_load_dword v92, v[12:13], off
	global_load_dword v93, v[12:13], off offset:2048
	v_lshl_add_u64 v[10:11], v[10:11], 0, s[38:39]
	v_lshl_add_u64 v[12:13], v[12:13], 0, s[38:39]
	global_load_dword v78, v[10:11], off
	global_load_dword v79, v[10:11], off offset:2048
	global_load_dword v94, v[12:13], off
	global_load_dword v95, v[12:13], off offset:2048
	v_lshl_add_u64 v[10:11], v[10:11], 0, s[38:39]
	v_lshl_add_u64 v[12:13], v[12:13], 0, s[38:39]
	s_waitcnt vmcnt(0)
	global_store_dword v[14:15], v8, off
	v_fmac_f32_e32 v80, v8, v64
	global_store_dword v[14:15], v80, off offset:2048
	v_fmac_f32_e32 v81, v80, v65
	v_mov_b32_e32 v8, v81
	v_lshl_add_u64 v[14:15], v[14:15], 0, s[38:39]
	global_store_dword v[14:15], v8, off
	v_fmac_f32_e32 v82, v8, v66
	global_store_dword v[14:15], v82, off offset:2048
	v_fmac_f32_e32 v83, v82, v67
	v_mov_b32_e32 v8, v83
	v_lshl_add_u64 v[14:15], v[14:15], 0, s[38:39]
	global_store_dword v[14:15], v8, off
	v_fmac_f32_e32 v84, v8, v68
	global_store_dword v[14:15], v84, off offset:2048
	v_fmac_f32_e32 v85, v84, v69
	v_mov_b32_e32 v8, v85
	v_lshl_add_u64 v[14:15], v[14:15], 0, s[38:39]
	global_store_dword v[14:15], v8, off
	v_fmac_f32_e32 v86, v8, v70
	global_store_dword v[14:15], v86, off offset:2048
	v_fmac_f32_e32 v87, v86, v71
	v_mov_b32_e32 v8, v87
	v_lshl_add_u64 v[14:15], v[14:15], 0, s[38:39]
	global_store_dword v[14:15], v8, off
	v_fmac_f32_e32 v88, v8, v72
	global_store_dword v[14:15], v88, off offset:2048
	v_fmac_f32_e32 v89, v88, v73
	v_mov_b32_e32 v8, v89
	v_lshl_add_u64 v[14:15], v[14:15], 0, s[38:39]
	global_store_dword v[14:15], v8, off
	v_fmac_f32_e32 v90, v8, v74
	global_store_dword v[14:15], v90, off offset:2048
	v_fmac_f32_e32 v91, v90, v75
	v_mov_b32_e32 v8, v91
	v_lshl_add_u64 v[14:15], v[14:15], 0, s[38:39]
	global_store_dword v[14:15], v8, off
	v_fmac_f32_e32 v92, v8, v76
	global_store_dword v[14:15], v92, off offset:2048
	v_fmac_f32_e32 v93, v92, v77
	v_mov_b32_e32 v8, v93
	v_lshl_add_u64 v[14:15], v[14:15], 0, s[38:39]
	global_store_dword v[14:15], v8, off
	v_fmac_f32_e32 v94, v8, v78
	global_store_dword v[14:15], v94, off offset:2048
	v_fmac_f32_e32 v95, v94, v79
	v_mov_b32_e32 v8, v95
	v_lshl_add_u64 v[14:15], v[14:15], 0, s[38:39]
	s_waitcnt vmcnt(24)
	global_load_dword v64, v[10:11], off
	global_load_dword v65, v[10:11], off offset:2048
	global_load_dword v80, v[12:13], off
	global_load_dword v81, v[12:13], off offset:2048
	v_lshl_add_u64 v[10:11], v[10:11], 0, s[38:39]
	v_lshl_add_u64 v[12:13], v[12:13], 0, s[38:39]
	global_load_dword v66, v[10:11], off
	global_load_dword v67, v[10:11], off offset:2048
	global_load_dword v82, v[12:13], off
	global_load_dword v83, v[12:13], off offset:2048
	v_lshl_add_u64 v[10:11], v[10:11], 0, s[38:39]
	v_lshl_add_u64 v[12:13], v[12:13], 0, s[38:39]
	global_load_dword v68, v[10:11], off
	global_load_dword v69, v[10:11], off offset:2048
	global_load_dword v84, v[12:13], off
	global_load_dword v85, v[12:13], off offset:2048
	v_lshl_add_u64 v[10:11], v[10:11], 0, s[38:39]
	v_lshl_add_u64 v[12:13], v[12:13], 0, s[38:39]
	global_load_dword v70, v[10:11], off
	global_load_dword v71, v[10:11], off offset:2048
	global_load_dword v86, v[12:13], off
	global_load_dword v87, v[12:13], off offset:2048
	v_lshl_add_u64 v[10:11], v[10:11], 0, s[38:39]
	v_lshl_add_u64 v[12:13], v[12:13], 0, s[38:39]
	global_load_dword v72, v[10:11], off
	global_load_dword v73, v[10:11], off offset:2048
	global_load_dword v88, v[12:13], off
	global_load_dword v89, v[12:13], off offset:2048
	v_lshl_add_u64 v[10:11], v[10:11], 0, s[38:39]
	v_lshl_add_u64 v[12:13], v[12:13], 0, s[38:39]
	global_load_dword v74, v[10:11], off
	global_load_dword v75, v[10:11], off offset:2048
	global_load_dword v90, v[12:13], off
	global_load_dword v91, v[12:13], off offset:2048
	v_lshl_add_u64 v[10:11], v[10:11], 0, s[38:39]
	v_lshl_add_u64 v[12:13], v[12:13], 0, s[38:39]
	global_load_dword v76, v[10:11], off
	global_load_dword v77, v[10:11], off offset:2048
	global_load_dword v92, v[12:13], off
	global_load_dword v93, v[12:13], off offset:2048
	v_lshl_add_u64 v[10:11], v[10:11], 0, s[38:39]
	v_lshl_add_u64 v[12:13], v[12:13], 0, s[38:39]
	global_load_dword v78, v[10:11], off
	global_load_dword v79, v[10:11], off offset:2048
	global_load_dword v94, v[12:13], off
	global_load_dword v95, v[12:13], off offset:2048
	v_lshl_add_u64 v[10:11], v[10:11], 0, s[38:39]
	v_lshl_add_u64 v[12:13], v[12:13], 0, s[38:39]
	s_waitcnt vmcnt(0)
	global_store_dword v[14:15], v8, off
	v_fmac_f32_e32 v80, v8, v64
	global_store_dword v[14:15], v80, off offset:2048
	v_fmac_f32_e32 v81, v80, v65
	v_mov_b32_e32 v8, v81
	v_lshl_add_u64 v[14:15], v[14:15], 0, s[38:39]
	global_store_dword v[14:15], v8, off
	v_fmac_f32_e32 v82, v8, v66
	global_store_dword v[14:15], v82, off offset:2048
	v_fmac_f32_e32 v83, v82, v67
	v_mov_b32_e32 v8, v83
	v_lshl_add_u64 v[14:15], v[14:15], 0, s[38:39]
	global_store_dword v[14:15], v8, off
	v_fmac_f32_e32 v84, v8, v68
	global_store_dword v[14:15], v84, off offset:2048
	v_fmac_f32_e32 v85, v84, v69
	v_mov_b32_e32 v8, v85
	v_lshl_add_u64 v[14:15], v[14:15], 0, s[38:39]
	global_store_dword v[14:15], v8, off
	v_fmac_f32_e32 v86, v8, v70
	global_store_dword v[14:15], v86, off offset:2048
	v_fmac_f32_e32 v87, v86, v71
	v_mov_b32_e32 v8, v87
	v_lshl_add_u64 v[14:15], v[14:15], 0, s[38:39]
	global_store_dword v[14:15], v8, off
	v_fmac_f32_e32 v88, v8, v72
	global_store_dword v[14:15], v88, off offset:2048
	v_fmac_f32_e32 v89, v88, v73
	v_mov_b32_e32 v8, v89
	v_lshl_add_u64 v[14:15], v[14:15], 0, s[38:39]
	global_store_dword v[14:15], v8, off
	v_fmac_f32_e32 v90, v8, v74
	global_store_dword v[14:15], v90, off offset:2048
	v_fmac_f32_e32 v91, v90, v75
	v_mov_b32_e32 v8, v91
	v_lshl_add_u64 v[14:15], v[14:15], 0, s[38:39]
	global_store_dword v[14:15], v8, off
	v_fmac_f32_e32 v92, v8, v76
	global_store_dword v[14:15], v92, off offset:2048
	v_fmac_f32_e32 v93, v92, v77
	v_mov_b32_e32 v8, v93
	v_lshl_add_u64 v[14:15], v[14:15], 0, s[38:39]
	global_store_dword v[14:15], v8, off
	v_fmac_f32_e32 v94, v8, v78
	global_store_dword v[14:15], v94, off offset:2048
	v_fmac_f32_e32 v95, v94, v79
	v_mov_b32_e32 v8, v95
	v_lshl_add_u64 v[14:15], v[14:15], 0, s[38:39]
	s_waitcnt vmcnt(24)
	global_load_dword v64, v[10:11], off
	global_load_dword v65, v[10:11], off offset:2048
	global_load_dword v80, v[12:13], off
	global_load_dword v81, v[12:13], off offset:2048
	v_lshl_add_u64 v[10:11], v[10:11], 0, s[38:39]
	v_lshl_add_u64 v[12:13], v[12:13], 0, s[38:39]
	global_load_dword v66, v[10:11], off
	global_load_dword v67, v[10:11], off offset:2048
	global_load_dword v82, v[12:13], off
	global_load_dword v83, v[12:13], off offset:2048
	v_lshl_add_u64 v[10:11], v[10:11], 0, s[38:39]
	v_lshl_add_u64 v[12:13], v[12:13], 0, s[38:39]
	global_load_dword v68, v[10:11], off
	global_load_dword v69, v[10:11], off offset:2048
	global_load_dword v84, v[12:13], off
	global_load_dword v85, v[12:13], off offset:2048
	v_lshl_add_u64 v[10:11], v[10:11], 0, s[38:39]
	v_lshl_add_u64 v[12:13], v[12:13], 0, s[38:39]
	global_load_dword v70, v[10:11], off
	global_load_dword v71, v[10:11], off offset:2048
	global_load_dword v86, v[12:13], off
	global_load_dword v87, v[12:13], off offset:2048
	v_lshl_add_u64 v[10:11], v[10:11], 0, s[38:39]
	v_lshl_add_u64 v[12:13], v[12:13], 0, s[38:39]
	global_load_dword v72, v[10:11], off
	global_load_dword v73, v[10:11], off offset:2048
	global_load_dword v88, v[12:13], off
	global_load_dword v89, v[12:13], off offset:2048
	v_lshl_add_u64 v[10:11], v[10:11], 0, s[38:39]
	v_lshl_add_u64 v[12:13], v[12:13], 0, s[38:39]
	global_load_dword v74, v[10:11], off
	global_load_dword v75, v[10:11], off offset:2048
	global_load_dword v90, v[12:13], off
	global_load_dword v91, v[12:13], off offset:2048
	v_lshl_add_u64 v[10:11], v[10:11], 0, s[38:39]
	v_lshl_add_u64 v[12:13], v[12:13], 0, s[38:39]
	global_load_dword v76, v[10:11], off
	global_load_dword v77, v[10:11], off offset:2048
	global_load_dword v92, v[12:13], off
	global_load_dword v93, v[12:13], off offset:2048
	v_lshl_add_u64 v[10:11], v[10:11], 0, s[38:39]
	v_lshl_add_u64 v[12:13], v[12:13], 0, s[38:39]
	global_load_dword v78, v[10:11], off
	global_load_dword v79, v[10:11], off offset:2048
	global_load_dword v94, v[12:13], off
	global_load_dword v95, v[12:13], off offset:2048
	v_lshl_add_u64 v[10:11], v[10:11], 0, s[38:39]
	v_lshl_add_u64 v[12:13], v[12:13], 0, s[38:39]
	s_waitcnt vmcnt(0)
	global_store_dword v[14:15], v8, off
	v_fmac_f32_e32 v80, v8, v64
	global_store_dword v[14:15], v80, off offset:2048
	v_fmac_f32_e32 v81, v80, v65
	v_mov_b32_e32 v8, v81
	v_lshl_add_u64 v[14:15], v[14:15], 0, s[38:39]
	global_store_dword v[14:15], v8, off
	v_fmac_f32_e32 v82, v8, v66
	global_store_dword v[14:15], v82, off offset:2048
	v_fmac_f32_e32 v83, v82, v67
	v_mov_b32_e32 v8, v83
	v_lshl_add_u64 v[14:15], v[14:15], 0, s[38:39]
	global_store_dword v[14:15], v8, off
	v_fmac_f32_e32 v84, v8, v68
	global_store_dword v[14:15], v84, off offset:2048
	v_fmac_f32_e32 v85, v84, v69
	v_mov_b32_e32 v8, v85
	v_lshl_add_u64 v[14:15], v[14:15], 0, s[38:39]
	global_store_dword v[14:15], v8, off
	v_fmac_f32_e32 v86, v8, v70
	global_store_dword v[14:15], v86, off offset:2048
	v_fmac_f32_e32 v87, v86, v71
	v_mov_b32_e32 v8, v87
	v_lshl_add_u64 v[14:15], v[14:15], 0, s[38:39]
	global_store_dword v[14:15], v8, off
	v_fmac_f32_e32 v88, v8, v72
	global_store_dword v[14:15], v88, off offset:2048
	v_fmac_f32_e32 v89, v88, v73
	v_mov_b32_e32 v8, v89
	v_lshl_add_u64 v[14:15], v[14:15], 0, s[38:39]
	global_store_dword v[14:15], v8, off
	v_fmac_f32_e32 v90, v8, v74
	global_store_dword v[14:15], v90, off offset:2048
	v_fmac_f32_e32 v91, v90, v75
	v_mov_b32_e32 v8, v91
	v_lshl_add_u64 v[14:15], v[14:15], 0, s[38:39]
	global_store_dword v[14:15], v8, off
	v_fmac_f32_e32 v92, v8, v76
	global_store_dword v[14:15], v92, off offset:2048
	v_fmac_f32_e32 v93, v92, v77
	v_mov_b32_e32 v8, v93
	v_lshl_add_u64 v[14:15], v[14:15], 0, s[38:39]
	global_store_dword v[14:15], v8, off
	v_fmac_f32_e32 v94, v8, v78
	global_store_dword v[14:15], v94, off offset:2048
	v_fmac_f32_e32 v95, v94, v79
	v_mov_b32_e32 v8, v95
	v_lshl_add_u64 v[14:15], v[14:15], 0, s[38:39]
	v_lshl_add_u64 v[2:3], v[2:3], 0, s[76:77]
	s_mov_b64 s[28:29], 0xfff
	v_cmp_lt_i64_e32 vcc, s[28:29], v[2:3]
	v_readlane_b32 s28, v254, 19
	s_or_b64 s[2:3], vcc, s[2:3]
	s_nop 0
	v_add_u16_e32 v0, s28, v0
	s_andn2_b64 exec, exec, s[2:3]
	s_cbranch_execnz .LBB0_125

.LBB0_511:
	ds_read_b128 v[196:199], v159
	ds_read_b128 v[200:203], v159 offset:6656
	ds_read_b128 v[204:207], v159 offset:32
	ds_read_b128 v[208:211], v159 offset:6688
	ds_read_b128 v[212:215], v159 offset:64
	ds_read_b128 v[216:219], v159 offset:6720
	ds_read_b128 v[220:223], v159 offset:96
	ds_read_b128 v[224:227], v159 offset:6752
	ds_read_b128 v[228:231], v159 offset:128
	ds_read_b128 v[232:235], v159 offset:6784
	ds_read_b128 v[236:239], v159 offset:160
	ds_read_b128 v[240:243], v159 offset:6816
	s_cmp_le_i32 s53, s50
	s_waitcnt lgkmcnt(11)
	v_mfma_f32_32x32x16_bf16 v[66:81], v[196:199], v[82:85], v[34:49]
	s_waitcnt lgkmcnt(10)
	v_mfma_f32_32x32x16_bf16 v[50:65], v[200:203], v[82:85], v[34:49]
	s_waitcnt lgkmcnt(9)
	v_mfma_f32_32x32x16_bf16 v[66:81], v[204:207], v[86:89], v[66:81]
	s_waitcnt lgkmcnt(8)
	v_mfma_f32_32x32x16_bf16 v[50:65], v[208:211], v[86:89], v[50:65]
	s_waitcnt lgkmcnt(7)
	v_mfma_f32_32x32x16_bf16 v[66:81], v[212:215], v[90:93], v[66:81]
	s_waitcnt lgkmcnt(6)
	v_mfma_f32_32x32x16_bf16 v[50:65], v[216:219], v[90:93], v[50:65]
	s_waitcnt lgkmcnt(5)
	v_mfma_f32_32x32x16_bf16 v[66:81], v[220:223], v[94:97], v[66:81]
	s_waitcnt lgkmcnt(4)
	v_mfma_f32_32x32x16_bf16 v[50:65], v[224:227], v[94:97], v[50:65]
	s_waitcnt lgkmcnt(3)
	v_mfma_f32_32x32x16_bf16 v[66:81], v[228:231], v[98:101], v[66:81]
	s_waitcnt lgkmcnt(2)
	v_mfma_f32_32x32x16_bf16 v[50:65], v[232:235], v[98:101], v[50:65]
	s_waitcnt lgkmcnt(1)
	v_mfma_f32_32x32x16_bf16 v[66:81], v[236:239], v[102:105], v[66:81]
	s_waitcnt lgkmcnt(0)
	v_mfma_f32_32x32x16_bf16 v[50:65], v[240:243], v[102:105], v[50:65]
	v_add_u32_e32 v244, s37, v155
	v_add_u32_e32 v245, 0xf000, v244
	v_add_u32_e32 v244, 0xd000, v244
	ds_read2_b64 v[196:199], v244 offset1:2
	ds_read2_b64 v[200:203], v245 offset0:32 offset1:34
	ds_read2_b64 v[204:207], v244 offset0:4 offset1:6
	ds_read2_b64 v[208:211], v245 offset0:36 offset1:38
	ds_read2_b64 v[212:215], v244 offset0:8 offset1:10
	ds_read2_b64 v[216:219], v245 offset0:40 offset1:42
	ds_read2_b64 v[220:223], v244 offset0:12 offset1:14
	ds_read2_b64 v[224:227], v245 offset0:44 offset1:46
	s_cbranch_scc1 .LBB0_513
	v_add_u32_e32 v136, s53, v129
	v_subrev_u32_e32 v138, 31, v136
	v_subrev_u32_e32 v137, 63, v136
	v_cmp_le_i32_e32 vcc, v138, v128
	s_nop 6
	v_cndmask_b32_e32 v50, v194, v50, vcc
	v_cmp_lt_i32_e32 vcc, v137, v128
	s_nop 1
	v_cndmask_b32_e32 v67, v194, v67, vcc
	v_cmp_le_i32_e32 vcc, v137, v128
	v_subrev_u32_e32 v137, 30, v136
	s_nop 0
	v_cndmask_b32_e32 v66, v194, v66, vcc
	v_cmp_le_i32_e32 vcc, v137, v128
	v_subrev_u32_e32 v137, 61, v136
	s_nop 0
	v_cndmask_b32_e32 v51, v194, v51, vcc
	v_cmp_le_i32_e32 vcc, v137, v128
	v_subrev_u32_e32 v137, 29, v136
	s_nop 0
	v_cndmask_b32_e32 v68, v194, v68, vcc
	v_cmp_le_i32_e32 vcc, v137, v128
	v_subrev_u32_e32 v137, 60, v136
	s_nop 0
	v_cndmask_b32_e32 v52, v194, v52, vcc
	v_cmp_le_i32_e32 vcc, v137, v128
	v_subrev_u32_e32 v137, 28, v136
	s_nop 0
	v_cndmask_b32_e32 v69, v194, v69, vcc
	v_cmp_le_i32_e32 vcc, v137, v128
	v_subrev_u32_e32 v137, 55, v136
	s_nop 0
	v_cndmask_b32_e32 v53, v194, v53, vcc
	v_cmp_le_i32_e32 vcc, v137, v128
	v_subrev_u32_e32 v137, 23, v136
	s_nop 0
	v_cndmask_b32_e32 v70, v194, v70, vcc
	v_cmp_le_i32_e32 vcc, v137, v128
	v_subrev_u32_e32 v137, 54, v136
	s_nop 0
	v_cndmask_b32_e32 v54, v194, v54, vcc
	v_cmp_le_i32_e32 vcc, v137, v128
	v_subrev_u32_e32 v137, 22, v136
	s_nop 0
	v_cndmask_b32_e32 v71, v194, v71, vcc
	v_cmp_le_i32_e32 vcc, v137, v128
	v_subrev_u32_e32 v137, 53, v136
	s_nop 0
	v_cndmask_b32_e32 v55, v194, v55, vcc
	v_cmp_le_i32_e32 vcc, v137, v128
	v_subrev_u32_e32 v137, 21, v136
	s_nop 0
	v_cndmask_b32_e32 v72, v194, v72, vcc
	v_cmp_le_i32_e32 vcc, v137, v128
	v_subrev_u32_e32 v137, 52, v136
	s_nop 0
	v_cndmask_b32_e32 v56, v194, v56, vcc
	v_cmp_le_i32_e32 vcc, v137, v128
	v_subrev_u32_e32 v137, 20, v136
	s_nop 0
	v_cndmask_b32_e32 v73, v194, v73, vcc
	v_cmp_le_i32_e32 vcc, v137, v128
	v_subrev_u32_e32 v137, 47, v136
	s_nop 0
	v_cndmask_b32_e32 v57, v194, v57, vcc
	v_cmp_le_i32_e32 vcc, v137, v128
	v_add_u32_e32 v137, -15, v136
	s_nop 0
	v_cndmask_b32_e32 v74, v194, v74, vcc
	v_cmp_le_i32_e32 vcc, v137, v128
	v_subrev_u32_e32 v137, 46, v136
	s_nop 0
	v_cndmask_b32_e32 v58, v194, v58, vcc
	v_cmp_le_i32_e32 vcc, v137, v128
	v_add_u32_e32 v137, -14, v136
	s_nop 0
	v_cndmask_b32_e32 v75, v194, v75, vcc
	v_cmp_le_i32_e32 vcc, v137, v128
	v_subrev_u32_e32 v137, 45, v136
	s_nop 0
	v_cndmask_b32_e32 v59, v194, v59, vcc
	v_cmp_le_i32_e32 vcc, v137, v128
	v_add_u32_e32 v137, -13, v136
	s_nop 0
	v_cndmask_b32_e32 v76, v194, v76, vcc
	v_cmp_le_i32_e32 vcc, v137, v128
	v_subrev_u32_e32 v137, 44, v136
	s_nop 0
	v_cndmask_b32_e32 v60, v194, v60, vcc
	v_cmp_le_i32_e32 vcc, v137, v128
	v_add_u32_e32 v137, -12, v136
	s_nop 0
	v_cndmask_b32_e32 v77, v194, v77, vcc
	v_cmp_le_i32_e32 vcc, v137, v128
	v_subrev_u32_e32 v137, 39, v136
	s_nop 0
	v_cndmask_b32_e32 v61, v194, v61, vcc
	v_cmp_le_i32_e32 vcc, v137, v128
	v_add_u32_e32 v137, -7, v136
	s_nop 0
	v_cndmask_b32_e32 v78, v194, v78, vcc
	v_cmp_le_i32_e32 vcc, v137, v128
	v_subrev_u32_e32 v137, 38, v136
	s_nop 0
	v_cndmask_b32_e32 v62, v194, v62, vcc
	v_cmp_le_i32_e32 vcc, v137, v128
	v_add_u32_e32 v137, -6, v136
	s_nop 0
	v_cndmask_b32_e32 v79, v194, v79, vcc
	v_cmp_le_i32_e32 vcc, v137, v128
	v_subrev_u32_e32 v137, 37, v136
	s_nop 0
	v_cndmask_b32_e32 v63, v194, v63, vcc
	v_cmp_le_i32_e32 vcc, v137, v128
	v_add_u32_e32 v137, -5, v136
	s_nop 0
	v_cndmask_b32_e32 v80, v194, v80, vcc
	v_cmp_le_i32_e32 vcc, v137, v128
	v_subrev_u32_e32 v137, 36, v136
	v_add_u32_e32 v136, -4, v136
	v_cndmask_b32_e32 v64, v194, v64, vcc
	v_cmp_le_i32_e32 vcc, v137, v128
	s_nop 1
	v_cndmask_b32_e32 v81, v194, v81, vcc
	v_cmp_le_i32_e32 vcc, v136, v128
	s_nop 1
	v_cndmask_b32_e32 v65, v194, v65, vcc

.LBB0_515:
	v_exp_f32_e32 v136, v66
	v_exp_f32_e32 v137, v67
	v_exp_f32_e32 v138, v68
	v_exp_f32_e32 v139, v69
	v_add_f32_e32 v66, 0, v136
	v_exp_f32_e32 v161, v70
	v_add_f32_e32 v66, v137, v66
	v_exp_f32_e32 v162, v71
	v_add_f32_e32 v66, v138, v66
	v_exp_f32_e32 v163, v72
	v_add_f32_e32 v66, v139, v66
	v_exp_f32_e32 v164, v73
	v_add_f32_e32 v66, v161, v66
	v_exp_f32_e32 v165, v74
	v_add_f32_e32 v66, v162, v66
	v_exp_f32_e32 v166, v75
	v_add_f32_e32 v66, v163, v66
	v_exp_f32_e32 v167, v76
	v_add_f32_e32 v66, v164, v66
	v_exp_f32_e32 v168, v77
	v_add_f32_e32 v66, v165, v66
	v_exp_f32_e32 v169, v78
	v_exp_f32_e32 v170, v79
	v_exp_f32_e32 v79, v62
	v_cvt_pk_bf16_f32 v62, v136, v137
	v_add_f32_e32 v66, v166, v66
	v_add_f32_e32 v66, v167, v66
	v_exp_f32_e32 v171, v80
	v_exp_f32_e32 v172, v81
	v_exp_f32_e32 v75, v58
	v_exp_f32_e32 v81, v64
	v_exp_f32_e32 v160, v65
	v_cvt_pk_bf16_f32 v64, v161, v162
	v_cvt_pk_bf16_f32 v65, v163, v164
	v_cvt_pk_bf16_f32 v58, v165, v166
	v_add_f32_e32 v66, v168, v66
	v_add_f32_e32 v66, v169, v66
	v_add_f32_e32 v66, v170, v66
	v_add_f32_e32 v66, v171, v66
	v_add_f32_e32 v66, v172, v66
	v_exp_f32_e32 v76, v59
	v_exp_f32_e32 v77, v60
	v_exp_f32_e32 v78, v61
	v_cvt_pk_bf16_f32 v59, v167, v168
	v_cvt_pk_bf16_f32 v60, v169, v170
	v_cvt_pk_bf16_f32 v61, v171, v172
	v_exp_f32_e32 v80, v63
	v_cvt_pk_bf16_f32 v63, v138, v139
	v_exp_f32_e32 v67, v50
	v_exp_f32_e32 v68, v51
	s_waitcnt lgkmcnt(7)
	v_mfma_f32_32x32x16_bf16 v[2:17], v[196:199], v[62:65], v[2:17]
	v_exp_f32_e32 v69, v52
	v_exp_f32_e32 v70, v53
	v_exp_f32_e32 v71, v54
	v_exp_f32_e32 v72, v55
	v_exp_f32_e32 v73, v56
	v_exp_f32_e32 v74, v57
	v_cvt_pk_bf16_f32 v54, v67, v68
	s_waitcnt lgkmcnt(6)
	v_mfma_f32_32x32x16_bf16 v[18:33], v[200:203], v[62:65], v[18:33]
	v_cvt_pk_bf16_f32 v55, v69, v70
	v_cvt_pk_bf16_f32 v56, v71, v72
	v_cvt_pk_bf16_f32 v57, v73, v74
	v_cvt_pk_bf16_f32 v50, v75, v76
	v_cvt_pk_bf16_f32 v51, v77, v78
	v_cvt_pk_bf16_f32 v52, v79, v80
	s_waitcnt lgkmcnt(5)
	v_mfma_f32_32x32x16_bf16 v[2:17], v[204:207], v[58:61], v[2:17]
	v_cvt_pk_bf16_f32 v53, v81, v160
	s_waitcnt lgkmcnt(4)
	v_mfma_f32_32x32x16_bf16 v[18:33], v[208:211], v[58:61], v[18:33]
	s_waitcnt lgkmcnt(3)
	v_mfma_f32_32x32x16_bf16 v[2:17], v[212:215], v[54:57], v[2:17]
	s_waitcnt lgkmcnt(2)
	v_mfma_f32_32x32x16_bf16 v[18:33], v[216:219], v[54:57], v[18:33]
	s_waitcnt lgkmcnt(1)
	v_mfma_f32_32x32x16_bf16 v[2:17], v[220:223], v[50:53], v[2:17]
	s_waitcnt lgkmcnt(0)
	v_mfma_f32_32x32x16_bf16 v[18:33], v[224:227], v[50:53], v[18:33]
	v_add_f32_e32 v50, v67, v66
	v_add_f32_e32 v50, v68, v50
	v_add_f32_e32 v50, v69, v50
	v_add_f32_e32 v50, v70, v50
	v_add_f32_e32 v50, v71, v50
	v_add_f32_e32 v50, v72, v50
	v_add_f32_e32 v50, v73, v50
	v_add_f32_e32 v50, v74, v50
	v_add_f32_e32 v50, v75, v50
	v_add_f32_e32 v50, v76, v50
	v_add_f32_e32 v50, v77, v50
	v_add_f32_e32 v50, v78, v50
	v_add_f32_e32 v50, v79, v50
	v_add_f32_e32 v50, v80, v50
	v_add_f32_e32 v50, v81, v50
	v_add_f32_e32 v50, v160, v50
	v_add_f32_e32 v157, v157, v50
	s_add_i32 s55, s53, 1
	s_cmp_gt_i32 s55, s51
	s_cbranch_scc1 .LBB0_507
.LBB0_516:
	ds_read_b128 v[196:199], v159 offset:13312
	ds_read_b128 v[200:203], v159 offset:19968
	ds_read_b128 v[204:207], v159 offset:13344
	ds_read_b128 v[208:211], v159 offset:20000
	ds_read_b128 v[212:215], v159 offset:13376
	ds_read_b128 v[216:219], v159 offset:20032
	ds_read_b128 v[220:223], v159 offset:13408
	ds_read_b128 v[224:227], v159 offset:20064
	ds_read_b128 v[228:231], v159 offset:13440
	ds_read_b128 v[232:235], v159 offset:20096
	ds_read_b128 v[236:239], v159 offset:13472
	ds_read_b128 v[240:243], v159 offset:20128
	s_add_i32 s55, s53, 64
	s_cmp_le_i32 s55, s50
	s_waitcnt lgkmcnt(11)
	v_mfma_f32_32x32x16_bf16 v[66:81], v[196:199], v[82:85], v[34:49]
	s_waitcnt lgkmcnt(10)
	v_mfma_f32_32x32x16_bf16 v[50:65], v[200:203], v[82:85], v[34:49]
	s_waitcnt lgkmcnt(9)
	v_mfma_f32_32x32x16_bf16 v[66:81], v[204:207], v[86:89], v[66:81]
	s_waitcnt lgkmcnt(8)
	v_mfma_f32_32x32x16_bf16 v[50:65], v[208:211], v[86:89], v[50:65]
	s_waitcnt lgkmcnt(7)
	v_mfma_f32_32x32x16_bf16 v[66:81], v[212:215], v[90:93], v[66:81]
	s_waitcnt lgkmcnt(6)
	v_mfma_f32_32x32x16_bf16 v[50:65], v[216:219], v[90:93], v[50:65]
	s_waitcnt lgkmcnt(5)
	v_mfma_f32_32x32x16_bf16 v[66:81], v[220:223], v[94:97], v[66:81]
	s_waitcnt lgkmcnt(4)
	v_mfma_f32_32x32x16_bf16 v[50:65], v[224:227], v[94:97], v[50:65]
	s_waitcnt lgkmcnt(3)
	v_mfma_f32_32x32x16_bf16 v[66:81], v[228:231], v[98:101], v[66:81]
	s_waitcnt lgkmcnt(2)
	v_mfma_f32_32x32x16_bf16 v[50:65], v[232:235], v[98:101], v[50:65]
	s_waitcnt lgkmcnt(1)
	v_mfma_f32_32x32x16_bf16 v[66:81], v[236:239], v[102:105], v[66:81]
	s_waitcnt lgkmcnt(0)
	v_mfma_f32_32x32x16_bf16 v[50:65], v[240:243], v[102:105], v[50:65]
	v_add_u32_e32 v244, s37, v155
	v_add_u32_e32 v245, 0xf000, v244
	v_add_u32_e32 v244, 0xd000, v244
	ds_read2_b64 v[196:199], v244 offset0:16 offset1:18
	ds_read2_b64 v[200:203], v245 offset0:48 offset1:50
	ds_read2_b64 v[204:207], v244 offset0:20 offset1:22
	ds_read2_b64 v[208:211], v245 offset0:52 offset1:54
	ds_read2_b64 v[212:215], v244 offset0:24 offset1:26
	ds_read2_b64 v[216:219], v245 offset0:56 offset1:58
	ds_read2_b64 v[220:223], v244 offset0:28 offset1:30
	ds_read2_b64 v[224:227], v245 offset0:60 offset1:62
	s_cbranch_scc1 .LBB0_518
	v_add_u32_e32 v136, s53, v129
	v_add_u32_e32 v138, 33, v136
	v_add_u32_e32 v137, 1, v136
	v_cmp_le_i32_e32 vcc, v138, v128
	s_nop 6
	v_cndmask_b32_e32 v50, v194, v50, vcc
	v_cmp_lt_i32_e32 vcc, v137, v128
	s_nop 1
	v_cndmask_b32_e32 v67, v194, v67, vcc
	v_cmp_le_i32_e32 vcc, v137, v128
	v_add_u32_e32 v137, 34, v136
	s_nop 0
	v_cndmask_b32_e32 v66, v194, v66, vcc
	v_cmp_le_i32_e32 vcc, v137, v128
	v_add_u32_e32 v137, 3, v136
	s_nop 0
	v_cndmask_b32_e32 v51, v194, v51, vcc
	v_cmp_le_i32_e32 vcc, v137, v128
	v_add_u32_e32 v137, 35, v136
	s_nop 0
	v_cndmask_b32_e32 v68, v194, v68, vcc
	v_cmp_le_i32_e32 vcc, v137, v128
	v_add_u32_e32 v137, 4, v136
	s_nop 0
	v_cndmask_b32_e32 v52, v194, v52, vcc
	v_cmp_le_i32_e32 vcc, v137, v128
	v_add_u32_e32 v137, 36, v136
	s_nop 0
	v_cndmask_b32_e32 v69, v194, v69, vcc
	v_cmp_le_i32_e32 vcc, v137, v128
	v_add_u32_e32 v137, 9, v136
	s_nop 0
	v_cndmask_b32_e32 v53, v194, v53, vcc
	v_cmp_le_i32_e32 vcc, v137, v128
	v_add_u32_e32 v137, 41, v136
	s_nop 0
	v_cndmask_b32_e32 v70, v194, v70, vcc
	v_cmp_le_i32_e32 vcc, v137, v128
	v_add_u32_e32 v137, 10, v136
	s_nop 0
	v_cndmask_b32_e32 v54, v194, v54, vcc
	v_cmp_le_i32_e32 vcc, v137, v128
	v_add_u32_e32 v137, 42, v136
	s_nop 0
	v_cndmask_b32_e32 v71, v194, v71, vcc
	v_cmp_le_i32_e32 vcc, v137, v128
	v_add_u32_e32 v137, 11, v136
	s_nop 0
	v_cndmask_b32_e32 v55, v194, v55, vcc
	v_cmp_le_i32_e32 vcc, v137, v128
	v_add_u32_e32 v137, 43, v136
	s_nop 0
	v_cndmask_b32_e32 v72, v194, v72, vcc
	v_cmp_le_i32_e32 vcc, v137, v128
	v_add_u32_e32 v137, 12, v136
	s_nop 0
	v_cndmask_b32_e32 v56, v194, v56, vcc
	v_cmp_le_i32_e32 vcc, v137, v128
	v_add_u32_e32 v137, 44, v136
	s_nop 0
	v_cndmask_b32_e32 v73, v194, v73, vcc
	v_cmp_le_i32_e32 vcc, v137, v128
	v_add_u32_e32 v137, 17, v136
	s_nop 0
	v_cndmask_b32_e32 v57, v194, v57, vcc
	v_cmp_le_i32_e32 vcc, v137, v128
	v_add_u32_e32 v137, 49, v136
	s_nop 0
	v_cndmask_b32_e32 v74, v194, v74, vcc
	v_cmp_le_i32_e32 vcc, v137, v128
	v_add_u32_e32 v137, 18, v136
	s_nop 0
	v_cndmask_b32_e32 v58, v194, v58, vcc
	v_cmp_le_i32_e32 vcc, v137, v128
	v_add_u32_e32 v137, 50, v136
	s_nop 0
	v_cndmask_b32_e32 v75, v194, v75, vcc
	v_cmp_le_i32_e32 vcc, v137, v128
	v_add_u32_e32 v137, 19, v136
	s_nop 0
	v_cndmask_b32_e32 v59, v194, v59, vcc
	v_cmp_le_i32_e32 vcc, v137, v128
	v_add_u32_e32 v137, 51, v136
	s_nop 0
	v_cndmask_b32_e32 v76, v194, v76, vcc
	v_cmp_le_i32_e32 vcc, v137, v128
	v_add_u32_e32 v137, 20, v136
	s_nop 0
	v_cndmask_b32_e32 v60, v194, v60, vcc
	v_cmp_le_i32_e32 vcc, v137, v128
	v_add_u32_e32 v137, 52, v136
	s_nop 0
	v_cndmask_b32_e32 v77, v194, v77, vcc
	v_cmp_le_i32_e32 vcc, v137, v128
	v_add_u32_e32 v137, 25, v136
	s_nop 0
	v_cndmask_b32_e32 v61, v194, v61, vcc
	v_cmp_le_i32_e32 vcc, v137, v128
	v_add_u32_e32 v137, 57, v136
	s_nop 0
	v_cndmask_b32_e32 v78, v194, v78, vcc
	v_cmp_le_i32_e32 vcc, v137, v128
	v_add_u32_e32 v137, 26, v136
	s_nop 0
	v_cndmask_b32_e32 v62, v194, v62, vcc
	v_cmp_le_i32_e32 vcc, v137, v128
	v_add_u32_e32 v137, 58, v136
	s_nop 0
	v_cndmask_b32_e32 v79, v194, v79, vcc
	v_cmp_le_i32_e32 vcc, v137, v128
	v_add_u32_e32 v137, 27, v136
	s_nop 0
	v_cndmask_b32_e32 v63, v194, v63, vcc
	v_cmp_le_i32_e32 vcc, v137, v128
	v_add_u32_e32 v137, 59, v136
	s_nop 0
	v_cndmask_b32_e32 v80, v194, v80, vcc
	v_cmp_le_i32_e32 vcc, v137, v128
	v_add_u32_e32 v137, 28, v136
	v_add_u32_e32 v136, 60, v136
	v_cndmask_b32_e32 v64, v194, v64, vcc
	v_cmp_le_i32_e32 vcc, v137, v128
	s_nop 1
	v_cndmask_b32_e32 v81, v194, v81, vcc
	v_cmp_le_i32_e32 vcc, v136, v128
	s_nop 1
	v_cndmask_b32_e32 v65, v194, v65, vcc

.LBB0_520:
	v_exp_f32_e32 v136, v66
	v_exp_f32_e32 v137, v67
	v_exp_f32_e32 v138, v68
	v_exp_f32_e32 v139, v69
	v_add_f32_e32 v66, 0, v136
	v_exp_f32_e32 v160, v70
	v_add_f32_e32 v66, v137, v66
	v_exp_f32_e32 v161, v71
	v_add_f32_e32 v66, v138, v66
	v_exp_f32_e32 v162, v72
	v_add_f32_e32 v66, v139, v66
	v_exp_f32_e32 v163, v73
	v_add_f32_e32 v66, v160, v66
	v_exp_f32_e32 v164, v74
	v_add_f32_e32 v66, v161, v66
	v_exp_f32_e32 v165, v75
	v_add_f32_e32 v66, v162, v66
	v_exp_f32_e32 v166, v76
	v_add_f32_e32 v66, v163, v66
	v_exp_f32_e32 v167, v77
	v_add_f32_e32 v66, v164, v66
	v_exp_f32_e32 v168, v78
	v_exp_f32_e32 v169, v79
	v_exp_f32_e32 v79, v62
	v_cvt_pk_bf16_f32 v62, v136, v137
	v_add_f32_e32 v66, v165, v66
	v_add_f32_e32 v66, v166, v66
	v_exp_f32_e32 v170, v80
	v_exp_f32_e32 v171, v81
	v_exp_f32_e32 v81, v64
	v_exp_f32_e32 v159, v65
	v_cvt_pk_bf16_f32 v64, v160, v161
	v_cvt_pk_bf16_f32 v65, v162, v163
	v_add_f32_e32 v66, v167, v66
	v_add_f32_e32 v66, v168, v66
	v_add_f32_e32 v66, v169, v66
	v_add_f32_e32 v66, v170, v66
	v_add_f32_e32 v66, v171, v66
	v_exp_f32_e32 v75, v58
	v_exp_f32_e32 v76, v59
	v_exp_f32_e32 v77, v60
	v_exp_f32_e32 v78, v61
	v_cvt_pk_bf16_f32 v58, v164, v165
	v_cvt_pk_bf16_f32 v59, v166, v167
	v_cvt_pk_bf16_f32 v60, v168, v169
	v_cvt_pk_bf16_f32 v61, v170, v171
	v_exp_f32_e32 v80, v63
	v_cvt_pk_bf16_f32 v63, v138, v139
	v_exp_f32_e32 v67, v50
	v_exp_f32_e32 v68, v51
	s_waitcnt lgkmcnt(7)
	v_mfma_f32_32x32x16_bf16 v[2:17], v[196:199], v[62:65], v[2:17]
	v_exp_f32_e32 v69, v52
	v_exp_f32_e32 v70, v53
	v_exp_f32_e32 v71, v54
	v_exp_f32_e32 v72, v55
	v_exp_f32_e32 v73, v56
	v_exp_f32_e32 v74, v57
	v_cvt_pk_bf16_f32 v54, v67, v68
	s_waitcnt lgkmcnt(6)
	v_mfma_f32_32x32x16_bf16 v[18:33], v[200:203], v[62:65], v[18:33]
	v_cvt_pk_bf16_f32 v55, v69, v70
	v_cvt_pk_bf16_f32 v56, v71, v72
	v_cvt_pk_bf16_f32 v57, v73, v74
	v_cvt_pk_bf16_f32 v50, v75, v76
	v_cvt_pk_bf16_f32 v51, v77, v78
	v_cvt_pk_bf16_f32 v52, v79, v80
	s_waitcnt lgkmcnt(5)
	v_mfma_f32_32x32x16_bf16 v[2:17], v[204:207], v[58:61], v[2:17]
	v_cvt_pk_bf16_f32 v53, v81, v159
	s_waitcnt lgkmcnt(4)
	v_mfma_f32_32x32x16_bf16 v[18:33], v[208:211], v[58:61], v[18:33]
	s_waitcnt lgkmcnt(3)
	v_mfma_f32_32x32x16_bf16 v[2:17], v[212:215], v[54:57], v[2:17]
	s_waitcnt lgkmcnt(2)
	v_mfma_f32_32x32x16_bf16 v[18:33], v[216:219], v[54:57], v[18:33]
	s_waitcnt lgkmcnt(1)
	v_mfma_f32_32x32x16_bf16 v[2:17], v[220:223], v[50:53], v[2:17]
	s_waitcnt lgkmcnt(0)
	v_mfma_f32_32x32x16_bf16 v[18:33], v[224:227], v[50:53], v[18:33]
	v_add_f32_e32 v50, v67, v66
	v_add_f32_e32 v50, v68, v50
	v_add_f32_e32 v50, v69, v50
	v_add_f32_e32 v50, v70, v50
	v_add_f32_e32 v50, v71, v50
	v_add_f32_e32 v50, v72, v50
	v_add_f32_e32 v50, v73, v50
	v_add_f32_e32 v50, v74, v50
	v_add_f32_e32 v50, v75, v50
	v_add_f32_e32 v50, v76, v50
	v_add_f32_e32 v50, v77, v50
	v_add_f32_e32 v50, v78, v50
	v_add_f32_e32 v50, v79, v50
	v_add_f32_e32 v50, v80, v50
	v_add_f32_e32 v50, v81, v50
	v_add_f32_e32 v50, v159, v50
	v_add_f32_e32 v157, v157, v50
	s_and_b64 vcc, exec, s[2:3]
	s_cbranch_vccnz .LBB0_508
	s_branch .LBB0_509

.LBB0_530:
	ds_read_b128 v[196:199], v160
	ds_read_b128 v[200:203], v160 offset:6656
	ds_read_b128 v[204:207], v160 offset:32
	ds_read_b128 v[208:211], v160 offset:6688
	ds_read_b128 v[212:215], v160 offset:64
	ds_read_b128 v[216:219], v160 offset:6720
	ds_read_b128 v[220:223], v160 offset:96
	ds_read_b128 v[224:227], v160 offset:6752
	ds_read_b128 v[228:231], v160 offset:128
	ds_read_b128 v[232:235], v160 offset:6784
	ds_read_b128 v[236:239], v160 offset:160
	ds_read_b128 v[240:243], v160 offset:6816
	s_cmp_le_i32 s41, s50
	s_waitcnt lgkmcnt(11)
	v_mfma_f32_32x32x16_bf16 v[66:81], v[196:199], v[82:85], v[34:49]
	s_waitcnt lgkmcnt(10)
	v_mfma_f32_32x32x16_bf16 v[50:65], v[200:203], v[82:85], v[34:49]
	s_waitcnt lgkmcnt(9)
	v_mfma_f32_32x32x16_bf16 v[66:81], v[204:207], v[86:89], v[66:81]
	s_waitcnt lgkmcnt(8)
	v_mfma_f32_32x32x16_bf16 v[50:65], v[208:211], v[86:89], v[50:65]
	s_waitcnt lgkmcnt(7)
	v_mfma_f32_32x32x16_bf16 v[66:81], v[212:215], v[90:93], v[66:81]
	s_waitcnt lgkmcnt(6)
	v_mfma_f32_32x32x16_bf16 v[50:65], v[216:219], v[90:93], v[50:65]
	s_waitcnt lgkmcnt(5)
	v_mfma_f32_32x32x16_bf16 v[66:81], v[220:223], v[94:97], v[66:81]
	s_waitcnt lgkmcnt(4)
	v_mfma_f32_32x32x16_bf16 v[50:65], v[224:227], v[94:97], v[50:65]
	s_waitcnt lgkmcnt(3)
	v_mfma_f32_32x32x16_bf16 v[66:81], v[228:231], v[98:101], v[66:81]
	s_waitcnt lgkmcnt(2)
	v_mfma_f32_32x32x16_bf16 v[50:65], v[232:235], v[98:101], v[50:65]
	s_waitcnt lgkmcnt(1)
	v_mfma_f32_32x32x16_bf16 v[66:81], v[236:239], v[102:105], v[66:81]
	s_waitcnt lgkmcnt(0)
	v_mfma_f32_32x32x16_bf16 v[50:65], v[240:243], v[102:105], v[50:65]
	v_add_u32_e32 v244, s37, v156
	v_add_u32_e32 v245, 0xf000, v244
	v_add_u32_e32 v244, 0xd000, v244
	ds_read2_b64 v[196:199], v244 offset1:2
	ds_read2_b64 v[200:203], v245 offset0:32 offset1:34
	ds_read2_b64 v[204:207], v244 offset0:4 offset1:6
	ds_read2_b64 v[208:211], v245 offset0:36 offset1:38
	ds_read2_b64 v[212:215], v244 offset0:8 offset1:10
	ds_read2_b64 v[216:219], v245 offset0:40 offset1:42
	ds_read2_b64 v[220:223], v244 offset0:12 offset1:14
	ds_read2_b64 v[224:227], v245 offset0:44 offset1:46
	s_cbranch_scc1 .LBB0_532
	v_add_u32_e32 v136, s41, v129
	v_subrev_u32_e32 v138, 31, v136
	v_subrev_u32_e32 v137, 63, v136
	v_cmp_le_i32_e32 vcc, v138, v128
	s_nop 6
	v_cndmask_b32_e32 v50, v194, v50, vcc
	v_cmp_lt_i32_e32 vcc, v137, v128
	s_nop 1
	v_cndmask_b32_e32 v67, v194, v67, vcc
	v_cmp_le_i32_e32 vcc, v137, v128
	v_subrev_u32_e32 v137, 30, v136
	s_nop 0
	v_cndmask_b32_e32 v66, v194, v66, vcc
	v_cmp_le_i32_e32 vcc, v137, v128
	v_subrev_u32_e32 v137, 61, v136
	s_nop 0
	v_cndmask_b32_e32 v51, v194, v51, vcc
	v_cmp_le_i32_e32 vcc, v137, v128
	v_subrev_u32_e32 v137, 29, v136
	s_nop 0
	v_cndmask_b32_e32 v68, v194, v68, vcc
	v_cmp_le_i32_e32 vcc, v137, v128
	v_subrev_u32_e32 v137, 60, v136
	s_nop 0
	v_cndmask_b32_e32 v52, v194, v52, vcc
	v_cmp_le_i32_e32 vcc, v137, v128
	v_subrev_u32_e32 v137, 28, v136
	s_nop 0
	v_cndmask_b32_e32 v69, v194, v69, vcc
	v_cmp_le_i32_e32 vcc, v137, v128
	v_subrev_u32_e32 v137, 55, v136
	s_nop 0
	v_cndmask_b32_e32 v53, v194, v53, vcc
	v_cmp_le_i32_e32 vcc, v137, v128
	v_subrev_u32_e32 v137, 23, v136
	s_nop 0
	v_cndmask_b32_e32 v70, v194, v70, vcc
	v_cmp_le_i32_e32 vcc, v137, v128
	v_subrev_u32_e32 v137, 54, v136
	s_nop 0
	v_cndmask_b32_e32 v54, v194, v54, vcc
	v_cmp_le_i32_e32 vcc, v137, v128
	v_subrev_u32_e32 v137, 22, v136
	s_nop 0
	v_cndmask_b32_e32 v71, v194, v71, vcc
	v_cmp_le_i32_e32 vcc, v137, v128
	v_subrev_u32_e32 v137, 53, v136
	s_nop 0
	v_cndmask_b32_e32 v55, v194, v55, vcc
	v_cmp_le_i32_e32 vcc, v137, v128
	v_subrev_u32_e32 v137, 21, v136
	s_nop 0
	v_cndmask_b32_e32 v72, v194, v72, vcc
	v_cmp_le_i32_e32 vcc, v137, v128
	v_subrev_u32_e32 v137, 52, v136
	s_nop 0
	v_cndmask_b32_e32 v56, v194, v56, vcc
	v_cmp_le_i32_e32 vcc, v137, v128
	v_subrev_u32_e32 v137, 20, v136
	s_nop 0
	v_cndmask_b32_e32 v73, v194, v73, vcc
	v_cmp_le_i32_e32 vcc, v137, v128
	v_subrev_u32_e32 v137, 47, v136
	s_nop 0
	v_cndmask_b32_e32 v57, v194, v57, vcc
	v_cmp_le_i32_e32 vcc, v137, v128
	v_add_u32_e32 v137, -15, v136
	s_nop 0
	v_cndmask_b32_e32 v74, v194, v74, vcc
	v_cmp_le_i32_e32 vcc, v137, v128
	v_subrev_u32_e32 v137, 46, v136
	s_nop 0
	v_cndmask_b32_e32 v58, v194, v58, vcc
	v_cmp_le_i32_e32 vcc, v137, v128
	v_add_u32_e32 v137, -14, v136
	s_nop 0
	v_cndmask_b32_e32 v75, v194, v75, vcc
	v_cmp_le_i32_e32 vcc, v137, v128
	v_subrev_u32_e32 v137, 45, v136
	s_nop 0
	v_cndmask_b32_e32 v59, v194, v59, vcc
	v_cmp_le_i32_e32 vcc, v137, v128
	v_add_u32_e32 v137, -13, v136
	s_nop 0
	v_cndmask_b32_e32 v76, v194, v76, vcc
	v_cmp_le_i32_e32 vcc, v137, v128
	v_subrev_u32_e32 v137, 44, v136
	s_nop 0
	v_cndmask_b32_e32 v60, v194, v60, vcc
	v_cmp_le_i32_e32 vcc, v137, v128
	v_add_u32_e32 v137, -12, v136
	s_nop 0
	v_cndmask_b32_e32 v77, v194, v77, vcc
	v_cmp_le_i32_e32 vcc, v137, v128
	v_subrev_u32_e32 v137, 39, v136
	s_nop 0
	v_cndmask_b32_e32 v61, v194, v61, vcc
	v_cmp_le_i32_e32 vcc, v137, v128
	v_add_u32_e32 v137, -7, v136
	s_nop 0
	v_cndmask_b32_e32 v78, v194, v78, vcc
	v_cmp_le_i32_e32 vcc, v137, v128
	v_subrev_u32_e32 v137, 38, v136
	s_nop 0
	v_cndmask_b32_e32 v62, v194, v62, vcc
	v_cmp_le_i32_e32 vcc, v137, v128
	v_add_u32_e32 v137, -6, v136
	s_nop 0
	v_cndmask_b32_e32 v79, v194, v79, vcc
	v_cmp_le_i32_e32 vcc, v137, v128
	v_subrev_u32_e32 v137, 37, v136
	s_nop 0
	v_cndmask_b32_e32 v63, v194, v63, vcc
	v_cmp_le_i32_e32 vcc, v137, v128
	v_add_u32_e32 v137, -5, v136
	s_nop 0
	v_cndmask_b32_e32 v80, v194, v80, vcc
	v_cmp_le_i32_e32 vcc, v137, v128
	v_subrev_u32_e32 v137, 36, v136
	v_add_u32_e32 v136, -4, v136
	v_cndmask_b32_e32 v64, v194, v64, vcc
	v_cmp_le_i32_e32 vcc, v137, v128
	s_nop 1
	v_cndmask_b32_e32 v81, v194, v81, vcc
	v_cmp_le_i32_e32 vcc, v136, v128
	s_nop 1
	v_cndmask_b32_e32 v65, v194, v65, vcc

.LBB0_534:
	v_exp_f32_e32 v136, v66
	v_exp_f32_e32 v137, v67
	v_exp_f32_e32 v138, v68
	v_exp_f32_e32 v139, v69
	v_add_f32_e32 v66, 0, v136
	v_exp_f32_e32 v162, v70
	v_add_f32_e32 v66, v137, v66
	v_exp_f32_e32 v163, v71
	v_add_f32_e32 v66, v138, v66
	v_exp_f32_e32 v164, v72
	v_add_f32_e32 v66, v139, v66
	v_exp_f32_e32 v165, v73
	v_add_f32_e32 v66, v162, v66
	v_exp_f32_e32 v166, v74
	v_add_f32_e32 v66, v163, v66
	v_exp_f32_e32 v167, v75
	v_add_f32_e32 v66, v164, v66
	v_exp_f32_e32 v168, v76
	v_add_f32_e32 v66, v165, v66
	v_exp_f32_e32 v169, v77
	v_add_f32_e32 v66, v166, v66
	v_exp_f32_e32 v170, v78
	v_exp_f32_e32 v171, v79
	v_exp_f32_e32 v79, v62
	v_cvt_pk_bf16_f32 v62, v136, v137
	v_add_f32_e32 v66, v167, v66
	v_add_f32_e32 v66, v168, v66
	v_exp_f32_e32 v172, v80
	v_exp_f32_e32 v173, v81
	v_exp_f32_e32 v81, v64
	v_exp_f32_e32 v161, v65
	v_cvt_pk_bf16_f32 v64, v162, v163
	v_cvt_pk_bf16_f32 v65, v164, v165
	v_add_f32_e32 v66, v169, v66
	v_add_f32_e32 v66, v170, v66
	v_add_f32_e32 v66, v171, v66
	v_add_f32_e32 v66, v172, v66
	v_add_f32_e32 v66, v173, v66
	v_exp_f32_e32 v75, v58
	v_exp_f32_e32 v76, v59
	v_exp_f32_e32 v77, v60
	v_exp_f32_e32 v78, v61
	v_cvt_pk_bf16_f32 v58, v166, v167
	v_cvt_pk_bf16_f32 v59, v168, v169
	v_cvt_pk_bf16_f32 v60, v170, v171
	v_cvt_pk_bf16_f32 v61, v172, v173
	v_exp_f32_e32 v80, v63
	v_cvt_pk_bf16_f32 v63, v138, v139
	v_exp_f32_e32 v67, v50
	v_exp_f32_e32 v68, v51
	s_waitcnt lgkmcnt(7)
	v_mfma_f32_32x32x16_bf16 v[2:17], v[196:199], v[62:65], v[2:17]
	v_exp_f32_e32 v69, v52
	v_exp_f32_e32 v70, v53
	v_exp_f32_e32 v71, v54
	v_exp_f32_e32 v72, v55
	v_exp_f32_e32 v73, v56
	v_exp_f32_e32 v74, v57
	v_cvt_pk_bf16_f32 v54, v67, v68
	s_waitcnt lgkmcnt(6)
	v_mfma_f32_32x32x16_bf16 v[18:33], v[200:203], v[62:65], v[18:33]
	v_cvt_pk_bf16_f32 v55, v69, v70
	v_cvt_pk_bf16_f32 v56, v71, v72
	v_cvt_pk_bf16_f32 v57, v73, v74
	v_cvt_pk_bf16_f32 v50, v75, v76
	v_cvt_pk_bf16_f32 v51, v77, v78
	v_cvt_pk_bf16_f32 v52, v79, v80
	s_waitcnt lgkmcnt(5)
	v_mfma_f32_32x32x16_bf16 v[2:17], v[204:207], v[58:61], v[2:17]
	v_cvt_pk_bf16_f32 v53, v81, v161
	s_waitcnt lgkmcnt(4)
	v_mfma_f32_32x32x16_bf16 v[18:33], v[208:211], v[58:61], v[18:33]
	s_waitcnt lgkmcnt(3)
	v_mfma_f32_32x32x16_bf16 v[2:17], v[212:215], v[54:57], v[2:17]
	s_waitcnt lgkmcnt(2)
	v_mfma_f32_32x32x16_bf16 v[18:33], v[216:219], v[54:57], v[18:33]
	s_waitcnt lgkmcnt(1)
	v_mfma_f32_32x32x16_bf16 v[2:17], v[220:223], v[50:53], v[2:17]
	s_waitcnt lgkmcnt(0)
	v_mfma_f32_32x32x16_bf16 v[18:33], v[224:227], v[50:53], v[18:33]
	v_add_f32_e32 v50, v67, v66
	v_add_f32_e32 v50, v68, v50
	v_add_f32_e32 v50, v69, v50
	v_add_f32_e32 v50, v70, v50
	v_add_f32_e32 v50, v71, v50
	v_add_f32_e32 v50, v72, v50
	v_add_f32_e32 v50, v73, v50
	v_add_f32_e32 v50, v74, v50
	v_add_f32_e32 v50, v75, v50
	v_add_f32_e32 v50, v76, v50
	v_add_f32_e32 v50, v77, v50
	v_add_f32_e32 v50, v78, v50
	v_add_f32_e32 v50, v79, v50
	v_add_f32_e32 v50, v80, v50
	v_add_f32_e32 v50, v81, v50
	v_add_f32_e32 v50, v161, v50
	v_add_f32_e32 v158, v158, v50
	s_add_i32 s43, s41, 1
	s_cmp_gt_i32 s43, s39
	s_cbranch_scc1 .LBB0_526
.LBB0_535:
	ds_read_b128 v[196:199], v160 offset:13312
	ds_read_b128 v[200:203], v160 offset:19968
	ds_read_b128 v[204:207], v160 offset:13344
	ds_read_b128 v[208:211], v160 offset:20000
	ds_read_b128 v[212:215], v160 offset:13376
	ds_read_b128 v[216:219], v160 offset:20032
	ds_read_b128 v[220:223], v160 offset:13408
	ds_read_b128 v[224:227], v160 offset:20064
	ds_read_b128 v[228:231], v160 offset:13440
	ds_read_b128 v[232:235], v160 offset:20096
	ds_read_b128 v[236:239], v160 offset:13472
	ds_read_b128 v[240:243], v160 offset:20128
	s_add_i32 s43, s41, 64
	s_cmp_le_i32 s43, s50
	s_waitcnt lgkmcnt(11)
	v_mfma_f32_32x32x16_bf16 v[66:81], v[196:199], v[82:85], v[34:49]
	s_waitcnt lgkmcnt(10)
	v_mfma_f32_32x32x16_bf16 v[50:65], v[200:203], v[82:85], v[34:49]
	s_waitcnt lgkmcnt(9)
	v_mfma_f32_32x32x16_bf16 v[66:81], v[204:207], v[86:89], v[66:81]
	s_waitcnt lgkmcnt(8)
	v_mfma_f32_32x32x16_bf16 v[50:65], v[208:211], v[86:89], v[50:65]
	s_waitcnt lgkmcnt(7)
	v_mfma_f32_32x32x16_bf16 v[66:81], v[212:215], v[90:93], v[66:81]
	s_waitcnt lgkmcnt(6)
	v_mfma_f32_32x32x16_bf16 v[50:65], v[216:219], v[90:93], v[50:65]
	s_waitcnt lgkmcnt(5)
	v_mfma_f32_32x32x16_bf16 v[66:81], v[220:223], v[94:97], v[66:81]
	s_waitcnt lgkmcnt(4)
	v_mfma_f32_32x32x16_bf16 v[50:65], v[224:227], v[94:97], v[50:65]
	s_waitcnt lgkmcnt(3)
	v_mfma_f32_32x32x16_bf16 v[66:81], v[228:231], v[98:101], v[66:81]
	s_waitcnt lgkmcnt(2)
	v_mfma_f32_32x32x16_bf16 v[50:65], v[232:235], v[98:101], v[50:65]
	s_waitcnt lgkmcnt(1)
	v_mfma_f32_32x32x16_bf16 v[66:81], v[236:239], v[102:105], v[66:81]
	s_waitcnt lgkmcnt(0)
	v_mfma_f32_32x32x16_bf16 v[50:65], v[240:243], v[102:105], v[50:65]
	v_add_u32_e32 v244, s37, v156
	v_add_u32_e32 v245, 0xf000, v244
	v_add_u32_e32 v244, 0xd000, v244
	ds_read2_b64 v[196:199], v244 offset0:16 offset1:18
	ds_read2_b64 v[200:203], v245 offset0:48 offset1:50
	ds_read2_b64 v[204:207], v244 offset0:20 offset1:22
	ds_read2_b64 v[208:211], v245 offset0:52 offset1:54
	ds_read2_b64 v[212:215], v244 offset0:24 offset1:26
	ds_read2_b64 v[216:219], v245 offset0:56 offset1:58
	ds_read2_b64 v[220:223], v244 offset0:28 offset1:30
	ds_read2_b64 v[224:227], v245 offset0:60 offset1:62
	s_cbranch_scc1 .LBB0_537
	v_add_u32_e32 v136, s41, v129
	v_add_u32_e32 v138, 33, v136
	v_add_u32_e32 v137, 1, v136
	v_cmp_le_i32_e32 vcc, v138, v128
	s_nop 6
	v_cndmask_b32_e32 v50, v194, v50, vcc
	v_cmp_lt_i32_e32 vcc, v137, v128
	s_nop 1
	v_cndmask_b32_e32 v67, v194, v67, vcc
	v_cmp_le_i32_e32 vcc, v137, v128
	v_add_u32_e32 v137, 34, v136
	s_nop 0
	v_cndmask_b32_e32 v66, v194, v66, vcc
	v_cmp_le_i32_e32 vcc, v137, v128
	v_add_u32_e32 v137, 3, v136
	s_nop 0
	v_cndmask_b32_e32 v51, v194, v51, vcc
	v_cmp_le_i32_e32 vcc, v137, v128
	v_add_u32_e32 v137, 35, v136
	s_nop 0
	v_cndmask_b32_e32 v68, v194, v68, vcc
	v_cmp_le_i32_e32 vcc, v137, v128
	v_add_u32_e32 v137, 4, v136
	s_nop 0
	v_cndmask_b32_e32 v52, v194, v52, vcc
	v_cmp_le_i32_e32 vcc, v137, v128
	v_add_u32_e32 v137, 36, v136
	s_nop 0
	v_cndmask_b32_e32 v69, v194, v69, vcc
	v_cmp_le_i32_e32 vcc, v137, v128
	v_add_u32_e32 v137, 9, v136
	s_nop 0
	v_cndmask_b32_e32 v53, v194, v53, vcc
	v_cmp_le_i32_e32 vcc, v137, v128
	v_add_u32_e32 v137, 41, v136
	s_nop 0
	v_cndmask_b32_e32 v70, v194, v70, vcc
	v_cmp_le_i32_e32 vcc, v137, v128
	v_add_u32_e32 v137, 10, v136
	s_nop 0
	v_cndmask_b32_e32 v54, v194, v54, vcc
	v_cmp_le_i32_e32 vcc, v137, v128
	v_add_u32_e32 v137, 42, v136
	s_nop 0
	v_cndmask_b32_e32 v71, v194, v71, vcc
	v_cmp_le_i32_e32 vcc, v137, v128
	v_add_u32_e32 v137, 11, v136
	s_nop 0
	v_cndmask_b32_e32 v55, v194, v55, vcc
	v_cmp_le_i32_e32 vcc, v137, v128
	v_add_u32_e32 v137, 43, v136
	s_nop 0
	v_cndmask_b32_e32 v72, v194, v72, vcc
	v_cmp_le_i32_e32 vcc, v137, v128
	v_add_u32_e32 v137, 12, v136
	s_nop 0
	v_cndmask_b32_e32 v56, v194, v56, vcc
	v_cmp_le_i32_e32 vcc, v137, v128
	v_add_u32_e32 v137, 44, v136
	s_nop 0
	v_cndmask_b32_e32 v73, v194, v73, vcc
	v_cmp_le_i32_e32 vcc, v137, v128
	v_add_u32_e32 v137, 17, v136
	s_nop 0
	v_cndmask_b32_e32 v57, v194, v57, vcc
	v_cmp_le_i32_e32 vcc, v137, v128
	v_add_u32_e32 v137, 49, v136
	s_nop 0
	v_cndmask_b32_e32 v74, v194, v74, vcc
	v_cmp_le_i32_e32 vcc, v137, v128
	v_add_u32_e32 v137, 18, v136
	s_nop 0
	v_cndmask_b32_e32 v58, v194, v58, vcc
	v_cmp_le_i32_e32 vcc, v137, v128
	v_add_u32_e32 v137, 50, v136
	s_nop 0
	v_cndmask_b32_e32 v75, v194, v75, vcc
	v_cmp_le_i32_e32 vcc, v137, v128
	v_add_u32_e32 v137, 19, v136
	s_nop 0
	v_cndmask_b32_e32 v59, v194, v59, vcc
	v_cmp_le_i32_e32 vcc, v137, v128
	v_add_u32_e32 v137, 51, v136
	s_nop 0
	v_cndmask_b32_e32 v76, v194, v76, vcc
	v_cmp_le_i32_e32 vcc, v137, v128
	v_add_u32_e32 v137, 20, v136
	s_nop 0
	v_cndmask_b32_e32 v60, v194, v60, vcc
	v_cmp_le_i32_e32 vcc, v137, v128
	v_add_u32_e32 v137, 52, v136
	s_nop 0
	v_cndmask_b32_e32 v77, v194, v77, vcc
	v_cmp_le_i32_e32 vcc, v137, v128
	v_add_u32_e32 v137, 25, v136
	s_nop 0
	v_cndmask_b32_e32 v61, v194, v61, vcc
	v_cmp_le_i32_e32 vcc, v137, v128
	v_add_u32_e32 v137, 57, v136
	s_nop 0
	v_cndmask_b32_e32 v78, v194, v78, vcc
	v_cmp_le_i32_e32 vcc, v137, v128
	v_add_u32_e32 v137, 26, v136
	s_nop 0
	v_cndmask_b32_e32 v62, v194, v62, vcc
	v_cmp_le_i32_e32 vcc, v137, v128
	v_add_u32_e32 v137, 58, v136
	s_nop 0
	v_cndmask_b32_e32 v79, v194, v79, vcc
	v_cmp_le_i32_e32 vcc, v137, v128
	v_add_u32_e32 v137, 27, v136
	s_nop 0
	v_cndmask_b32_e32 v63, v194, v63, vcc
	v_cmp_le_i32_e32 vcc, v137, v128
	v_add_u32_e32 v137, 59, v136
	s_nop 0
	v_cndmask_b32_e32 v80, v194, v80, vcc
	v_cmp_le_i32_e32 vcc, v137, v128
	v_add_u32_e32 v137, 28, v136
	v_add_u32_e32 v136, 60, v136
	v_cndmask_b32_e32 v64, v194, v64, vcc
	v_cmp_le_i32_e32 vcc, v137, v128
	s_nop 1
	v_cndmask_b32_e32 v81, v194, v81, vcc
	v_cmp_le_i32_e32 vcc, v136, v128
	s_nop 1
	v_cndmask_b32_e32 v65, v194, v65, vcc

.LBB0_539:
	v_exp_f32_e32 v136, v66
	v_exp_f32_e32 v137, v67
	v_exp_f32_e32 v138, v68
	v_exp_f32_e32 v139, v69
	v_add_f32_e32 v66, 0, v136
	v_exp_f32_e32 v161, v70
	v_add_f32_e32 v66, v137, v66
	v_exp_f32_e32 v162, v71
	v_add_f32_e32 v66, v138, v66
	v_exp_f32_e32 v163, v72
	v_add_f32_e32 v66, v139, v66
	v_exp_f32_e32 v164, v73
	v_add_f32_e32 v66, v161, v66
	v_exp_f32_e32 v165, v74
	v_add_f32_e32 v66, v162, v66
	v_exp_f32_e32 v166, v75
	v_add_f32_e32 v66, v163, v66
	v_exp_f32_e32 v167, v76
	v_add_f32_e32 v66, v164, v66
	v_exp_f32_e32 v168, v77
	v_add_f32_e32 v66, v165, v66
	v_exp_f32_e32 v169, v78
	v_exp_f32_e32 v170, v79
	v_exp_f32_e32 v79, v62
	v_cvt_pk_bf16_f32 v62, v136, v137
	v_add_f32_e32 v66, v166, v66
	v_add_f32_e32 v66, v167, v66
	v_exp_f32_e32 v171, v80
	v_exp_f32_e32 v172, v81
	v_exp_f32_e32 v75, v58
	v_exp_f32_e32 v81, v64
	v_exp_f32_e32 v160, v65
	v_cvt_pk_bf16_f32 v64, v161, v162
	v_cvt_pk_bf16_f32 v65, v163, v164
	v_cvt_pk_bf16_f32 v58, v165, v166
	v_add_f32_e32 v66, v168, v66
	v_add_f32_e32 v66, v169, v66
	v_add_f32_e32 v66, v170, v66
	v_add_f32_e32 v66, v171, v66
	v_add_f32_e32 v66, v172, v66
	v_exp_f32_e32 v76, v59
	v_exp_f32_e32 v77, v60
	v_exp_f32_e32 v78, v61
	v_cvt_pk_bf16_f32 v59, v167, v168
	v_cvt_pk_bf16_f32 v60, v169, v170
	v_cvt_pk_bf16_f32 v61, v171, v172
	v_exp_f32_e32 v80, v63
	v_cvt_pk_bf16_f32 v63, v138, v139
	v_exp_f32_e32 v67, v50
	v_exp_f32_e32 v68, v51
	s_waitcnt lgkmcnt(7)
	v_mfma_f32_32x32x16_bf16 v[2:17], v[196:199], v[62:65], v[2:17]
	v_exp_f32_e32 v69, v52
	v_exp_f32_e32 v70, v53
	v_exp_f32_e32 v71, v54
	v_exp_f32_e32 v72, v55
	v_exp_f32_e32 v73, v56
	v_exp_f32_e32 v74, v57
	v_cvt_pk_bf16_f32 v54, v67, v68
	s_waitcnt lgkmcnt(6)
	v_mfma_f32_32x32x16_bf16 v[18:33], v[200:203], v[62:65], v[18:33]
	v_cvt_pk_bf16_f32 v55, v69, v70
	v_cvt_pk_bf16_f32 v56, v71, v72
	v_cvt_pk_bf16_f32 v57, v73, v74
	v_cvt_pk_bf16_f32 v50, v75, v76
	v_cvt_pk_bf16_f32 v51, v77, v78
	v_cvt_pk_bf16_f32 v52, v79, v80
	s_waitcnt lgkmcnt(5)
	v_mfma_f32_32x32x16_bf16 v[2:17], v[204:207], v[58:61], v[2:17]
	v_cvt_pk_bf16_f32 v53, v81, v160
	s_waitcnt lgkmcnt(4)
	v_mfma_f32_32x32x16_bf16 v[18:33], v[208:211], v[58:61], v[18:33]
	s_waitcnt lgkmcnt(3)
	v_mfma_f32_32x32x16_bf16 v[2:17], v[212:215], v[54:57], v[2:17]
	s_waitcnt lgkmcnt(2)
	v_mfma_f32_32x32x16_bf16 v[18:33], v[216:219], v[54:57], v[18:33]
	s_waitcnt lgkmcnt(1)
	v_mfma_f32_32x32x16_bf16 v[2:17], v[220:223], v[50:53], v[2:17]
	s_waitcnt lgkmcnt(0)
	v_mfma_f32_32x32x16_bf16 v[18:33], v[224:227], v[50:53], v[18:33]
	v_add_f32_e32 v50, v67, v66
	v_add_f32_e32 v50, v68, v50
	v_add_f32_e32 v50, v69, v50
	v_add_f32_e32 v50, v70, v50
	v_add_f32_e32 v50, v71, v50
	v_add_f32_e32 v50, v72, v50
	v_add_f32_e32 v50, v73, v50
	v_add_f32_e32 v50, v74, v50
	v_add_f32_e32 v50, v75, v50
	v_add_f32_e32 v50, v76, v50
	v_add_f32_e32 v50, v77, v50
	v_add_f32_e32 v50, v78, v50
	v_add_f32_e32 v50, v79, v50
	v_add_f32_e32 v50, v80, v50
	v_add_f32_e32 v50, v81, v50
	v_add_f32_e32 v50, v160, v50
	v_add_f32_e32 v158, v158, v50
	s_and_b64 vcc, exec, s[2:3]
	s_cbranch_vccnz .LBB0_527
	s_branch .LBB0_528

.LBB0_892:
	v_ashrrev_i32_e32 v2, 7, v25
	v_add_u32_e32 v22, s54, v2
	v_cmp_gt_i32_e64 s[42:43], 0, v0
	v_cmp_ne_u32_e64 s[40:41], -1, v0
	s_and_saveexec_b64 s[2:3], s[42:43]
	s_xor_b64 s[2:3], exec, s[2:3]
	s_cbranch_execz .LBB0_896
	v_mov_b32_e32 v2, 0
	s_and_saveexec_b64 s[44:45], s[40:41]
	s_cbranch_execz .LBB0_895
	v_mad_i64_i32 v[2:3], s[28:29], v22, s91, 0
	v_lshl_add_u64 v[2:3], v[2:3], 2, s[0:1]
	s_mov_b64 s[28:29], 0x1000
	v_lshl_add_u64 v[14:15], v[2:3], 0, s[28:29]
	v_add_co_u32_e32 v2, vcc, 0x1000, v2
	v_sub_u32_e32 v18, -2, v0
	v_mov_b32_e32 v19, v1
	v_addc_co_u32_e32 v3, vcc, 0, v3, vcc
	v_lshl_add_u64 v[18:19], v[18:19], 2, s[76:77]
	v_sub_u32_e32 v216, -2, v0
	v_mov_b32_e32 v217, v1
	v_lshl_add_u64 v[216:217], v[216:217], 2, s[76:77]
	s_mov_b64 s[98:99], 0x1000
	global_load_dword v200, v[216:217], off
	global_load_dword v201, v[216:217], off offset:1024
	global_load_dword v202, v[216:217], off offset:2048
	global_load_dword v203, v[216:217], off offset:3072
	v_lshl_add_u64 v[216:217], v[216:217], 0, s[98:99]
	global_load_dword v204, v[216:217], off
	global_load_dword v205, v[216:217], off offset:1024
	global_load_dword v206, v[216:217], off offset:2048
	global_load_dword v207, v[216:217], off offset:3072
	v_lshl_add_u64 v[216:217], v[216:217], 0, s[98:99]
	global_load_dword v208, v[216:217], off
	global_load_dword v209, v[216:217], off offset:1024
	global_load_dword v210, v[216:217], off offset:2048
	global_load_dword v211, v[216:217], off offset:3072
	v_lshl_add_u64 v[216:217], v[216:217], 0, s[98:99]
	global_load_dword v212, v[216:217], off
	global_load_dword v213, v[216:217], off offset:1024
	global_load_dword v214, v[216:217], off offset:2048
	global_load_dword v215, v[216:217], off offset:3072
	global_load_dwordx4 v[6:9], v[2:3], off
	s_nop 0
	global_load_dwordx4 v[2:5], v[14:15], off offset:48
	global_load_dwordx4 v[10:13], v[14:15], off offset:32
	s_nop 0
	global_load_dwordx4 v[14:17], v[14:15], off offset:16
	s_nop 0
	s_waitcnt vmcnt(0)
	v_mov_b32_e32 v18, v200
	v_fma_f32 v20, v6, v18, 0
	v_sub_u32_e32 v18, 0xfe, v0
	v_ashrrev_i32_e32 v19, 31, v18
	v_lshl_add_u64 v[18:19], v[18:19], 2, s[76:77]
	s_waitcnt vmcnt(0)
	v_mov_b32_e32 v6, v201
	v_fmac_f32_e32 v20, v7, v6
	v_sub_u32_e32 v6, 0x1fe, v0
	v_ashrrev_i32_e32 v7, 31, v6
	v_lshl_add_u64 v[6:7], v[6:7], 2, s[76:77]
	s_waitcnt vmcnt(0)
	v_mov_b32_e32 v6, v202
	v_fmac_f32_e32 v20, v8, v6
	v_sub_u32_e32 v6, 0x2fe, v0
	v_ashrrev_i32_e32 v7, 31, v6
	v_lshl_add_u64 v[6:7], v[6:7], 2, s[76:77]
	v_sub_u32_e32 v8, 0x4fe, v0
	s_waitcnt vmcnt(0)
	v_mov_b32_e32 v6, v203
	v_fmac_f32_e32 v20, v9, v6
	v_sub_u32_e32 v6, 0x3fe, v0
	v_ashrrev_i32_e32 v7, 31, v6
	v_ashrrev_i32_e32 v9, 31, v8
	v_lshl_add_u64 v[6:7], v[6:7], 2, s[76:77]
	v_lshl_add_u64 v[8:9], v[8:9], 2, s[76:77]
	s_nop 0
	v_sub_u32_e32 v8, 0x6fe, v0
	v_ashrrev_i32_e32 v9, 31, v8
	v_lshl_add_u64 v[8:9], v[8:9], 2, s[76:77]
	s_waitcnt vmcnt(0)
	v_mov_b32_e32 v6, v204
	v_mov_b32_e32 v7, v205
	v_pk_mul_f32 v[6:7], v[14:15], v[6:7]
	s_nop 0
	v_add_f32_e32 v6, v20, v6
	v_add_f32_e32 v14, v6, v7
	v_sub_u32_e32 v6, 0x5fe, v0
	v_ashrrev_i32_e32 v7, 31, v6
	v_lshl_add_u64 v[6:7], v[6:7], 2, s[76:77]
	s_nop 0
	v_sub_u32_e32 v8, 0x8fe, v0
	v_ashrrev_i32_e32 v9, 31, v8
	v_lshl_add_u64 v[8:9], v[8:9], 2, s[76:77]
	s_waitcnt vmcnt(0)
	v_mov_b32_e32 v6, v206
	v_mov_b32_e32 v7, v207
	v_pk_mul_f32 v[6:7], v[16:17], v[6:7]
	s_nop 0
	v_add_f32_e32 v6, v14, v6
	v_add_f32_e32 v14, v6, v7
	v_sub_u32_e32 v6, 0x7fe, v0
	v_ashrrev_i32_e32 v7, 31, v6
	v_lshl_add_u64 v[6:7], v[6:7], 2, s[76:77]
	s_nop 0
	v_sub_u32_e32 v8, 0xafe, v0
	v_ashrrev_i32_e32 v9, 31, v8
	v_lshl_add_u64 v[8:9], v[8:9], 2, s[76:77]
	s_waitcnt vmcnt(0)
	v_mov_b32_e32 v6, v208
	v_mov_b32_e32 v7, v209
	v_pk_mul_f32 v[6:7], v[10:11], v[6:7]
	s_nop 0
	v_add_f32_e32 v6, v14, v6
	v_add_f32_e32 v10, v6, v7
	v_sub_u32_e32 v6, 0x9fe, v0
	v_ashrrev_i32_e32 v7, 31, v6
	v_lshl_add_u64 v[6:7], v[6:7], 2, s[76:77]
	s_nop 0
	v_sub_u32_e32 v8, 0xcfe, v0
	v_ashrrev_i32_e32 v9, 31, v8
	v_lshl_add_u64 v[8:9], v[8:9], 2, s[76:77]
	s_waitcnt vmcnt(0)
	v_mov_b32_e32 v6, v210
	v_mov_b32_e32 v7, v211
	v_pk_mul_f32 v[6:7], v[12:13], v[6:7]
	s_nop 0
	v_add_f32_e32 v6, v10, v6
	v_add_f32_e32 v10, v6, v7
	v_sub_u32_e32 v6, 0xbfe, v0
	v_ashrrev_i32_e32 v7, 31, v6
	v_lshl_add_u64 v[6:7], v[6:7], 2, s[76:77]
	s_nop 0
	s_waitcnt vmcnt(0)
	v_mov_b32_e32 v6, v212
	v_mov_b32_e32 v7, v213
	v_pk_mul_f32 v[2:3], v[2:3], v[6:7]
	s_nop 0
	v_add_f32_e32 v2, v10, v2
	v_add_f32_e32 v8, v2, v3
	v_sub_u32_e32 v2, 0xdfe, v0
	v_sub_u32_e32 v6, 0xefe, v0
	v_ashrrev_i32_e32 v3, 31, v2
	v_ashrrev_i32_e32 v7, 31, v6
	v_lshl_add_u64 v[2:3], v[2:3], 2, s[76:77]
	v_lshl_add_u64 v[6:7], v[6:7], 2, s[76:77]
	s_nop 0
	s_waitcnt vmcnt(0)
	v_mov_b32_e32 v2, v214
	v_mov_b32_e32 v3, v215
	v_pk_mul_f32 v[2:3], v[4:5], v[2:3]
	s_nop 0
	v_add_f32_e32 v2, v8, v2
	v_add_f32_e32 v2, v2, v3

.LBB0_900:
	v_add_u32_e32 v4, 4, v22
	s_and_saveexec_b64 s[28:29], s[42:43]
	s_xor_b64 s[44:45], exec, s[28:29]
	s_cbranch_execz .LBB0_904
	v_mov_b32_e32 v3, 0
	s_and_saveexec_b64 s[58:59], s[40:41]
	s_cbranch_execz .LBB0_903
	v_mad_i64_i32 v[4:5], s[28:29], v4, s91, 0
	v_lshl_add_u64 v[4:5], v[4:5], 2, s[0:1]
	s_mov_b64 s[28:29], 0x1000
	v_lshl_add_u64 v[16:17], v[4:5], 0, s[28:29]
	v_add_co_u32_e32 v4, vcc, 0x1000, v4
	v_sub_u32_e32 v26, -2, v0
	v_mov_b32_e32 v27, v1
	v_addc_co_u32_e32 v5, vcc, 0, v5, vcc
	v_lshl_add_u64 v[26:27], v[26:27], 2, s[76:77]
	v_sub_u32_e32 v216, -2, v0
	v_mov_b32_e32 v217, v1
	v_lshl_add_u64 v[216:217], v[216:217], 2, s[76:77]
	s_mov_b64 s[98:99], 0x1000
	global_load_dword v200, v[216:217], off
	global_load_dword v201, v[216:217], off offset:1024
	global_load_dword v202, v[216:217], off offset:2048
	global_load_dword v203, v[216:217], off offset:3072
	v_lshl_add_u64 v[216:217], v[216:217], 0, s[98:99]
	global_load_dword v204, v[216:217], off
	global_load_dword v205, v[216:217], off offset:1024
	global_load_dword v206, v[216:217], off offset:2048
	global_load_dword v207, v[216:217], off offset:3072
	v_lshl_add_u64 v[216:217], v[216:217], 0, s[98:99]
	global_load_dword v208, v[216:217], off
	global_load_dword v209, v[216:217], off offset:1024
	global_load_dword v210, v[216:217], off offset:2048
	global_load_dword v211, v[216:217], off offset:3072
	v_lshl_add_u64 v[216:217], v[216:217], 0, s[98:99]
	global_load_dword v212, v[216:217], off
	global_load_dword v213, v[216:217], off offset:1024
	global_load_dword v214, v[216:217], off offset:2048
	global_load_dword v215, v[216:217], off offset:3072
	global_load_dwordx4 v[8:11], v[4:5], off
	s_nop 0
	global_load_dwordx4 v[4:7], v[16:17], off offset:48
	global_load_dwordx4 v[12:15], v[16:17], off offset:32
	s_nop 0
	global_load_dwordx4 v[16:19], v[16:17], off offset:16
	s_nop 0
	v_sub_u32_e32 v26, 0xfe, v0
	v_ashrrev_i32_e32 v27, 31, v26
	v_lshl_add_u64 v[26:27], v[26:27], 2, s[76:77]
	s_waitcnt vmcnt(0)
	v_mov_b32_e32 v3, v200
	v_fma_f32 v3, v8, v3, 0
	s_waitcnt vmcnt(0)
	v_mov_b32_e32 v8, v201
	v_fmac_f32_e32 v3, v9, v8
	v_sub_u32_e32 v8, 0x1fe, v0
	v_ashrrev_i32_e32 v9, 31, v8
	v_lshl_add_u64 v[8:9], v[8:9], 2, s[76:77]
	s_waitcnt vmcnt(0)
	v_mov_b32_e32 v8, v202
	v_fmac_f32_e32 v3, v10, v8
	v_sub_u32_e32 v8, 0x2fe, v0
	v_ashrrev_i32_e32 v9, 31, v8
	v_lshl_add_u64 v[8:9], v[8:9], 2, s[76:77]
	v_sub_u32_e32 v10, 0x4fe, v0
	s_waitcnt vmcnt(0)
	v_mov_b32_e32 v8, v203
	v_fmac_f32_e32 v3, v11, v8
	v_sub_u32_e32 v8, 0x3fe, v0
	v_ashrrev_i32_e32 v9, 31, v8
	v_ashrrev_i32_e32 v11, 31, v10
	v_lshl_add_u64 v[8:9], v[8:9], 2, s[76:77]
	v_lshl_add_u64 v[10:11], v[10:11], 2, s[76:77]
	s_nop 0
	v_sub_u32_e32 v10, 0x6fe, v0
	v_ashrrev_i32_e32 v11, 31, v10
	v_lshl_add_u64 v[10:11], v[10:11], 2, s[76:77]
	s_waitcnt vmcnt(0)
	v_mov_b32_e32 v8, v204
	v_mov_b32_e32 v9, v205
	v_pk_mul_f32 v[8:9], v[16:17], v[8:9]
	s_nop 0
	v_add_f32_e32 v3, v3, v8
	v_sub_u32_e32 v8, 0x5fe, v0
	v_add_f32_e32 v3, v3, v9
	v_ashrrev_i32_e32 v9, 31, v8
	v_lshl_add_u64 v[8:9], v[8:9], 2, s[76:77]
	s_nop 0
	v_sub_u32_e32 v10, 0x8fe, v0
	v_ashrrev_i32_e32 v11, 31, v10
	v_lshl_add_u64 v[10:11], v[10:11], 2, s[76:77]
	s_waitcnt vmcnt(0)
	v_mov_b32_e32 v8, v206
	v_mov_b32_e32 v9, v207
	v_pk_mul_f32 v[8:9], v[18:19], v[8:9]
	s_nop 0
	v_add_f32_e32 v3, v3, v8
	v_sub_u32_e32 v8, 0x7fe, v0
	v_add_f32_e32 v3, v3, v9
	v_ashrrev_i32_e32 v9, 31, v8
	v_lshl_add_u64 v[8:9], v[8:9], 2, s[76:77]
	s_nop 0
	v_sub_u32_e32 v10, 0xafe, v0
	v_ashrrev_i32_e32 v11, 31, v10
	v_lshl_add_u64 v[10:11], v[10:11], 2, s[76:77]
	s_waitcnt vmcnt(0)
	v_mov_b32_e32 v8, v208
	v_mov_b32_e32 v9, v209
	v_pk_mul_f32 v[8:9], v[12:13], v[8:9]
	s_nop 0
	v_add_f32_e32 v3, v3, v8
	v_sub_u32_e32 v8, 0x9fe, v0
	v_add_f32_e32 v3, v3, v9
	v_ashrrev_i32_e32 v9, 31, v8
	v_lshl_add_u64 v[8:9], v[8:9], 2, s[76:77]
	s_nop 0
	v_sub_u32_e32 v10, 0xcfe, v0
	v_ashrrev_i32_e32 v11, 31, v10
	v_lshl_add_u64 v[10:11], v[10:11], 2, s[76:77]
	s_waitcnt vmcnt(0)
	v_mov_b32_e32 v8, v210
	v_mov_b32_e32 v9, v211
	v_pk_mul_f32 v[8:9], v[14:15], v[8:9]
	s_nop 0
	v_add_f32_e32 v3, v3, v8
	v_sub_u32_e32 v8, 0xbfe, v0
	v_add_f32_e32 v3, v3, v9
	v_ashrrev_i32_e32 v9, 31, v8
	v_lshl_add_u64 v[8:9], v[8:9], 2, s[76:77]
	s_nop 0
	s_waitcnt vmcnt(0)
	v_mov_b32_e32 v8, v212
	v_mov_b32_e32 v9, v213
	v_pk_mul_f32 v[4:5], v[4:5], v[8:9]
	s_nop 0
	v_add_f32_e32 v3, v3, v4
	v_sub_u32_e32 v4, 0xdfe, v0
	v_sub_u32_e32 v8, 0xefe, v0
	v_add_f32_e32 v3, v3, v5
	v_ashrrev_i32_e32 v5, 31, v4
	v_ashrrev_i32_e32 v9, 31, v8
	v_lshl_add_u64 v[4:5], v[4:5], 2, s[76:77]
	v_lshl_add_u64 v[8:9], v[8:9], 2, s[76:77]
	s_nop 0
	s_waitcnt vmcnt(0)
	v_mov_b32_e32 v4, v214
	v_mov_b32_e32 v5, v215
	v_pk_mul_f32 v[4:5], v[6:7], v[4:5]
	s_nop 0
	v_add_f32_e32 v3, v3, v4
	v_add_f32_e32 v3, v3, v5

.LBB0_1049:
	v_ashrrev_i32_e32 v2, 7, v23
	v_add_u32_e32 v24, s92, v2
	v_cmp_gt_i32_e64 s[40:41], 0, v0
	v_cmp_ne_u32_e64 s[38:39], -1, v0
	s_and_saveexec_b64 s[2:3], s[40:41]
	s_xor_b64 s[2:3], exec, s[2:3]
	s_cbranch_execz .LBB0_1053
	v_mov_b32_e32 v2, 0
	s_and_saveexec_b64 s[42:43], s[38:39]
	s_cbranch_execz .LBB0_1052
	v_mad_i64_i32 v[2:3], s[28:29], v24, s91, 0
	v_lshl_add_u64 v[2:3], v[2:3], 2, s[0:1]
	s_mov_b64 s[28:29], 0x1000
	v_lshl_add_u64 v[14:15], v[2:3], 0, s[28:29]
	v_add_co_u32_e32 v2, vcc, 0x1000, v2
	v_sub_u32_e32 v18, -2, v0
	v_mov_b32_e32 v19, v1
	v_addc_co_u32_e32 v3, vcc, 0, v3, vcc
	v_lshl_add_u64 v[18:19], v[18:19], 2, s[52:53]
	v_sub_u32_e32 v216, -2, v0
	v_mov_b32_e32 v217, v1
	v_lshl_add_u64 v[216:217], v[216:217], 2, s[52:53]
	s_mov_b64 s[98:99], 0x1000
	global_load_dword v200, v[216:217], off
	global_load_dword v201, v[216:217], off offset:1024
	global_load_dword v202, v[216:217], off offset:2048
	global_load_dword v203, v[216:217], off offset:3072
	v_lshl_add_u64 v[216:217], v[216:217], 0, s[98:99]
	global_load_dword v204, v[216:217], off
	global_load_dword v205, v[216:217], off offset:1024
	global_load_dword v206, v[216:217], off offset:2048
	global_load_dword v207, v[216:217], off offset:3072
	v_lshl_add_u64 v[216:217], v[216:217], 0, s[98:99]
	global_load_dword v208, v[216:217], off
	global_load_dword v209, v[216:217], off offset:1024
	global_load_dword v210, v[216:217], off offset:2048
	global_load_dword v211, v[216:217], off offset:3072
	v_lshl_add_u64 v[216:217], v[216:217], 0, s[98:99]
	global_load_dword v212, v[216:217], off
	global_load_dword v213, v[216:217], off offset:1024
	global_load_dword v214, v[216:217], off offset:2048
	global_load_dword v215, v[216:217], off offset:3072
	global_load_dwordx4 v[6:9], v[2:3], off
	s_nop 0
	global_load_dwordx4 v[2:5], v[14:15], off offset:48
	global_load_dwordx4 v[10:13], v[14:15], off offset:32
	s_nop 0
	global_load_dwordx4 v[14:17], v[14:15], off offset:16
	s_nop 0
	s_waitcnt vmcnt(0)
	v_mov_b32_e32 v18, v200
	v_fma_f32 v20, v6, v18, 0
	v_sub_u32_e32 v18, 0xfe, v0
	v_ashrrev_i32_e32 v19, 31, v18
	v_lshl_add_u64 v[18:19], v[18:19], 2, s[52:53]
	s_waitcnt vmcnt(0)
	v_mov_b32_e32 v6, v201
	v_fmac_f32_e32 v20, v7, v6
	v_sub_u32_e32 v6, 0x1fe, v0
	v_ashrrev_i32_e32 v7, 31, v6
	v_lshl_add_u64 v[6:7], v[6:7], 2, s[52:53]
	s_waitcnt vmcnt(0)
	v_mov_b32_e32 v6, v202
	v_fmac_f32_e32 v20, v8, v6
	v_sub_u32_e32 v6, 0x2fe, v0
	v_ashrrev_i32_e32 v7, 31, v6
	v_lshl_add_u64 v[6:7], v[6:7], 2, s[52:53]
	v_sub_u32_e32 v8, 0x4fe, v0
	s_waitcnt vmcnt(0)
	v_mov_b32_e32 v6, v203
	v_fmac_f32_e32 v20, v9, v6
	v_sub_u32_e32 v6, 0x3fe, v0
	v_ashrrev_i32_e32 v7, 31, v6
	v_ashrrev_i32_e32 v9, 31, v8
	v_lshl_add_u64 v[6:7], v[6:7], 2, s[52:53]
	v_lshl_add_u64 v[8:9], v[8:9], 2, s[52:53]
	s_nop 0
	v_sub_u32_e32 v8, 0x6fe, v0
	v_ashrrev_i32_e32 v9, 31, v8
	v_lshl_add_u64 v[8:9], v[8:9], 2, s[52:53]
	s_waitcnt vmcnt(0)
	v_mov_b32_e32 v6, v204
	v_mov_b32_e32 v7, v205
	v_pk_mul_f32 v[6:7], v[14:15], v[6:7]
	s_nop 0
	v_add_f32_e32 v6, v20, v6
	v_add_f32_e32 v14, v6, v7
	v_sub_u32_e32 v6, 0x5fe, v0
	v_ashrrev_i32_e32 v7, 31, v6
	v_lshl_add_u64 v[6:7], v[6:7], 2, s[52:53]
	s_nop 0
	v_sub_u32_e32 v8, 0x8fe, v0
	v_ashrrev_i32_e32 v9, 31, v8
	v_lshl_add_u64 v[8:9], v[8:9], 2, s[52:53]
	s_waitcnt vmcnt(0)
	v_mov_b32_e32 v6, v206
	v_mov_b32_e32 v7, v207
	v_pk_mul_f32 v[6:7], v[16:17], v[6:7]
	s_nop 0
	v_add_f32_e32 v6, v14, v6
	v_add_f32_e32 v14, v6, v7
	v_sub_u32_e32 v6, 0x7fe, v0
	v_ashrrev_i32_e32 v7, 31, v6
	v_lshl_add_u64 v[6:7], v[6:7], 2, s[52:53]
	s_nop 0
	v_sub_u32_e32 v8, 0xafe, v0
	v_ashrrev_i32_e32 v9, 31, v8
	v_lshl_add_u64 v[8:9], v[8:9], 2, s[52:53]
	s_waitcnt vmcnt(0)
	v_mov_b32_e32 v6, v208
	v_mov_b32_e32 v7, v209
	v_pk_mul_f32 v[6:7], v[10:11], v[6:7]
	s_nop 0
	v_add_f32_e32 v6, v14, v6
	v_add_f32_e32 v10, v6, v7
	v_sub_u32_e32 v6, 0x9fe, v0
	v_ashrrev_i32_e32 v7, 31, v6
	v_lshl_add_u64 v[6:7], v[6:7], 2, s[52:53]
	s_nop 0
	v_sub_u32_e32 v8, 0xcfe, v0
	v_ashrrev_i32_e32 v9, 31, v8
	v_lshl_add_u64 v[8:9], v[8:9], 2, s[52:53]
	s_waitcnt vmcnt(0)
	v_mov_b32_e32 v6, v210
	v_mov_b32_e32 v7, v211
	v_pk_mul_f32 v[6:7], v[12:13], v[6:7]
	s_nop 0
	v_add_f32_e32 v6, v10, v6
	v_add_f32_e32 v10, v6, v7
	v_sub_u32_e32 v6, 0xbfe, v0
	v_ashrrev_i32_e32 v7, 31, v6
	v_lshl_add_u64 v[6:7], v[6:7], 2, s[52:53]
	s_nop 0
	s_waitcnt vmcnt(0)
	v_mov_b32_e32 v6, v212
	v_mov_b32_e32 v7, v213
	v_pk_mul_f32 v[2:3], v[2:3], v[6:7]
	s_nop 0
	v_add_f32_e32 v2, v10, v2
	v_add_f32_e32 v8, v2, v3
	v_sub_u32_e32 v2, 0xdfe, v0
	v_sub_u32_e32 v6, 0xefe, v0
	v_ashrrev_i32_e32 v3, 31, v2
	v_ashrrev_i32_e32 v7, 31, v6
	v_lshl_add_u64 v[2:3], v[2:3], 2, s[52:53]
	v_lshl_add_u64 v[6:7], v[6:7], 2, s[52:53]
	s_nop 0
	s_waitcnt vmcnt(0)
	v_mov_b32_e32 v2, v214
	v_mov_b32_e32 v3, v215
	v_pk_mul_f32 v[2:3], v[4:5], v[2:3]
	s_nop 0
	v_add_f32_e32 v2, v8, v2
	v_add_f32_e32 v2, v2, v3

.LBB0_1057:
	v_add_u32_e32 v4, 4, v24
	s_and_saveexec_b64 s[28:29], s[40:41]
	s_xor_b64 s[42:43], exec, s[28:29]
	s_cbranch_execz .LBB0_1061
	v_mov_b32_e32 v3, 0
	s_and_saveexec_b64 s[58:59], s[38:39]
	s_cbranch_execz .LBB0_1060
	v_mad_i64_i32 v[4:5], s[28:29], v4, s91, 0
	v_lshl_add_u64 v[4:5], v[4:5], 2, s[0:1]
	s_mov_b64 s[28:29], 0x1000
	v_lshl_add_u64 v[16:17], v[4:5], 0, s[28:29]
	v_add_co_u32_e32 v4, vcc, 0x1000, v4
	v_sub_u32_e32 v36, -2, v0
	v_mov_b32_e32 v37, v1
	v_addc_co_u32_e32 v5, vcc, 0, v5, vcc
	v_lshl_add_u64 v[36:37], v[36:37], 2, s[52:53]
	v_sub_u32_e32 v216, -2, v0
	v_mov_b32_e32 v217, v1
	v_lshl_add_u64 v[216:217], v[216:217], 2, s[52:53]
	s_mov_b64 s[98:99], 0x1000
	global_load_dword v200, v[216:217], off
	global_load_dword v201, v[216:217], off offset:1024
	global_load_dword v202, v[216:217], off offset:2048
	global_load_dword v203, v[216:217], off offset:3072
	v_lshl_add_u64 v[216:217], v[216:217], 0, s[98:99]
	global_load_dword v204, v[216:217], off
	global_load_dword v205, v[216:217], off offset:1024
	global_load_dword v206, v[216:217], off offset:2048
	global_load_dword v207, v[216:217], off offset:3072
	v_lshl_add_u64 v[216:217], v[216:217], 0, s[98:99]
	global_load_dword v208, v[216:217], off
	global_load_dword v209, v[216:217], off offset:1024
	global_load_dword v210, v[216:217], off offset:2048
	global_load_dword v211, v[216:217], off offset:3072
	v_lshl_add_u64 v[216:217], v[216:217], 0, s[98:99]
	global_load_dword v212, v[216:217], off
	global_load_dword v213, v[216:217], off offset:1024
	global_load_dword v214, v[216:217], off offset:2048
	global_load_dword v215, v[216:217], off offset:3072
	global_load_dwordx4 v[8:11], v[4:5], off
	s_nop 0
	global_load_dwordx4 v[4:7], v[16:17], off offset:48
	global_load_dwordx4 v[12:15], v[16:17], off offset:32
	s_nop 0
	global_load_dwordx4 v[16:19], v[16:17], off offset:16
	s_nop 0
	v_sub_u32_e32 v36, 0xfe, v0
	v_ashrrev_i32_e32 v37, 31, v36
	v_lshl_add_u64 v[36:37], v[36:37], 2, s[52:53]
	s_waitcnt vmcnt(0)
	v_mov_b32_e32 v3, v200
	v_fma_f32 v3, v8, v3, 0
	s_waitcnt vmcnt(0)
	v_mov_b32_e32 v8, v201
	v_fmac_f32_e32 v3, v9, v8
	v_sub_u32_e32 v8, 0x1fe, v0
	v_ashrrev_i32_e32 v9, 31, v8
	v_lshl_add_u64 v[8:9], v[8:9], 2, s[52:53]
	s_waitcnt vmcnt(0)
	v_mov_b32_e32 v8, v202
	v_fmac_f32_e32 v3, v10, v8
	v_sub_u32_e32 v8, 0x2fe, v0
	v_ashrrev_i32_e32 v9, 31, v8
	v_lshl_add_u64 v[8:9], v[8:9], 2, s[52:53]
	v_sub_u32_e32 v10, 0x4fe, v0
	s_waitcnt vmcnt(0)
	v_mov_b32_e32 v8, v203
	v_fmac_f32_e32 v3, v11, v8
	v_sub_u32_e32 v8, 0x3fe, v0
	v_ashrrev_i32_e32 v9, 31, v8
	v_ashrrev_i32_e32 v11, 31, v10
	v_lshl_add_u64 v[8:9], v[8:9], 2, s[52:53]
	v_lshl_add_u64 v[10:11], v[10:11], 2, s[52:53]
	s_nop 0
	v_sub_u32_e32 v10, 0x6fe, v0
	v_ashrrev_i32_e32 v11, 31, v10
	v_lshl_add_u64 v[10:11], v[10:11], 2, s[52:53]
	s_waitcnt vmcnt(0)
	v_mov_b32_e32 v8, v204
	v_mov_b32_e32 v9, v205
	v_pk_mul_f32 v[8:9], v[16:17], v[8:9]
	s_nop 0
	v_add_f32_e32 v3, v3, v8
	v_sub_u32_e32 v8, 0x5fe, v0
	v_add_f32_e32 v3, v3, v9
	v_ashrrev_i32_e32 v9, 31, v8
	v_lshl_add_u64 v[8:9], v[8:9], 2, s[52:53]
	s_nop 0
	v_sub_u32_e32 v10, 0x8fe, v0
	v_ashrrev_i32_e32 v11, 31, v10
	v_lshl_add_u64 v[10:11], v[10:11], 2, s[52:53]
	s_waitcnt vmcnt(0)
	v_mov_b32_e32 v8, v206
	v_mov_b32_e32 v9, v207
	v_pk_mul_f32 v[8:9], v[18:19], v[8:9]
	s_nop 0
	v_add_f32_e32 v3, v3, v8
	v_sub_u32_e32 v8, 0x7fe, v0
	v_add_f32_e32 v3, v3, v9
	v_ashrrev_i32_e32 v9, 31, v8
	v_lshl_add_u64 v[8:9], v[8:9], 2, s[52:53]
	s_nop 0
	v_sub_u32_e32 v10, 0xafe, v0
	v_ashrrev_i32_e32 v11, 31, v10
	v_lshl_add_u64 v[10:11], v[10:11], 2, s[52:53]
	s_waitcnt vmcnt(0)
	v_mov_b32_e32 v8, v208
	v_mov_b32_e32 v9, v209
	v_pk_mul_f32 v[8:9], v[12:13], v[8:9]
	s_nop 0
	v_add_f32_e32 v3, v3, v8
	v_sub_u32_e32 v8, 0x9fe, v0
	v_add_f32_e32 v3, v3, v9
	v_ashrrev_i32_e32 v9, 31, v8
	v_lshl_add_u64 v[8:9], v[8:9], 2, s[52:53]
	s_nop 0
	v_sub_u32_e32 v10, 0xcfe, v0
	v_ashrrev_i32_e32 v11, 31, v10
	v_lshl_add_u64 v[10:11], v[10:11], 2, s[52:53]
	s_waitcnt vmcnt(0)
	v_mov_b32_e32 v8, v210
	v_mov_b32_e32 v9, v211
	v_pk_mul_f32 v[8:9], v[14:15], v[8:9]
	s_nop 0
	v_add_f32_e32 v3, v3, v8
	v_sub_u32_e32 v8, 0xbfe, v0
	v_add_f32_e32 v3, v3, v9
	v_ashrrev_i32_e32 v9, 31, v8
	v_lshl_add_u64 v[8:9], v[8:9], 2, s[52:53]
	s_nop 0
	s_waitcnt vmcnt(0)
	v_mov_b32_e32 v8, v212
	v_mov_b32_e32 v9, v213
	v_pk_mul_f32 v[4:5], v[4:5], v[8:9]
	s_nop 0
	v_add_f32_e32 v3, v3, v4
	v_sub_u32_e32 v4, 0xdfe, v0
	v_sub_u32_e32 v8, 0xefe, v0
	v_add_f32_e32 v3, v3, v5
	v_ashrrev_i32_e32 v5, 31, v4
	v_ashrrev_i32_e32 v9, 31, v8
	v_lshl_add_u64 v[4:5], v[4:5], 2, s[52:53]
	v_lshl_add_u64 v[8:9], v[8:9], 2, s[52:53]
	s_nop 0
	s_waitcnt vmcnt(0)
	v_mov_b32_e32 v4, v214
	v_mov_b32_e32 v5, v215
	v_pk_mul_f32 v[4:5], v[6:7], v[4:5]
	s_nop 0
	v_add_f32_e32 v3, v3, v4
	v_add_f32_e32 v3, v3, v5

.LBB0_1131:
	v_mov_b32_e32 v4, 0
	s_and_saveexec_b64 s[58:59], s[38:39]
	s_cbranch_execz .LBB0_1133
	v_mad_i64_i32 v[4:5], s[28:29], v5, s91, 0
	v_lshl_add_u64 v[4:5], v[4:5], 2, s[0:1]
	s_mov_b64 s[28:29], 0x1000
	v_lshl_add_u64 v[16:17], v[4:5], 0, s[28:29]
	v_add_co_u32_e32 v4, vcc, 0x1000, v4
	v_sub_u32_e32 v36, -2, v0
	v_mov_b32_e32 v37, v1
	v_addc_co_u32_e32 v5, vcc, 0, v5, vcc
	v_lshl_add_u64 v[36:37], v[36:37], 2, s[52:53]
	v_sub_u32_e32 v216, -2, v0
	v_mov_b32_e32 v217, v1
	v_lshl_add_u64 v[216:217], v[216:217], 2, s[52:53]
	s_mov_b64 s[98:99], 0x1000
	global_load_dword v200, v[216:217], off
	global_load_dword v201, v[216:217], off offset:1024
	global_load_dword v202, v[216:217], off offset:2048
	global_load_dword v203, v[216:217], off offset:3072
	v_lshl_add_u64 v[216:217], v[216:217], 0, s[98:99]
	global_load_dword v204, v[216:217], off
	global_load_dword v205, v[216:217], off offset:1024
	global_load_dword v206, v[216:217], off offset:2048
	global_load_dword v207, v[216:217], off offset:3072
	v_lshl_add_u64 v[216:217], v[216:217], 0, s[98:99]
	global_load_dword v208, v[216:217], off
	global_load_dword v209, v[216:217], off offset:1024
	global_load_dword v210, v[216:217], off offset:2048
	global_load_dword v211, v[216:217], off offset:3072
	v_lshl_add_u64 v[216:217], v[216:217], 0, s[98:99]
	global_load_dword v212, v[216:217], off
	global_load_dword v213, v[216:217], off offset:1024
	global_load_dword v214, v[216:217], off offset:2048
	global_load_dword v215, v[216:217], off offset:3072
	global_load_dwordx4 v[8:11], v[4:5], off
	s_nop 0
	global_load_dwordx4 v[4:7], v[16:17], off offset:48
	global_load_dwordx4 v[12:15], v[16:17], off offset:32
	s_nop 0
	global_load_dwordx4 v[16:19], v[16:17], off offset:16
	s_nop 0
	v_sub_u32_e32 v36, 0xfe, v0
	v_ashrrev_i32_e32 v37, 31, v36
	v_lshl_add_u64 v[36:37], v[36:37], 2, s[52:53]
	s_waitcnt vmcnt(0)
	v_mov_b32_e32 v35, v200
	v_fma_f32 v35, v8, v35, 0
	s_waitcnt vmcnt(0)
	v_mov_b32_e32 v8, v201
	v_fmac_f32_e32 v35, v9, v8
	v_sub_u32_e32 v8, 0x1fe, v0
	v_ashrrev_i32_e32 v9, 31, v8
	v_lshl_add_u64 v[8:9], v[8:9], 2, s[52:53]
	s_waitcnt vmcnt(0)
	v_mov_b32_e32 v8, v202
	v_fmac_f32_e32 v35, v10, v8
	v_sub_u32_e32 v8, 0x2fe, v0
	v_ashrrev_i32_e32 v9, 31, v8
	v_lshl_add_u64 v[8:9], v[8:9], 2, s[52:53]
	v_sub_u32_e32 v10, 0x4fe, v0
	s_waitcnt vmcnt(0)
	v_mov_b32_e32 v8, v203
	v_fmac_f32_e32 v35, v11, v8
	v_sub_u32_e32 v8, 0x3fe, v0
	v_ashrrev_i32_e32 v9, 31, v8
	v_ashrrev_i32_e32 v11, 31, v10
	v_lshl_add_u64 v[8:9], v[8:9], 2, s[52:53]
	v_lshl_add_u64 v[10:11], v[10:11], 2, s[52:53]
	s_nop 0
	v_sub_u32_e32 v10, 0x6fe, v0
	v_ashrrev_i32_e32 v11, 31, v10
	v_lshl_add_u64 v[10:11], v[10:11], 2, s[52:53]
	s_waitcnt vmcnt(0)
	v_mov_b32_e32 v8, v204
	v_mov_b32_e32 v9, v205
	v_pk_mul_f32 v[8:9], v[16:17], v[8:9]
	s_nop 0
	v_add_f32_e32 v8, v35, v8
	v_add_f32_e32 v16, v8, v9
	v_sub_u32_e32 v8, 0x5fe, v0
	v_ashrrev_i32_e32 v9, 31, v8
	v_lshl_add_u64 v[8:9], v[8:9], 2, s[52:53]
	s_nop 0
	v_sub_u32_e32 v10, 0x8fe, v0
	v_ashrrev_i32_e32 v11, 31, v10
	v_lshl_add_u64 v[10:11], v[10:11], 2, s[52:53]
	s_waitcnt vmcnt(0)
	v_mov_b32_e32 v8, v206
	v_mov_b32_e32 v9, v207
	v_pk_mul_f32 v[8:9], v[18:19], v[8:9]
	s_nop 0
	v_add_f32_e32 v8, v16, v8
	v_add_f32_e32 v16, v8, v9
	v_sub_u32_e32 v8, 0x7fe, v0
	v_ashrrev_i32_e32 v9, 31, v8
	v_lshl_add_u64 v[8:9], v[8:9], 2, s[52:53]
	s_nop 0
	v_sub_u32_e32 v10, 0xafe, v0
	v_ashrrev_i32_e32 v11, 31, v10
	v_lshl_add_u64 v[10:11], v[10:11], 2, s[52:53]
	s_waitcnt vmcnt(0)
	v_mov_b32_e32 v8, v208
	v_mov_b32_e32 v9, v209
	v_pk_mul_f32 v[8:9], v[12:13], v[8:9]
	s_nop 0
	v_add_f32_e32 v8, v16, v8
	v_add_f32_e32 v12, v8, v9
	v_sub_u32_e32 v8, 0x9fe, v0
	v_ashrrev_i32_e32 v9, 31, v8
	v_lshl_add_u64 v[8:9], v[8:9], 2, s[52:53]
	s_nop 0
	v_sub_u32_e32 v10, 0xcfe, v0
	v_ashrrev_i32_e32 v11, 31, v10
	v_lshl_add_u64 v[10:11], v[10:11], 2, s[52:53]
	s_waitcnt vmcnt(0)
	v_mov_b32_e32 v8, v210
	v_mov_b32_e32 v9, v211
	v_pk_mul_f32 v[8:9], v[14:15], v[8:9]
	s_nop 0
	v_add_f32_e32 v8, v12, v8
	v_add_f32_e32 v12, v8, v9
	v_sub_u32_e32 v8, 0xbfe, v0
	v_ashrrev_i32_e32 v9, 31, v8
	v_lshl_add_u64 v[8:9], v[8:9], 2, s[52:53]
	s_nop 0
	s_waitcnt vmcnt(0)
	v_mov_b32_e32 v8, v212
	v_mov_b32_e32 v9, v213
	v_pk_mul_f32 v[4:5], v[4:5], v[8:9]
	s_nop 0
	v_add_f32_e32 v4, v12, v4
	v_add_f32_e32 v10, v4, v5
	v_sub_u32_e32 v4, 0xdfe, v0
	v_sub_u32_e32 v8, 0xefe, v0
	v_ashrrev_i32_e32 v5, 31, v4
	v_ashrrev_i32_e32 v9, 31, v8
	v_lshl_add_u64 v[4:5], v[4:5], 2, s[52:53]
	v_lshl_add_u64 v[8:9], v[8:9], 2, s[52:53]
	s_nop 0
	s_waitcnt vmcnt(0)
	v_mov_b32_e32 v4, v214
	v_mov_b32_e32 v5, v215
	v_pk_mul_f32 v[4:5], v[6:7], v[4:5]
	s_nop 0
	v_add_f32_e32 v4, v10, v4
	v_add_f32_e32 v4, v4, v5

.LBB0_1135:
	v_mov_b32_e32 v5, 0
	s_and_saveexec_b64 s[58:59], s[38:39]
	s_cbranch_execz .LBB0_1137
	v_mad_i64_i32 v[6:7], s[28:29], v6, s91, 0
	v_lshl_add_u64 v[6:7], v[6:7], 2, s[0:1]
	s_mov_b64 s[28:29], 0x1000
	v_lshl_add_u64 v[18:19], v[6:7], 0, s[28:29]
	v_add_co_u32_e32 v6, vcc, 0x1000, v6
	s_nop 1
	v_addc_co_u32_e32 v7, vcc, 0, v7, vcc
	v_sub_u32_e32 v216, -2, v0
	v_mov_b32_e32 v217, v1
	v_lshl_add_u64 v[216:217], v[216:217], 2, s[52:53]
	s_mov_b64 s[98:99], 0x1000
	global_load_dword v200, v[216:217], off
	global_load_dword v201, v[216:217], off offset:1024
	global_load_dword v202, v[216:217], off offset:2048
	global_load_dword v203, v[216:217], off offset:3072
	v_lshl_add_u64 v[216:217], v[216:217], 0, s[98:99]
	global_load_dword v204, v[216:217], off
	global_load_dword v205, v[216:217], off offset:1024
	global_load_dword v206, v[216:217], off offset:2048
	global_load_dword v207, v[216:217], off offset:3072
	v_lshl_add_u64 v[216:217], v[216:217], 0, s[98:99]
	global_load_dword v208, v[216:217], off
	global_load_dword v209, v[216:217], off offset:1024
	global_load_dword v210, v[216:217], off offset:2048
	global_load_dword v211, v[216:217], off offset:3072
	v_lshl_add_u64 v[216:217], v[216:217], 0, s[98:99]
	global_load_dword v212, v[216:217], off
	global_load_dword v213, v[216:217], off offset:1024
	global_load_dword v214, v[216:217], off offset:2048
	global_load_dword v215, v[216:217], off offset:3072
	global_load_dwordx4 v[10:13], v[6:7], off
	s_nop 0
	global_load_dwordx4 v[6:9], v[18:19], off offset:48
	global_load_dwordx4 v[14:17], v[18:19], off offset:32
	global_load_dwordx4 v[36:39], v[18:19], off offset:16
	v_sub_u32_e32 v18, -2, v0
	v_mov_b32_e32 v19, v1
	v_lshl_add_u64 v[18:19], v[18:19], 2, s[52:53]
	v_sub_u32_e32 v18, 0xfe, v0
	v_ashrrev_i32_e32 v19, 31, v18
	v_lshl_add_u64 v[18:19], v[18:19], 2, s[52:53]
	s_waitcnt vmcnt(0)
	v_mov_b32_e32 v5, v200
	v_fma_f32 v5, v10, v5, 0
	s_waitcnt vmcnt(0)
	v_mov_b32_e32 v10, v201
	v_fmac_f32_e32 v5, v11, v10
	v_sub_u32_e32 v10, 0x1fe, v0
	v_ashrrev_i32_e32 v11, 31, v10
	v_lshl_add_u64 v[10:11], v[10:11], 2, s[52:53]
	s_waitcnt vmcnt(0)
	v_mov_b32_e32 v10, v202
	v_fmac_f32_e32 v5, v12, v10
	v_sub_u32_e32 v10, 0x2fe, v0
	v_ashrrev_i32_e32 v11, 31, v10
	v_lshl_add_u64 v[10:11], v[10:11], 2, s[52:53]
	v_sub_u32_e32 v12, 0x4fe, v0
	s_waitcnt vmcnt(0)
	v_mov_b32_e32 v10, v203
	v_fmac_f32_e32 v5, v13, v10
	v_sub_u32_e32 v10, 0x3fe, v0
	v_ashrrev_i32_e32 v11, 31, v10
	v_ashrrev_i32_e32 v13, 31, v12
	v_lshl_add_u64 v[10:11], v[10:11], 2, s[52:53]
	v_lshl_add_u64 v[12:13], v[12:13], 2, s[52:53]
	s_nop 0
	v_sub_u32_e32 v12, 0x6fe, v0
	v_ashrrev_i32_e32 v13, 31, v12
	v_lshl_add_u64 v[12:13], v[12:13], 2, s[52:53]
	s_waitcnt vmcnt(0)
	v_mov_b32_e32 v10, v204
	v_mov_b32_e32 v11, v205
	v_pk_mul_f32 v[10:11], v[36:37], v[10:11]
	s_nop 0
	v_add_f32_e32 v5, v5, v10
	v_sub_u32_e32 v10, 0x5fe, v0
	v_add_f32_e32 v5, v5, v11
	v_ashrrev_i32_e32 v11, 31, v10
	v_lshl_add_u64 v[10:11], v[10:11], 2, s[52:53]
	s_nop 0
	v_sub_u32_e32 v12, 0x8fe, v0
	v_ashrrev_i32_e32 v13, 31, v12
	v_lshl_add_u64 v[12:13], v[12:13], 2, s[52:53]
	s_waitcnt vmcnt(0)
	v_mov_b32_e32 v10, v206
	v_mov_b32_e32 v11, v207
	v_pk_mul_f32 v[10:11], v[38:39], v[10:11]
	s_nop 0
	v_add_f32_e32 v5, v5, v10
	v_sub_u32_e32 v10, 0x7fe, v0
	v_add_f32_e32 v5, v5, v11
	v_ashrrev_i32_e32 v11, 31, v10
	v_lshl_add_u64 v[10:11], v[10:11], 2, s[52:53]
	s_nop 0
	v_sub_u32_e32 v12, 0xafe, v0
	v_ashrrev_i32_e32 v13, 31, v12
	v_lshl_add_u64 v[12:13], v[12:13], 2, s[52:53]
	s_waitcnt vmcnt(0)
	v_mov_b32_e32 v10, v208
	v_mov_b32_e32 v11, v209
	v_pk_mul_f32 v[10:11], v[14:15], v[10:11]
	s_nop 0
	v_add_f32_e32 v5, v5, v10
	v_sub_u32_e32 v10, 0x9fe, v0
	v_add_f32_e32 v5, v5, v11
	v_ashrrev_i32_e32 v11, 31, v10
	v_lshl_add_u64 v[10:11], v[10:11], 2, s[52:53]
	s_nop 0
	v_sub_u32_e32 v12, 0xcfe, v0
	v_ashrrev_i32_e32 v13, 31, v12
	v_lshl_add_u64 v[12:13], v[12:13], 2, s[52:53]
	s_waitcnt vmcnt(0)
	v_mov_b32_e32 v10, v210
	v_mov_b32_e32 v11, v211
	v_pk_mul_f32 v[10:11], v[16:17], v[10:11]
	s_nop 0
	v_add_f32_e32 v5, v5, v10
	v_sub_u32_e32 v10, 0xbfe, v0
	v_add_f32_e32 v5, v5, v11
	v_ashrrev_i32_e32 v11, 31, v10
	v_lshl_add_u64 v[10:11], v[10:11], 2, s[52:53]
	s_nop 0
	s_waitcnt vmcnt(0)
	v_mov_b32_e32 v10, v212
	v_mov_b32_e32 v11, v213
	v_pk_mul_f32 v[6:7], v[6:7], v[10:11]
	s_nop 0
	v_add_f32_e32 v5, v5, v6
	v_sub_u32_e32 v6, 0xdfe, v0
	v_sub_u32_e32 v10, 0xefe, v0
	v_add_f32_e32 v5, v5, v7
	v_ashrrev_i32_e32 v7, 31, v6
	v_ashrrev_i32_e32 v11, 31, v10
	v_lshl_add_u64 v[6:7], v[6:7], 2, s[52:53]
	v_lshl_add_u64 v[10:11], v[10:11], 2, s[52:53]
	s_nop 0
	s_waitcnt vmcnt(0)
	v_mov_b32_e32 v6, v214
	v_mov_b32_e32 v7, v215
	v_pk_mul_f32 v[6:7], v[8:9], v[6:7]
	s_nop 0
	v_add_f32_e32 v5, v5, v6
	v_add_f32_e32 v5, v5, v7

.LBB0_1139:
	v_mov_b32_e32 v6, 0
	s_and_saveexec_b64 s[58:59], s[38:39]
	s_cbranch_execz .LBB0_1141
	v_mad_i64_i32 v[6:7], s[28:29], v7, s91, 0
	v_lshl_add_u64 v[6:7], v[6:7], 2, s[0:1]
	s_mov_b64 s[28:29], 0x1000
	v_lshl_add_u64 v[18:19], v[6:7], 0, s[28:29]
	v_add_co_u32_e32 v6, vcc, 0x1000, v6
	s_nop 1
	v_addc_co_u32_e32 v7, vcc, 0, v7, vcc
	v_sub_u32_e32 v216, -2, v0
	v_mov_b32_e32 v217, v1
	v_lshl_add_u64 v[216:217], v[216:217], 2, s[52:53]
	s_mov_b64 s[98:99], 0x1000
	global_load_dword v200, v[216:217], off
	global_load_dword v201, v[216:217], off offset:1024
	global_load_dword v202, v[216:217], off offset:2048
	global_load_dword v203, v[216:217], off offset:3072
	v_lshl_add_u64 v[216:217], v[216:217], 0, s[98:99]
	global_load_dword v204, v[216:217], off
	global_load_dword v205, v[216:217], off offset:1024
	global_load_dword v206, v[216:217], off offset:2048
	global_load_dword v207, v[216:217], off offset:3072
	v_lshl_add_u64 v[216:217], v[216:217], 0, s[98:99]
	global_load_dword v208, v[216:217], off
	global_load_dword v209, v[216:217], off offset:1024
	global_load_dword v210, v[216:217], off offset:2048
	global_load_dword v211, v[216:217], off offset:3072
	v_lshl_add_u64 v[216:217], v[216:217], 0, s[98:99]
	global_load_dword v212, v[216:217], off
	global_load_dword v213, v[216:217], off offset:1024
	global_load_dword v214, v[216:217], off offset:2048
	global_load_dword v215, v[216:217], off offset:3072
	global_load_dwordx4 v[10:13], v[6:7], off
	s_nop 0
	global_load_dwordx4 v[6:9], v[18:19], off offset:48
	global_load_dwordx4 v[14:17], v[18:19], off offset:32
	global_load_dwordx4 v[36:39], v[18:19], off offset:16
	v_sub_u32_e32 v18, -2, v0
	v_mov_b32_e32 v19, v1
	v_lshl_add_u64 v[18:19], v[18:19], 2, s[52:53]
	s_waitcnt vmcnt(0)
	v_mov_b32_e32 v18, v200
	v_fma_f32 v35, v10, v18, 0
	v_sub_u32_e32 v18, 0xfe, v0
	v_ashrrev_i32_e32 v19, 31, v18
	v_lshl_add_u64 v[18:19], v[18:19], 2, s[52:53]
	s_waitcnt vmcnt(0)
	v_mov_b32_e32 v10, v201
	v_fmac_f32_e32 v35, v11, v10
	v_sub_u32_e32 v10, 0x1fe, v0
	v_ashrrev_i32_e32 v11, 31, v10
	v_lshl_add_u64 v[10:11], v[10:11], 2, s[52:53]
	s_waitcnt vmcnt(0)
	v_mov_b32_e32 v10, v202
	v_fmac_f32_e32 v35, v12, v10
	v_sub_u32_e32 v10, 0x2fe, v0
	v_ashrrev_i32_e32 v11, 31, v10
	v_lshl_add_u64 v[10:11], v[10:11], 2, s[52:53]
	v_sub_u32_e32 v12, 0x4fe, v0
	s_waitcnt vmcnt(0)
	v_mov_b32_e32 v10, v203
	v_fmac_f32_e32 v35, v13, v10
	v_sub_u32_e32 v10, 0x3fe, v0
	v_ashrrev_i32_e32 v11, 31, v10
	v_ashrrev_i32_e32 v13, 31, v12
	v_lshl_add_u64 v[10:11], v[10:11], 2, s[52:53]
	v_lshl_add_u64 v[12:13], v[12:13], 2, s[52:53]
	s_nop 0
	v_sub_u32_e32 v12, 0x6fe, v0
	v_ashrrev_i32_e32 v13, 31, v12
	v_lshl_add_u64 v[12:13], v[12:13], 2, s[52:53]
	s_waitcnt vmcnt(0)
	v_mov_b32_e32 v10, v204
	v_mov_b32_e32 v11, v205
	v_pk_mul_f32 v[10:11], v[36:37], v[10:11]
	s_nop 0
	v_add_f32_e32 v10, v35, v10
	v_add_f32_e32 v18, v10, v11
	v_sub_u32_e32 v10, 0x5fe, v0
	v_ashrrev_i32_e32 v11, 31, v10
	v_lshl_add_u64 v[10:11], v[10:11], 2, s[52:53]
	s_nop 0
	v_sub_u32_e32 v12, 0x8fe, v0
	v_ashrrev_i32_e32 v13, 31, v12
	v_lshl_add_u64 v[12:13], v[12:13], 2, s[52:53]
	s_waitcnt vmcnt(0)
	v_mov_b32_e32 v10, v206
	v_mov_b32_e32 v11, v207
	v_pk_mul_f32 v[10:11], v[38:39], v[10:11]
	s_nop 0
	v_add_f32_e32 v10, v18, v10
	v_add_f32_e32 v18, v10, v11
	v_sub_u32_e32 v10, 0x7fe, v0
	v_ashrrev_i32_e32 v11, 31, v10
	v_lshl_add_u64 v[10:11], v[10:11], 2, s[52:53]
	s_nop 0
	v_sub_u32_e32 v12, 0xafe, v0
	v_ashrrev_i32_e32 v13, 31, v12
	v_lshl_add_u64 v[12:13], v[12:13], 2, s[52:53]
	s_waitcnt vmcnt(0)
	v_mov_b32_e32 v10, v208
	v_mov_b32_e32 v11, v209
	v_pk_mul_f32 v[10:11], v[14:15], v[10:11]
	s_nop 0
	v_add_f32_e32 v10, v18, v10
	v_add_f32_e32 v14, v10, v11
	v_sub_u32_e32 v10, 0x9fe, v0
	v_ashrrev_i32_e32 v11, 31, v10
	v_lshl_add_u64 v[10:11], v[10:11], 2, s[52:53]
	s_nop 0
	v_sub_u32_e32 v12, 0xcfe, v0
	v_ashrrev_i32_e32 v13, 31, v12
	v_lshl_add_u64 v[12:13], v[12:13], 2, s[52:53]
	s_waitcnt vmcnt(0)
	v_mov_b32_e32 v10, v210
	v_mov_b32_e32 v11, v211
	v_pk_mul_f32 v[10:11], v[16:17], v[10:11]
	s_nop 0
	v_add_f32_e32 v10, v14, v10
	v_add_f32_e32 v14, v10, v11
	v_sub_u32_e32 v10, 0xbfe, v0
	v_ashrrev_i32_e32 v11, 31, v10
	v_lshl_add_u64 v[10:11], v[10:11], 2, s[52:53]
	s_nop 0
	s_waitcnt vmcnt(0)
	v_mov_b32_e32 v10, v212
	v_mov_b32_e32 v11, v213
	v_pk_mul_f32 v[6:7], v[6:7], v[10:11]
	s_nop 0
	v_add_f32_e32 v6, v14, v6
	v_add_f32_e32 v12, v6, v7
	v_sub_u32_e32 v6, 0xdfe, v0
	v_sub_u32_e32 v10, 0xefe, v0
	v_ashrrev_i32_e32 v7, 31, v6
	v_ashrrev_i32_e32 v11, 31, v10
	v_lshl_add_u64 v[6:7], v[6:7], 2, s[52:53]
	v_lshl_add_u64 v[10:11], v[10:11], 2, s[52:53]
	s_nop 0
	s_waitcnt vmcnt(0)
	v_mov_b32_e32 v6, v214
	v_mov_b32_e32 v7, v215
	v_pk_mul_f32 v[6:7], v[8:9], v[6:7]
	s_nop 0
	v_add_f32_e32 v6, v12, v6
	v_add_f32_e32 v6, v6, v7

.LBB0_1143:
	v_mov_b32_e32 v7, 0
	s_and_saveexec_b64 s[58:59], s[38:39]
	s_cbranch_execz .LBB0_1145
	v_mad_i64_i32 v[8:9], s[28:29], v8, s91, 0
	v_lshl_add_u64 v[8:9], v[8:9], 2, s[0:1]
	s_mov_b64 s[28:29], 0x1000
	v_lshl_add_u64 v[36:37], v[8:9], 0, s[28:29]
	v_add_co_u32_e32 v8, vcc, 0x1000, v8
	v_sub_u32_e32 v40, -2, v0
	v_mov_b32_e32 v41, v1
	v_addc_co_u32_e32 v9, vcc, 0, v9, vcc
	v_lshl_add_u64 v[40:41], v[40:41], 2, s[52:53]
	v_sub_u32_e32 v216, -2, v0
	v_mov_b32_e32 v217, v1
	v_lshl_add_u64 v[216:217], v[216:217], 2, s[52:53]
	s_mov_b64 s[98:99], 0x1000
	global_load_dword v200, v[216:217], off
	global_load_dword v201, v[216:217], off offset:1024
	global_load_dword v202, v[216:217], off offset:2048
	global_load_dword v203, v[216:217], off offset:3072
	v_lshl_add_u64 v[216:217], v[216:217], 0, s[98:99]
	global_load_dword v204, v[216:217], off
	global_load_dword v205, v[216:217], off offset:1024
	global_load_dword v206, v[216:217], off offset:2048
	global_load_dword v207, v[216:217], off offset:3072
	v_lshl_add_u64 v[216:217], v[216:217], 0, s[98:99]
	global_load_dword v208, v[216:217], off
	global_load_dword v209, v[216:217], off offset:1024
	global_load_dword v210, v[216:217], off offset:2048
	global_load_dword v211, v[216:217], off offset:3072
	v_lshl_add_u64 v[216:217], v[216:217], 0, s[98:99]
	global_load_dword v212, v[216:217], off
	global_load_dword v213, v[216:217], off offset:1024
	global_load_dword v214, v[216:217], off offset:2048
	global_load_dword v215, v[216:217], off offset:3072
	global_load_dwordx4 v[12:15], v[8:9], off
	s_nop 0
	global_load_dwordx4 v[8:11], v[36:37], off offset:48
	global_load_dwordx4 v[16:19], v[36:37], off offset:32
	s_nop 0
	global_load_dwordx4 v[36:39], v[36:37], off offset:16
	s_nop 0
	v_sub_u32_e32 v40, 0xfe, v0
	v_ashrrev_i32_e32 v41, 31, v40
	v_lshl_add_u64 v[40:41], v[40:41], 2, s[52:53]
	s_waitcnt vmcnt(0)
	v_mov_b32_e32 v7, v200
	v_fma_f32 v7, v12, v7, 0
	s_waitcnt vmcnt(0)
	v_mov_b32_e32 v12, v201
	v_fmac_f32_e32 v7, v13, v12
	v_sub_u32_e32 v12, 0x1fe, v0
	v_ashrrev_i32_e32 v13, 31, v12
	v_lshl_add_u64 v[12:13], v[12:13], 2, s[52:53]
	s_waitcnt vmcnt(0)
	v_mov_b32_e32 v12, v202
	v_fmac_f32_e32 v7, v14, v12
	v_sub_u32_e32 v12, 0x2fe, v0
	v_ashrrev_i32_e32 v13, 31, v12
	v_lshl_add_u64 v[12:13], v[12:13], 2, s[52:53]
	v_sub_u32_e32 v14, 0x4fe, v0
	s_waitcnt vmcnt(0)
	v_mov_b32_e32 v12, v203
	v_fmac_f32_e32 v7, v15, v12
	v_sub_u32_e32 v12, 0x3fe, v0
	v_ashrrev_i32_e32 v13, 31, v12
	v_ashrrev_i32_e32 v15, 31, v14
	v_lshl_add_u64 v[12:13], v[12:13], 2, s[52:53]
	v_lshl_add_u64 v[14:15], v[14:15], 2, s[52:53]
	s_nop 0
	v_sub_u32_e32 v14, 0x6fe, v0
	v_ashrrev_i32_e32 v15, 31, v14
	v_lshl_add_u64 v[14:15], v[14:15], 2, s[52:53]
	s_waitcnt vmcnt(0)
	v_mov_b32_e32 v12, v204
	v_mov_b32_e32 v13, v205
	v_pk_mul_f32 v[12:13], v[36:37], v[12:13]
	s_nop 0
	v_add_f32_e32 v7, v7, v12
	v_sub_u32_e32 v12, 0x5fe, v0
	v_add_f32_e32 v7, v7, v13
	v_ashrrev_i32_e32 v13, 31, v12
	v_lshl_add_u64 v[12:13], v[12:13], 2, s[52:53]
	s_nop 0
	v_sub_u32_e32 v14, 0x8fe, v0
	v_ashrrev_i32_e32 v15, 31, v14
	v_lshl_add_u64 v[14:15], v[14:15], 2, s[52:53]
	s_waitcnt vmcnt(0)
	v_mov_b32_e32 v12, v206
	v_mov_b32_e32 v13, v207
	v_pk_mul_f32 v[12:13], v[38:39], v[12:13]
	s_nop 0
	v_add_f32_e32 v7, v7, v12
	v_sub_u32_e32 v12, 0x7fe, v0
	v_add_f32_e32 v7, v7, v13
	v_ashrrev_i32_e32 v13, 31, v12
	v_lshl_add_u64 v[12:13], v[12:13], 2, s[52:53]
	s_nop 0
	v_sub_u32_e32 v14, 0xafe, v0
	v_ashrrev_i32_e32 v15, 31, v14
	v_lshl_add_u64 v[14:15], v[14:15], 2, s[52:53]
	s_waitcnt vmcnt(0)
	v_mov_b32_e32 v12, v208
	v_mov_b32_e32 v13, v209
	v_pk_mul_f32 v[12:13], v[16:17], v[12:13]
	s_nop 0
	v_add_f32_e32 v7, v7, v12
	v_sub_u32_e32 v12, 0x9fe, v0
	v_add_f32_e32 v7, v7, v13
	v_ashrrev_i32_e32 v13, 31, v12
	v_lshl_add_u64 v[12:13], v[12:13], 2, s[52:53]
	s_nop 0
	v_sub_u32_e32 v14, 0xcfe, v0
	v_ashrrev_i32_e32 v15, 31, v14
	v_lshl_add_u64 v[14:15], v[14:15], 2, s[52:53]
	s_waitcnt vmcnt(0)
	v_mov_b32_e32 v12, v210
	v_mov_b32_e32 v13, v211
	v_pk_mul_f32 v[12:13], v[18:19], v[12:13]
	s_nop 0
	v_add_f32_e32 v7, v7, v12
	v_sub_u32_e32 v12, 0xbfe, v0
	v_add_f32_e32 v7, v7, v13
	v_ashrrev_i32_e32 v13, 31, v12
	v_lshl_add_u64 v[12:13], v[12:13], 2, s[52:53]
	s_nop 0
	s_waitcnt vmcnt(0)
	v_mov_b32_e32 v12, v212
	v_mov_b32_e32 v13, v213
	v_pk_mul_f32 v[8:9], v[8:9], v[12:13]
	s_nop 0
	v_add_f32_e32 v7, v7, v8
	v_sub_u32_e32 v8, 0xdfe, v0
	v_sub_u32_e32 v12, 0xefe, v0
	v_add_f32_e32 v7, v7, v9
	v_ashrrev_i32_e32 v9, 31, v8
	v_ashrrev_i32_e32 v13, 31, v12
	v_lshl_add_u64 v[8:9], v[8:9], 2, s[52:53]
	v_lshl_add_u64 v[12:13], v[12:13], 2, s[52:53]
	s_nop 0
	s_waitcnt vmcnt(0)
	v_mov_b32_e32 v8, v214
	v_mov_b32_e32 v9, v215
	v_pk_mul_f32 v[8:9], v[10:11], v[8:9]
	s_nop 0
	v_add_f32_e32 v7, v7, v8
	v_add_f32_e32 v7, v7, v9

.LBB0_1147:
	v_mov_b32_e32 v8, 0
	s_and_saveexec_b64 s[58:59], s[38:39]
	s_cbranch_execz .LBB0_1149
	v_mad_i64_i32 v[8:9], s[28:29], v9, s91, 0
	v_lshl_add_u64 v[8:9], v[8:9], 2, s[0:1]
	s_mov_b64 s[28:29], 0x1000
	v_lshl_add_u64 v[36:37], v[8:9], 0, s[28:29]
	v_add_co_u32_e32 v8, vcc, 0x1000, v8
	v_sub_u32_e32 v40, -2, v0
	v_mov_b32_e32 v41, v1
	v_addc_co_u32_e32 v9, vcc, 0, v9, vcc
	v_lshl_add_u64 v[40:41], v[40:41], 2, s[52:53]
	v_sub_u32_e32 v216, -2, v0
	v_mov_b32_e32 v217, v1
	v_lshl_add_u64 v[216:217], v[216:217], 2, s[52:53]
	s_mov_b64 s[98:99], 0x1000
	global_load_dword v200, v[216:217], off
	global_load_dword v201, v[216:217], off offset:1024
	global_load_dword v202, v[216:217], off offset:2048
	global_load_dword v203, v[216:217], off offset:3072
	v_lshl_add_u64 v[216:217], v[216:217], 0, s[98:99]
	global_load_dword v204, v[216:217], off
	global_load_dword v205, v[216:217], off offset:1024
	global_load_dword v206, v[216:217], off offset:2048
	global_load_dword v207, v[216:217], off offset:3072
	v_lshl_add_u64 v[216:217], v[216:217], 0, s[98:99]
	global_load_dword v208, v[216:217], off
	global_load_dword v209, v[216:217], off offset:1024
	global_load_dword v210, v[216:217], off offset:2048
	global_load_dword v211, v[216:217], off offset:3072
	v_lshl_add_u64 v[216:217], v[216:217], 0, s[98:99]
	global_load_dword v212, v[216:217], off
	global_load_dword v213, v[216:217], off offset:1024
	global_load_dword v214, v[216:217], off offset:2048
	global_load_dword v215, v[216:217], off offset:3072
	global_load_dwordx4 v[12:15], v[8:9], off
	s_nop 0
	global_load_dwordx4 v[8:11], v[36:37], off offset:48
	global_load_dwordx4 v[16:19], v[36:37], off offset:32
	s_nop 0
	global_load_dwordx4 v[36:39], v[36:37], off offset:16
	s_nop 0
	v_sub_u32_e32 v40, 0xfe, v0
	v_ashrrev_i32_e32 v41, 31, v40
	v_lshl_add_u64 v[40:41], v[40:41], 2, s[52:53]
	s_waitcnt vmcnt(0)
	v_mov_b32_e32 v35, v200
	v_fma_f32 v35, v12, v35, 0
	s_waitcnt vmcnt(0)
	v_mov_b32_e32 v12, v201
	v_fmac_f32_e32 v35, v13, v12
	v_sub_u32_e32 v12, 0x1fe, v0
	v_ashrrev_i32_e32 v13, 31, v12
	v_lshl_add_u64 v[12:13], v[12:13], 2, s[52:53]
	s_waitcnt vmcnt(0)
	v_mov_b32_e32 v12, v202
	v_fmac_f32_e32 v35, v14, v12
	v_sub_u32_e32 v12, 0x2fe, v0
	v_ashrrev_i32_e32 v13, 31, v12
	v_lshl_add_u64 v[12:13], v[12:13], 2, s[52:53]
	v_sub_u32_e32 v14, 0x4fe, v0
	s_waitcnt vmcnt(0)
	v_mov_b32_e32 v12, v203
	v_fmac_f32_e32 v35, v15, v12
	v_sub_u32_e32 v12, 0x3fe, v0
	v_ashrrev_i32_e32 v13, 31, v12
	v_ashrrev_i32_e32 v15, 31, v14
	v_lshl_add_u64 v[12:13], v[12:13], 2, s[52:53]
	v_lshl_add_u64 v[14:15], v[14:15], 2, s[52:53]
	s_nop 0
	v_sub_u32_e32 v14, 0x6fe, v0
	v_ashrrev_i32_e32 v15, 31, v14
	v_lshl_add_u64 v[14:15], v[14:15], 2, s[52:53]
	s_waitcnt vmcnt(0)
	v_mov_b32_e32 v12, v204
	v_mov_b32_e32 v13, v205
	v_pk_mul_f32 v[12:13], v[36:37], v[12:13]
	s_nop 0
	v_add_f32_e32 v12, v35, v12
	v_add_f32_e32 v35, v12, v13
	v_sub_u32_e32 v12, 0x5fe, v0
	v_ashrrev_i32_e32 v13, 31, v12
	v_lshl_add_u64 v[12:13], v[12:13], 2, s[52:53]
	s_nop 0
	v_sub_u32_e32 v14, 0x8fe, v0
	v_ashrrev_i32_e32 v15, 31, v14
	v_lshl_add_u64 v[14:15], v[14:15], 2, s[52:53]
	s_waitcnt vmcnt(0)
	v_mov_b32_e32 v12, v206
	v_mov_b32_e32 v13, v207
	v_pk_mul_f32 v[12:13], v[38:39], v[12:13]
	s_nop 0
	v_add_f32_e32 v12, v35, v12
	v_add_f32_e32 v35, v12, v13
	v_sub_u32_e32 v12, 0x7fe, v0
	v_ashrrev_i32_e32 v13, 31, v12
	v_lshl_add_u64 v[12:13], v[12:13], 2, s[52:53]
	s_nop 0
	v_sub_u32_e32 v14, 0xafe, v0
	v_ashrrev_i32_e32 v15, 31, v14
	v_lshl_add_u64 v[14:15], v[14:15], 2, s[52:53]
	s_waitcnt vmcnt(0)
	v_mov_b32_e32 v12, v208
	v_mov_b32_e32 v13, v209
	v_pk_mul_f32 v[12:13], v[16:17], v[12:13]
	s_nop 0
	v_add_f32_e32 v12, v35, v12
	v_add_f32_e32 v16, v12, v13
	v_sub_u32_e32 v12, 0x9fe, v0
	v_ashrrev_i32_e32 v13, 31, v12
	v_lshl_add_u64 v[12:13], v[12:13], 2, s[52:53]
	s_nop 0
	v_sub_u32_e32 v14, 0xcfe, v0
	v_ashrrev_i32_e32 v15, 31, v14
	v_lshl_add_u64 v[14:15], v[14:15], 2, s[52:53]
	s_waitcnt vmcnt(0)
	v_mov_b32_e32 v12, v210
	v_mov_b32_e32 v13, v211
	v_pk_mul_f32 v[12:13], v[18:19], v[12:13]
	s_nop 0
	v_add_f32_e32 v12, v16, v12
	v_add_f32_e32 v16, v12, v13
	v_sub_u32_e32 v12, 0xbfe, v0
	v_ashrrev_i32_e32 v13, 31, v12
	v_lshl_add_u64 v[12:13], v[12:13], 2, s[52:53]
	s_nop 0
	s_waitcnt vmcnt(0)
	v_mov_b32_e32 v12, v212
	v_mov_b32_e32 v13, v213
	v_pk_mul_f32 v[8:9], v[8:9], v[12:13]
	s_nop 0
	v_add_f32_e32 v8, v16, v8
	v_add_f32_e32 v14, v8, v9
	v_sub_u32_e32 v8, 0xdfe, v0
	v_sub_u32_e32 v12, 0xefe, v0
	v_ashrrev_i32_e32 v9, 31, v8
	v_ashrrev_i32_e32 v13, 31, v12
	v_lshl_add_u64 v[8:9], v[8:9], 2, s[52:53]
	v_lshl_add_u64 v[12:13], v[12:13], 2, s[52:53]
	s_nop 0
	s_waitcnt vmcnt(0)
	v_mov_b32_e32 v8, v214
	v_mov_b32_e32 v9, v215
	v_pk_mul_f32 v[8:9], v[10:11], v[8:9]
	s_nop 0
	v_add_f32_e32 v8, v14, v8
	v_add_f32_e32 v8, v8, v9

.LBB0_1151:
	v_mov_b32_e32 v9, 0
	s_and_saveexec_b64 s[58:59], s[38:39]
	s_cbranch_execz .LBB0_1153
	v_mad_i64_i32 v[10:11], s[28:29], v10, s91, 0
	v_lshl_add_u64 v[10:11], v[10:11], 2, s[0:1]
	s_mov_b64 s[28:29], 0x1000
	v_lshl_add_u64 v[18:19], v[10:11], 0, s[28:29]
	v_add_co_u32_e32 v10, vcc, 0x1000, v10
	s_nop 1
	v_addc_co_u32_e32 v11, vcc, 0, v11, vcc
	v_sub_u32_e32 v216, -2, v0
	v_mov_b32_e32 v217, v1
	v_lshl_add_u64 v[216:217], v[216:217], 2, s[52:53]
	s_mov_b64 s[98:99], 0x1000
	global_load_dword v200, v[216:217], off
	global_load_dword v201, v[216:217], off offset:1024
	global_load_dword v202, v[216:217], off offset:2048
	global_load_dword v203, v[216:217], off offset:3072
	v_lshl_add_u64 v[216:217], v[216:217], 0, s[98:99]
	global_load_dword v204, v[216:217], off
	global_load_dword v205, v[216:217], off offset:1024
	global_load_dword v206, v[216:217], off offset:2048
	global_load_dword v207, v[216:217], off offset:3072
	v_lshl_add_u64 v[216:217], v[216:217], 0, s[98:99]
	global_load_dword v208, v[216:217], off
	global_load_dword v209, v[216:217], off offset:1024
	global_load_dword v210, v[216:217], off offset:2048
	global_load_dword v211, v[216:217], off offset:3072
	v_lshl_add_u64 v[216:217], v[216:217], 0, s[98:99]
	global_load_dword v212, v[216:217], off
	global_load_dword v213, v[216:217], off offset:1024
	global_load_dword v214, v[216:217], off offset:2048
	global_load_dword v215, v[216:217], off offset:3072
	global_load_dwordx4 v[14:17], v[10:11], off
	s_nop 0
	global_load_dwordx4 v[10:13], v[18:19], off offset:48
	global_load_dwordx4 v[36:39], v[18:19], off offset:32
	global_load_dwordx4 v[40:43], v[18:19], off offset:16
	v_sub_u32_e32 v18, -2, v0
	v_mov_b32_e32 v19, v1
	v_lshl_add_u64 v[18:19], v[18:19], 2, s[52:53]
	v_sub_u32_e32 v18, 0xfe, v0
	v_ashrrev_i32_e32 v19, 31, v18
	v_lshl_add_u64 v[18:19], v[18:19], 2, s[52:53]
	s_waitcnt vmcnt(0)
	v_mov_b32_e32 v9, v200
	v_fma_f32 v9, v14, v9, 0
	s_waitcnt vmcnt(0)
	v_mov_b32_e32 v14, v201
	v_fmac_f32_e32 v9, v15, v14
	v_sub_u32_e32 v14, 0x1fe, v0
	v_ashrrev_i32_e32 v15, 31, v14
	v_lshl_add_u64 v[14:15], v[14:15], 2, s[52:53]
	s_waitcnt vmcnt(0)
	v_mov_b32_e32 v14, v202
	v_fmac_f32_e32 v9, v16, v14
	v_sub_u32_e32 v14, 0x2fe, v0
	v_ashrrev_i32_e32 v15, 31, v14
	v_lshl_add_u64 v[14:15], v[14:15], 2, s[52:53]
	v_sub_u32_e32 v16, 0x4fe, v0
	s_waitcnt vmcnt(0)
	v_mov_b32_e32 v14, v203
	v_fmac_f32_e32 v9, v17, v14
	v_sub_u32_e32 v14, 0x3fe, v0
	v_ashrrev_i32_e32 v15, 31, v14
	v_ashrrev_i32_e32 v17, 31, v16
	v_lshl_add_u64 v[14:15], v[14:15], 2, s[52:53]
	v_lshl_add_u64 v[16:17], v[16:17], 2, s[52:53]
	s_nop 0
	v_sub_u32_e32 v16, 0x6fe, v0
	v_ashrrev_i32_e32 v17, 31, v16
	v_lshl_add_u64 v[16:17], v[16:17], 2, s[52:53]
	s_waitcnt vmcnt(0)
	v_mov_b32_e32 v14, v204
	v_mov_b32_e32 v15, v205
	v_pk_mul_f32 v[14:15], v[40:41], v[14:15]
	s_nop 0
	v_add_f32_e32 v9, v9, v14
	v_sub_u32_e32 v14, 0x5fe, v0
	v_add_f32_e32 v9, v9, v15
	v_ashrrev_i32_e32 v15, 31, v14
	v_lshl_add_u64 v[14:15], v[14:15], 2, s[52:53]
	s_nop 0
	v_sub_u32_e32 v16, 0x8fe, v0
	v_ashrrev_i32_e32 v17, 31, v16
	v_lshl_add_u64 v[16:17], v[16:17], 2, s[52:53]
	s_waitcnt vmcnt(0)
	v_mov_b32_e32 v14, v206
	v_mov_b32_e32 v15, v207
	v_pk_mul_f32 v[14:15], v[42:43], v[14:15]
	s_nop 0
	v_add_f32_e32 v9, v9, v14
	v_sub_u32_e32 v14, 0x7fe, v0
	v_add_f32_e32 v9, v9, v15
	v_ashrrev_i32_e32 v15, 31, v14
	v_lshl_add_u64 v[14:15], v[14:15], 2, s[52:53]
	s_nop 0
	v_sub_u32_e32 v16, 0xafe, v0
	v_ashrrev_i32_e32 v17, 31, v16
	v_lshl_add_u64 v[16:17], v[16:17], 2, s[52:53]
	s_waitcnt vmcnt(0)
	v_mov_b32_e32 v14, v208
	v_mov_b32_e32 v15, v209
	v_pk_mul_f32 v[14:15], v[36:37], v[14:15]
	s_nop 0
	v_add_f32_e32 v9, v9, v14
	v_sub_u32_e32 v14, 0x9fe, v0
	v_add_f32_e32 v9, v9, v15
	v_ashrrev_i32_e32 v15, 31, v14
	v_lshl_add_u64 v[14:15], v[14:15], 2, s[52:53]
	s_nop 0
	v_sub_u32_e32 v16, 0xcfe, v0
	v_ashrrev_i32_e32 v17, 31, v16
	v_lshl_add_u64 v[16:17], v[16:17], 2, s[52:53]
	s_waitcnt vmcnt(0)
	v_mov_b32_e32 v14, v210
	v_mov_b32_e32 v15, v211
	v_pk_mul_f32 v[14:15], v[38:39], v[14:15]
	s_nop 0
	v_add_f32_e32 v9, v9, v14
	v_sub_u32_e32 v14, 0xbfe, v0
	v_add_f32_e32 v9, v9, v15
	v_ashrrev_i32_e32 v15, 31, v14
	v_lshl_add_u64 v[14:15], v[14:15], 2, s[52:53]
	s_nop 0
	s_waitcnt vmcnt(0)
	v_mov_b32_e32 v14, v212
	v_mov_b32_e32 v15, v213
	v_pk_mul_f32 v[10:11], v[10:11], v[14:15]
	s_nop 0
	v_add_f32_e32 v9, v9, v10
	v_sub_u32_e32 v10, 0xdfe, v0
	v_sub_u32_e32 v14, 0xefe, v0
	v_add_f32_e32 v9, v9, v11
	v_ashrrev_i32_e32 v11, 31, v10
	v_ashrrev_i32_e32 v15, 31, v14
	v_lshl_add_u64 v[10:11], v[10:11], 2, s[52:53]
	v_lshl_add_u64 v[14:15], v[14:15], 2, s[52:53]
	s_nop 0
	s_waitcnt vmcnt(0)
	v_mov_b32_e32 v10, v214
	v_mov_b32_e32 v11, v215
	v_pk_mul_f32 v[10:11], v[12:13], v[10:11]
	s_nop 0
	v_add_f32_e32 v9, v9, v10
	v_add_f32_e32 v9, v9, v11

.LBB0_1155:
	v_mov_b32_e32 v10, 0
	s_and_saveexec_b64 s[58:59], s[38:39]
	s_cbranch_execz .LBB0_1157
	v_mad_i64_i32 v[10:11], s[28:29], v11, s91, 0
	v_lshl_add_u64 v[10:11], v[10:11], 2, s[0:1]
	s_mov_b64 s[28:29], 0x1000
	v_lshl_add_u64 v[18:19], v[10:11], 0, s[28:29]
	v_add_co_u32_e32 v10, vcc, 0x1000, v10
	s_nop 1
	v_addc_co_u32_e32 v11, vcc, 0, v11, vcc
	v_sub_u32_e32 v216, -2, v0
	v_mov_b32_e32 v217, v1
	v_lshl_add_u64 v[216:217], v[216:217], 2, s[52:53]
	s_mov_b64 s[98:99], 0x1000
	global_load_dword v200, v[216:217], off
	global_load_dword v201, v[216:217], off offset:1024
	global_load_dword v202, v[216:217], off offset:2048
	global_load_dword v203, v[216:217], off offset:3072
	v_lshl_add_u64 v[216:217], v[216:217], 0, s[98:99]
	global_load_dword v204, v[216:217], off
	global_load_dword v205, v[216:217], off offset:1024
	global_load_dword v206, v[216:217], off offset:2048
	global_load_dword v207, v[216:217], off offset:3072
	v_lshl_add_u64 v[216:217], v[216:217], 0, s[98:99]
	global_load_dword v208, v[216:217], off
	global_load_dword v209, v[216:217], off offset:1024
	global_load_dword v210, v[216:217], off offset:2048
	global_load_dword v211, v[216:217], off offset:3072
	v_lshl_add_u64 v[216:217], v[216:217], 0, s[98:99]
	global_load_dword v212, v[216:217], off
	global_load_dword v213, v[216:217], off offset:1024
	global_load_dword v214, v[216:217], off offset:2048
	global_load_dword v215, v[216:217], off offset:3072
	global_load_dwordx4 v[14:17], v[10:11], off
	s_nop 0
	global_load_dwordx4 v[10:13], v[18:19], off offset:48
	global_load_dwordx4 v[36:39], v[18:19], off offset:32
	global_load_dwordx4 v[40:43], v[18:19], off offset:16
	v_sub_u32_e32 v18, -2, v0
	v_mov_b32_e32 v19, v1
	v_lshl_add_u64 v[18:19], v[18:19], 2, s[52:53]
	s_waitcnt vmcnt(0)
	v_mov_b32_e32 v18, v200
	v_fma_f32 v35, v14, v18, 0
	v_sub_u32_e32 v18, 0xfe, v0
	v_ashrrev_i32_e32 v19, 31, v18
	v_lshl_add_u64 v[18:19], v[18:19], 2, s[52:53]
	s_waitcnt vmcnt(0)
	v_mov_b32_e32 v14, v201
	v_fmac_f32_e32 v35, v15, v14
	v_sub_u32_e32 v14, 0x1fe, v0
	v_ashrrev_i32_e32 v15, 31, v14
	v_lshl_add_u64 v[14:15], v[14:15], 2, s[52:53]
	s_waitcnt vmcnt(0)
	v_mov_b32_e32 v14, v202
	v_fmac_f32_e32 v35, v16, v14
	v_sub_u32_e32 v14, 0x2fe, v0
	v_ashrrev_i32_e32 v15, 31, v14
	v_lshl_add_u64 v[14:15], v[14:15], 2, s[52:53]
	v_sub_u32_e32 v16, 0x4fe, v0
	s_waitcnt vmcnt(0)
	v_mov_b32_e32 v14, v203
	v_fmac_f32_e32 v35, v17, v14
	v_sub_u32_e32 v14, 0x3fe, v0
	v_ashrrev_i32_e32 v15, 31, v14
	v_ashrrev_i32_e32 v17, 31, v16
	v_lshl_add_u64 v[14:15], v[14:15], 2, s[52:53]
	v_lshl_add_u64 v[16:17], v[16:17], 2, s[52:53]
	s_nop 0
	v_sub_u32_e32 v16, 0x6fe, v0
	v_ashrrev_i32_e32 v17, 31, v16
	v_lshl_add_u64 v[16:17], v[16:17], 2, s[52:53]
	s_waitcnt vmcnt(0)
	v_mov_b32_e32 v14, v204
	v_mov_b32_e32 v15, v205
	v_pk_mul_f32 v[14:15], v[40:41], v[14:15]
	s_nop 0
	v_add_f32_e32 v14, v35, v14
	v_add_f32_e32 v18, v14, v15
	v_sub_u32_e32 v14, 0x5fe, v0
	v_ashrrev_i32_e32 v15, 31, v14
	v_lshl_add_u64 v[14:15], v[14:15], 2, s[52:53]
	s_nop 0
	v_sub_u32_e32 v16, 0x8fe, v0
	v_ashrrev_i32_e32 v17, 31, v16
	v_lshl_add_u64 v[16:17], v[16:17], 2, s[52:53]
	s_waitcnt vmcnt(0)
	v_mov_b32_e32 v14, v206
	v_mov_b32_e32 v15, v207
	v_pk_mul_f32 v[14:15], v[42:43], v[14:15]
	s_nop 0
	v_add_f32_e32 v14, v18, v14
	v_add_f32_e32 v18, v14, v15
	v_sub_u32_e32 v14, 0x7fe, v0
	v_ashrrev_i32_e32 v15, 31, v14
	v_lshl_add_u64 v[14:15], v[14:15], 2, s[52:53]
	s_nop 0
	v_sub_u32_e32 v16, 0xafe, v0
	v_ashrrev_i32_e32 v17, 31, v16
	v_lshl_add_u64 v[16:17], v[16:17], 2, s[52:53]
	s_waitcnt vmcnt(0)
	v_mov_b32_e32 v14, v208
	v_mov_b32_e32 v15, v209
	v_pk_mul_f32 v[14:15], v[36:37], v[14:15]
	s_nop 0
	v_add_f32_e32 v14, v18, v14
	v_add_f32_e32 v18, v14, v15
	v_sub_u32_e32 v14, 0x9fe, v0
	v_ashrrev_i32_e32 v15, 31, v14
	v_lshl_add_u64 v[14:15], v[14:15], 2, s[52:53]
	s_nop 0
	v_sub_u32_e32 v16, 0xcfe, v0
	v_ashrrev_i32_e32 v17, 31, v16
	v_lshl_add_u64 v[16:17], v[16:17], 2, s[52:53]
	s_waitcnt vmcnt(0)
	v_mov_b32_e32 v14, v210
	v_mov_b32_e32 v15, v211
	v_pk_mul_f32 v[14:15], v[38:39], v[14:15]
	s_nop 0
	v_add_f32_e32 v14, v18, v14
	v_add_f32_e32 v18, v14, v15
	v_sub_u32_e32 v14, 0xbfe, v0
	v_ashrrev_i32_e32 v15, 31, v14
	v_lshl_add_u64 v[14:15], v[14:15], 2, s[52:53]
	s_nop 0
	s_waitcnt vmcnt(0)
	v_mov_b32_e32 v14, v212
	v_mov_b32_e32 v15, v213
	v_pk_mul_f32 v[10:11], v[10:11], v[14:15]
	s_nop 0
	v_add_f32_e32 v10, v18, v10
	v_add_f32_e32 v16, v10, v11
	v_sub_u32_e32 v10, 0xdfe, v0
	v_sub_u32_e32 v14, 0xefe, v0
	v_ashrrev_i32_e32 v11, 31, v10
	v_ashrrev_i32_e32 v15, 31, v14
	v_lshl_add_u64 v[10:11], v[10:11], 2, s[52:53]
	v_lshl_add_u64 v[14:15], v[14:15], 2, s[52:53]
	s_nop 0
	s_waitcnt vmcnt(0)
	v_mov_b32_e32 v10, v214
	v_mov_b32_e32 v11, v215
	v_pk_mul_f32 v[10:11], v[12:13], v[10:11]
	s_nop 0
	v_add_f32_e32 v10, v16, v10
	v_add_f32_e32 v10, v10, v11

.LBB0_1159:
	v_mov_b32_e32 v11, 0
	s_and_saveexec_b64 s[58:59], s[38:39]
	s_cbranch_execz .LBB0_1161
	v_mad_i64_i32 v[12:13], s[28:29], v12, s91, 0
	v_lshl_add_u64 v[12:13], v[12:13], 2, s[0:1]
	s_mov_b64 s[28:29], 0x1000
	v_lshl_add_u64 v[40:41], v[12:13], 0, s[28:29]
	v_add_co_u32_e32 v12, vcc, 0x1000, v12
	v_sub_u32_e32 v44, -2, v0
	v_mov_b32_e32 v45, v1
	v_addc_co_u32_e32 v13, vcc, 0, v13, vcc
	v_lshl_add_u64 v[44:45], v[44:45], 2, s[52:53]
	v_sub_u32_e32 v216, -2, v0
	v_mov_b32_e32 v217, v1
	v_lshl_add_u64 v[216:217], v[216:217], 2, s[52:53]
	s_mov_b64 s[98:99], 0x1000
	global_load_dword v200, v[216:217], off
	global_load_dword v201, v[216:217], off offset:1024
	global_load_dword v202, v[216:217], off offset:2048
	global_load_dword v203, v[216:217], off offset:3072
	v_lshl_add_u64 v[216:217], v[216:217], 0, s[98:99]
	global_load_dword v204, v[216:217], off
	global_load_dword v205, v[216:217], off offset:1024
	global_load_dword v206, v[216:217], off offset:2048
	global_load_dword v207, v[216:217], off offset:3072
	v_lshl_add_u64 v[216:217], v[216:217], 0, s[98:99]
	global_load_dword v208, v[216:217], off
	global_load_dword v209, v[216:217], off offset:1024
	global_load_dword v210, v[216:217], off offset:2048
	global_load_dword v211, v[216:217], off offset:3072
	v_lshl_add_u64 v[216:217], v[216:217], 0, s[98:99]
	global_load_dword v212, v[216:217], off
	global_load_dword v213, v[216:217], off offset:1024
	global_load_dword v214, v[216:217], off offset:2048
	global_load_dword v215, v[216:217], off offset:3072
	global_load_dwordx4 v[16:19], v[12:13], off
	s_nop 0
	global_load_dwordx4 v[12:15], v[40:41], off offset:48
	global_load_dwordx4 v[36:39], v[40:41], off offset:32
	s_nop 0
	global_load_dwordx4 v[40:43], v[40:41], off offset:16
	s_nop 0
	v_sub_u32_e32 v44, 0xfe, v0
	v_ashrrev_i32_e32 v45, 31, v44
	v_lshl_add_u64 v[44:45], v[44:45], 2, s[52:53]
	s_waitcnt vmcnt(0)
	v_mov_b32_e32 v11, v200
	v_fma_f32 v11, v16, v11, 0
	s_waitcnt vmcnt(0)
	v_mov_b32_e32 v16, v201
	v_fmac_f32_e32 v11, v17, v16
	v_sub_u32_e32 v16, 0x1fe, v0
	v_ashrrev_i32_e32 v17, 31, v16
	v_lshl_add_u64 v[16:17], v[16:17], 2, s[52:53]
	s_waitcnt vmcnt(0)
	v_mov_b32_e32 v16, v202
	v_fmac_f32_e32 v11, v18, v16
	v_sub_u32_e32 v16, 0x2fe, v0
	v_ashrrev_i32_e32 v17, 31, v16
	v_lshl_add_u64 v[16:17], v[16:17], 2, s[52:53]
	v_sub_u32_e32 v18, 0x4fe, v0
	s_waitcnt vmcnt(0)
	v_mov_b32_e32 v16, v203
	v_fmac_f32_e32 v11, v19, v16
	v_sub_u32_e32 v16, 0x3fe, v0
	v_ashrrev_i32_e32 v17, 31, v16
	v_ashrrev_i32_e32 v19, 31, v18
	v_lshl_add_u64 v[16:17], v[16:17], 2, s[52:53]
	v_lshl_add_u64 v[18:19], v[18:19], 2, s[52:53]
	s_nop 0
	v_sub_u32_e32 v18, 0x6fe, v0
	v_ashrrev_i32_e32 v19, 31, v18
	v_lshl_add_u64 v[18:19], v[18:19], 2, s[52:53]
	s_waitcnt vmcnt(0)
	v_mov_b32_e32 v16, v204
	v_mov_b32_e32 v17, v205
	v_pk_mul_f32 v[16:17], v[40:41], v[16:17]
	s_nop 0
	v_add_f32_e32 v11, v11, v16
	v_sub_u32_e32 v16, 0x5fe, v0
	v_add_f32_e32 v11, v11, v17
	v_ashrrev_i32_e32 v17, 31, v16
	v_lshl_add_u64 v[16:17], v[16:17], 2, s[52:53]
	s_nop 0
	v_sub_u32_e32 v18, 0x8fe, v0
	v_ashrrev_i32_e32 v19, 31, v18
	v_lshl_add_u64 v[18:19], v[18:19], 2, s[52:53]
	s_waitcnt vmcnt(0)
	v_mov_b32_e32 v16, v206
	v_mov_b32_e32 v17, v207
	v_pk_mul_f32 v[16:17], v[42:43], v[16:17]
	s_nop 0
	v_add_f32_e32 v11, v11, v16
	v_sub_u32_e32 v16, 0x7fe, v0
	v_add_f32_e32 v11, v11, v17
	v_ashrrev_i32_e32 v17, 31, v16
	v_lshl_add_u64 v[16:17], v[16:17], 2, s[52:53]
	s_nop 0
	v_sub_u32_e32 v18, 0xafe, v0
	v_ashrrev_i32_e32 v19, 31, v18
	v_lshl_add_u64 v[18:19], v[18:19], 2, s[52:53]
	s_waitcnt vmcnt(0)
	v_mov_b32_e32 v16, v208
	v_mov_b32_e32 v17, v209
	v_pk_mul_f32 v[16:17], v[36:37], v[16:17]
	s_nop 0
	v_add_f32_e32 v11, v11, v16
	v_sub_u32_e32 v16, 0x9fe, v0
	v_add_f32_e32 v11, v11, v17
	v_ashrrev_i32_e32 v17, 31, v16
	v_lshl_add_u64 v[16:17], v[16:17], 2, s[52:53]
	s_nop 0
	v_sub_u32_e32 v18, 0xcfe, v0
	v_ashrrev_i32_e32 v19, 31, v18
	v_lshl_add_u64 v[18:19], v[18:19], 2, s[52:53]
	s_waitcnt vmcnt(0)
	v_mov_b32_e32 v16, v210
	v_mov_b32_e32 v17, v211
	v_pk_mul_f32 v[16:17], v[38:39], v[16:17]
	s_nop 0
	v_add_f32_e32 v11, v11, v16
	v_sub_u32_e32 v16, 0xbfe, v0
	v_add_f32_e32 v11, v11, v17
	v_ashrrev_i32_e32 v17, 31, v16
	v_lshl_add_u64 v[16:17], v[16:17], 2, s[52:53]
	s_nop 0
	s_waitcnt vmcnt(0)
	v_mov_b32_e32 v16, v212
	v_mov_b32_e32 v17, v213
	v_pk_mul_f32 v[12:13], v[12:13], v[16:17]
	s_nop 0
	v_add_f32_e32 v11, v11, v12
	v_sub_u32_e32 v12, 0xdfe, v0
	v_sub_u32_e32 v16, 0xefe, v0
	v_add_f32_e32 v11, v11, v13
	v_ashrrev_i32_e32 v13, 31, v12
	v_ashrrev_i32_e32 v17, 31, v16
	v_lshl_add_u64 v[12:13], v[12:13], 2, s[52:53]
	v_lshl_add_u64 v[16:17], v[16:17], 2, s[52:53]
	s_nop 0
	s_waitcnt vmcnt(0)
	v_mov_b32_e32 v12, v214
	v_mov_b32_e32 v13, v215
	v_pk_mul_f32 v[12:13], v[14:15], v[12:13]
	s_nop 0
	v_add_f32_e32 v11, v11, v12
	v_add_f32_e32 v11, v11, v13

.LBB0_1163:
	v_mov_b32_e32 v12, 0
	s_and_saveexec_b64 s[58:59], s[38:39]
	s_cbranch_execz .LBB0_1165
	v_mad_i64_i32 v[12:13], s[28:29], v13, s91, 0
	v_lshl_add_u64 v[12:13], v[12:13], 2, s[0:1]
	s_mov_b64 s[28:29], 0x1000
	v_lshl_add_u64 v[40:41], v[12:13], 0, s[28:29]
	v_add_co_u32_e32 v12, vcc, 0x1000, v12
	v_sub_u32_e32 v44, -2, v0
	v_mov_b32_e32 v45, v1
	v_addc_co_u32_e32 v13, vcc, 0, v13, vcc
	v_lshl_add_u64 v[44:45], v[44:45], 2, s[52:53]
	v_sub_u32_e32 v216, -2, v0
	v_mov_b32_e32 v217, v1
	v_lshl_add_u64 v[216:217], v[216:217], 2, s[52:53]
	s_mov_b64 s[98:99], 0x1000
	global_load_dword v200, v[216:217], off
	global_load_dword v201, v[216:217], off offset:1024
	global_load_dword v202, v[216:217], off offset:2048
	global_load_dword v203, v[216:217], off offset:3072
	v_lshl_add_u64 v[216:217], v[216:217], 0, s[98:99]
	global_load_dword v204, v[216:217], off
	global_load_dword v205, v[216:217], off offset:1024
	global_load_dword v206, v[216:217], off offset:2048
	global_load_dword v207, v[216:217], off offset:3072
	v_lshl_add_u64 v[216:217], v[216:217], 0, s[98:99]
	global_load_dword v208, v[216:217], off
	global_load_dword v209, v[216:217], off offset:1024
	global_load_dword v210, v[216:217], off offset:2048
	global_load_dword v211, v[216:217], off offset:3072
	v_lshl_add_u64 v[216:217], v[216:217], 0, s[98:99]
	global_load_dword v212, v[216:217], off
	global_load_dword v213, v[216:217], off offset:1024
	global_load_dword v214, v[216:217], off offset:2048
	global_load_dword v215, v[216:217], off offset:3072
	global_load_dwordx4 v[16:19], v[12:13], off
	s_nop 0
	global_load_dwordx4 v[12:15], v[40:41], off offset:48
	global_load_dwordx4 v[36:39], v[40:41], off offset:32
	s_nop 0
	global_load_dwordx4 v[40:43], v[40:41], off offset:16
	s_nop 0
	v_sub_u32_e32 v44, 0xfe, v0
	v_ashrrev_i32_e32 v45, 31, v44
	v_lshl_add_u64 v[44:45], v[44:45], 2, s[52:53]
	s_waitcnt vmcnt(0)
	v_mov_b32_e32 v35, v200
	v_fma_f32 v35, v16, v35, 0
	s_waitcnt vmcnt(0)
	v_mov_b32_e32 v16, v201
	v_fmac_f32_e32 v35, v17, v16
	v_sub_u32_e32 v16, 0x1fe, v0
	v_ashrrev_i32_e32 v17, 31, v16
	v_lshl_add_u64 v[16:17], v[16:17], 2, s[52:53]
	s_waitcnt vmcnt(0)
	v_mov_b32_e32 v16, v202
	v_fmac_f32_e32 v35, v18, v16
	v_sub_u32_e32 v16, 0x2fe, v0
	v_ashrrev_i32_e32 v17, 31, v16
	v_lshl_add_u64 v[16:17], v[16:17], 2, s[52:53]
	v_sub_u32_e32 v18, 0x4fe, v0
	s_waitcnt vmcnt(0)
	v_mov_b32_e32 v16, v203
	v_fmac_f32_e32 v35, v19, v16
	v_sub_u32_e32 v16, 0x3fe, v0
	v_ashrrev_i32_e32 v17, 31, v16
	v_ashrrev_i32_e32 v19, 31, v18
	v_lshl_add_u64 v[16:17], v[16:17], 2, s[52:53]
	v_lshl_add_u64 v[18:19], v[18:19], 2, s[52:53]
	s_nop 0
	v_sub_u32_e32 v18, 0x6fe, v0
	v_ashrrev_i32_e32 v19, 31, v18
	v_lshl_add_u64 v[18:19], v[18:19], 2, s[52:53]
	s_waitcnt vmcnt(0)
	v_mov_b32_e32 v16, v204
	v_mov_b32_e32 v17, v205
	v_pk_mul_f32 v[16:17], v[40:41], v[16:17]
	s_nop 0
	v_add_f32_e32 v16, v35, v16
	v_add_f32_e32 v35, v16, v17
	v_sub_u32_e32 v16, 0x5fe, v0
	v_ashrrev_i32_e32 v17, 31, v16
	v_lshl_add_u64 v[16:17], v[16:17], 2, s[52:53]
	s_nop 0
	v_sub_u32_e32 v18, 0x8fe, v0
	v_ashrrev_i32_e32 v19, 31, v18
	v_lshl_add_u64 v[18:19], v[18:19], 2, s[52:53]
	s_waitcnt vmcnt(0)
	v_mov_b32_e32 v16, v206
	v_mov_b32_e32 v17, v207
	v_pk_mul_f32 v[16:17], v[42:43], v[16:17]
	s_nop 0
	v_add_f32_e32 v16, v35, v16
	v_add_f32_e32 v35, v16, v17
	v_sub_u32_e32 v16, 0x7fe, v0
	v_ashrrev_i32_e32 v17, 31, v16
	v_lshl_add_u64 v[16:17], v[16:17], 2, s[52:53]
	s_nop 0
	v_sub_u32_e32 v18, 0xafe, v0
	v_ashrrev_i32_e32 v19, 31, v18
	v_lshl_add_u64 v[18:19], v[18:19], 2, s[52:53]
	s_waitcnt vmcnt(0)
	v_mov_b32_e32 v16, v208
	v_mov_b32_e32 v17, v209
	v_pk_mul_f32 v[16:17], v[36:37], v[16:17]
	s_nop 0
	v_add_f32_e32 v16, v35, v16
	v_add_f32_e32 v35, v16, v17
	v_sub_u32_e32 v16, 0x9fe, v0
	v_ashrrev_i32_e32 v17, 31, v16
	v_lshl_add_u64 v[16:17], v[16:17], 2, s[52:53]
	s_nop 0
	v_sub_u32_e32 v18, 0xcfe, v0
	v_ashrrev_i32_e32 v19, 31, v18
	v_lshl_add_u64 v[18:19], v[18:19], 2, s[52:53]
	s_waitcnt vmcnt(0)
	v_mov_b32_e32 v16, v210
	v_mov_b32_e32 v17, v211
	v_pk_mul_f32 v[16:17], v[38:39], v[16:17]
	s_nop 0
	v_add_f32_e32 v16, v35, v16
	v_add_f32_e32 v35, v16, v17
	v_sub_u32_e32 v16, 0xbfe, v0
	v_ashrrev_i32_e32 v17, 31, v16
	v_lshl_add_u64 v[16:17], v[16:17], 2, s[52:53]
	s_nop 0
	s_waitcnt vmcnt(0)
	v_mov_b32_e32 v16, v212
	v_mov_b32_e32 v17, v213
	v_pk_mul_f32 v[12:13], v[12:13], v[16:17]
	s_nop 0
	v_add_f32_e32 v12, v35, v12
	v_add_f32_e32 v18, v12, v13
	v_sub_u32_e32 v12, 0xdfe, v0
	v_sub_u32_e32 v16, 0xefe, v0
	v_ashrrev_i32_e32 v13, 31, v12
	v_ashrrev_i32_e32 v17, 31, v16
	v_lshl_add_u64 v[12:13], v[12:13], 2, s[52:53]
	v_lshl_add_u64 v[16:17], v[16:17], 2, s[52:53]
	s_nop 0
	s_waitcnt vmcnt(0)
	v_mov_b32_e32 v12, v214
	v_mov_b32_e32 v13, v215
	v_pk_mul_f32 v[12:13], v[14:15], v[12:13]
	s_nop 0
	v_add_f32_e32 v12, v18, v12
	v_add_f32_e32 v12, v12, v13

.LBB0_1167:
	v_mov_b32_e32 v13, 0
	s_and_saveexec_b64 s[58:59], s[38:39]
	s_cbranch_execz .LBB0_1169
	v_mad_i64_i32 v[14:15], s[28:29], v14, s91, 0
	v_lshl_add_u64 v[14:15], v[14:15], 2, s[0:1]
	s_mov_b64 s[28:29], 0x1000
	v_lshl_add_u64 v[18:19], v[14:15], 0, s[28:29]
	v_add_co_u32_e32 v14, vcc, 0x1000, v14
	s_nop 1
	v_addc_co_u32_e32 v15, vcc, 0, v15, vcc
	v_sub_u32_e32 v216, -2, v0
	v_mov_b32_e32 v217, v1
	v_lshl_add_u64 v[216:217], v[216:217], 2, s[52:53]
	s_mov_b64 s[98:99], 0x1000
	global_load_dword v200, v[216:217], off
	global_load_dword v201, v[216:217], off offset:1024
	global_load_dword v202, v[216:217], off offset:2048
	global_load_dword v203, v[216:217], off offset:3072
	v_lshl_add_u64 v[216:217], v[216:217], 0, s[98:99]
	global_load_dword v204, v[216:217], off
	global_load_dword v205, v[216:217], off offset:1024
	global_load_dword v206, v[216:217], off offset:2048
	global_load_dword v207, v[216:217], off offset:3072
	v_lshl_add_u64 v[216:217], v[216:217], 0, s[98:99]
	global_load_dword v208, v[216:217], off
	global_load_dword v209, v[216:217], off offset:1024
	global_load_dword v210, v[216:217], off offset:2048
	global_load_dword v211, v[216:217], off offset:3072
	v_lshl_add_u64 v[216:217], v[216:217], 0, s[98:99]
	global_load_dword v212, v[216:217], off
	global_load_dword v213, v[216:217], off offset:1024
	global_load_dword v214, v[216:217], off offset:2048
	global_load_dword v215, v[216:217], off offset:3072
	global_load_dwordx4 v[36:39], v[14:15], off
	s_nop 0
	global_load_dwordx4 v[14:17], v[18:19], off offset:48
	global_load_dwordx4 v[40:43], v[18:19], off offset:32
	global_load_dwordx4 v[44:47], v[18:19], off offset:16
	v_sub_u32_e32 v18, -2, v0
	v_mov_b32_e32 v19, v1
	v_lshl_add_u64 v[18:19], v[18:19], 2, s[52:53]
	v_sub_u32_e32 v18, 0xfe, v0
	v_ashrrev_i32_e32 v19, 31, v18
	v_lshl_add_u64 v[18:19], v[18:19], 2, s[52:53]
	s_waitcnt vmcnt(0)
	v_mov_b32_e32 v13, v200
	v_mov_b32_e32 v18, v201
	v_fma_f32 v13, v36, v13, 0
	v_sub_u32_e32 v36, 0x4fe, v0
	s_waitcnt vmcnt(0)
	v_fmac_f32_e32 v13, v37, v18
	v_sub_u32_e32 v18, 0x1fe, v0
	v_ashrrev_i32_e32 v19, 31, v18
	v_lshl_add_u64 v[18:19], v[18:19], 2, s[52:53]
	v_ashrrev_i32_e32 v37, 31, v36
	v_lshl_add_u64 v[36:37], v[36:37], 2, s[52:53]
	s_waitcnt vmcnt(0)
	v_mov_b32_e32 v18, v202
	v_fmac_f32_e32 v13, v38, v18
	v_sub_u32_e32 v18, 0x2fe, v0
	v_ashrrev_i32_e32 v19, 31, v18
	v_lshl_add_u64 v[18:19], v[18:19], 2, s[52:53]
	s_waitcnt vmcnt(0)
	v_mov_b32_e32 v18, v203
	v_fmac_f32_e32 v13, v39, v18
	v_sub_u32_e32 v18, 0x3fe, v0
	v_ashrrev_i32_e32 v19, 31, v18
	v_lshl_add_u64 v[18:19], v[18:19], 2, s[52:53]
	s_nop 0
	v_sub_u32_e32 v36, 0x6fe, v0
	v_ashrrev_i32_e32 v37, 31, v36
	v_lshl_add_u64 v[36:37], v[36:37], 2, s[52:53]
	s_waitcnt vmcnt(0)
	v_mov_b32_e32 v18, v204
	v_mov_b32_e32 v19, v205
	v_pk_mul_f32 v[18:19], v[44:45], v[18:19]
	s_nop 0
	v_add_f32_e32 v13, v13, v18
	v_sub_u32_e32 v18, 0x5fe, v0
	v_add_f32_e32 v13, v13, v19
	v_ashrrev_i32_e32 v19, 31, v18
	v_lshl_add_u64 v[18:19], v[18:19], 2, s[52:53]
	s_nop 0
	v_sub_u32_e32 v36, 0x8fe, v0
	v_ashrrev_i32_e32 v37, 31, v36
	v_lshl_add_u64 v[36:37], v[36:37], 2, s[52:53]
	s_waitcnt vmcnt(0)
	v_mov_b32_e32 v18, v206
	v_mov_b32_e32 v19, v207
	v_pk_mul_f32 v[18:19], v[46:47], v[18:19]
	s_nop 0
	v_add_f32_e32 v13, v13, v18
	v_sub_u32_e32 v18, 0x7fe, v0
	v_add_f32_e32 v13, v13, v19
	v_ashrrev_i32_e32 v19, 31, v18
	v_lshl_add_u64 v[18:19], v[18:19], 2, s[52:53]
	s_nop 0
	v_sub_u32_e32 v36, 0xafe, v0
	v_ashrrev_i32_e32 v37, 31, v36
	v_lshl_add_u64 v[36:37], v[36:37], 2, s[52:53]
	s_waitcnt vmcnt(0)
	v_mov_b32_e32 v18, v208
	v_mov_b32_e32 v19, v209
	v_pk_mul_f32 v[18:19], v[40:41], v[18:19]
	s_nop 0
	v_add_f32_e32 v13, v13, v18
	v_sub_u32_e32 v18, 0x9fe, v0
	v_add_f32_e32 v13, v13, v19
	v_ashrrev_i32_e32 v19, 31, v18
	v_lshl_add_u64 v[18:19], v[18:19], 2, s[52:53]
	s_nop 0
	v_sub_u32_e32 v36, 0xcfe, v0
	v_ashrrev_i32_e32 v37, 31, v36
	v_lshl_add_u64 v[36:37], v[36:37], 2, s[52:53]
	s_waitcnt vmcnt(0)
	v_mov_b32_e32 v18, v210
	v_mov_b32_e32 v19, v211
	v_pk_mul_f32 v[18:19], v[42:43], v[18:19]
	s_nop 0
	v_add_f32_e32 v13, v13, v18
	v_sub_u32_e32 v18, 0xbfe, v0
	v_add_f32_e32 v13, v13, v19
	v_ashrrev_i32_e32 v19, 31, v18
	v_lshl_add_u64 v[18:19], v[18:19], 2, s[52:53]
	s_nop 0
	s_waitcnt vmcnt(0)
	v_mov_b32_e32 v18, v212
	v_mov_b32_e32 v19, v213
	v_pk_mul_f32 v[14:15], v[14:15], v[18:19]
	s_nop 0
	v_add_f32_e32 v13, v13, v14
	v_sub_u32_e32 v14, 0xdfe, v0
	v_sub_u32_e32 v18, 0xefe, v0
	v_add_f32_e32 v13, v13, v15
	v_ashrrev_i32_e32 v15, 31, v14
	v_ashrrev_i32_e32 v19, 31, v18
	v_lshl_add_u64 v[14:15], v[14:15], 2, s[52:53]
	v_lshl_add_u64 v[18:19], v[18:19], 2, s[52:53]
	s_nop 0
	s_waitcnt vmcnt(0)
	v_mov_b32_e32 v14, v214
	v_mov_b32_e32 v15, v215
	v_pk_mul_f32 v[14:15], v[16:17], v[14:15]
	s_nop 0
	v_add_f32_e32 v13, v13, v14
	v_add_f32_e32 v13, v13, v15

.LBB0_1171:
	v_mov_b32_e32 v14, 0
	s_and_saveexec_b64 s[58:59], s[38:39]
	s_cbranch_execz .LBB0_1173
	v_mad_i64_i32 v[14:15], s[28:29], v15, s91, 0
	v_lshl_add_u64 v[14:15], v[14:15], 2, s[0:1]
	s_mov_b64 s[28:29], 0x1000
	v_lshl_add_u64 v[18:19], v[14:15], 0, s[28:29]
	v_add_co_u32_e32 v14, vcc, 0x1000, v14
	s_nop 1
	v_addc_co_u32_e32 v15, vcc, 0, v15, vcc
	v_sub_u32_e32 v216, -2, v0
	v_mov_b32_e32 v217, v1
	v_lshl_add_u64 v[216:217], v[216:217], 2, s[52:53]
	s_mov_b64 s[98:99], 0x1000
	global_load_dword v200, v[216:217], off
	global_load_dword v201, v[216:217], off offset:1024
	global_load_dword v202, v[216:217], off offset:2048
	global_load_dword v203, v[216:217], off offset:3072
	v_lshl_add_u64 v[216:217], v[216:217], 0, s[98:99]
	global_load_dword v204, v[216:217], off
	global_load_dword v205, v[216:217], off offset:1024
	global_load_dword v206, v[216:217], off offset:2048
	global_load_dword v207, v[216:217], off offset:3072
	v_lshl_add_u64 v[216:217], v[216:217], 0, s[98:99]
	global_load_dword v208, v[216:217], off
	global_load_dword v209, v[216:217], off offset:1024
	global_load_dword v210, v[216:217], off offset:2048
	global_load_dword v211, v[216:217], off offset:3072
	v_lshl_add_u64 v[216:217], v[216:217], 0, s[98:99]
	global_load_dword v212, v[216:217], off
	global_load_dword v213, v[216:217], off offset:1024
	global_load_dword v214, v[216:217], off offset:2048
	global_load_dword v215, v[216:217], off offset:3072
	global_load_dwordx4 v[36:39], v[14:15], off
	s_nop 0
	global_load_dwordx4 v[14:17], v[18:19], off offset:48
	global_load_dwordx4 v[40:43], v[18:19], off offset:32
	global_load_dwordx4 v[44:47], v[18:19], off offset:16
	v_sub_u32_e32 v18, -2, v0
	v_mov_b32_e32 v19, v1
	v_lshl_add_u64 v[18:19], v[18:19], 2, s[52:53]
	s_waitcnt vmcnt(0)
	v_mov_b32_e32 v18, v200
	v_fma_f32 v35, v36, v18, 0
	v_sub_u32_e32 v18, 0xfe, v0
	v_ashrrev_i32_e32 v19, 31, v18
	v_lshl_add_u64 v[18:19], v[18:19], 2, s[52:53]
	v_sub_u32_e32 v36, 0x4fe, v0
	s_waitcnt vmcnt(0)
	v_mov_b32_e32 v18, v201
	v_fmac_f32_e32 v35, v37, v18
	v_sub_u32_e32 v18, 0x1fe, v0
	v_ashrrev_i32_e32 v19, 31, v18
	v_lshl_add_u64 v[18:19], v[18:19], 2, s[52:53]
	v_ashrrev_i32_e32 v37, 31, v36
	v_lshl_add_u64 v[36:37], v[36:37], 2, s[52:53]
	s_waitcnt vmcnt(0)
	v_mov_b32_e32 v18, v202
	v_fmac_f32_e32 v35, v38, v18
	v_sub_u32_e32 v18, 0x2fe, v0
	v_ashrrev_i32_e32 v19, 31, v18
	v_lshl_add_u64 v[18:19], v[18:19], 2, s[52:53]
	s_waitcnt vmcnt(0)
	v_mov_b32_e32 v18, v203
	v_fmac_f32_e32 v35, v39, v18
	v_sub_u32_e32 v18, 0x3fe, v0
	v_ashrrev_i32_e32 v19, 31, v18
	v_lshl_add_u64 v[18:19], v[18:19], 2, s[52:53]
	s_nop 0
	v_sub_u32_e32 v36, 0x6fe, v0
	v_ashrrev_i32_e32 v37, 31, v36
	v_lshl_add_u64 v[36:37], v[36:37], 2, s[52:53]
	s_waitcnt vmcnt(0)
	v_mov_b32_e32 v18, v204
	v_mov_b32_e32 v19, v205
	v_pk_mul_f32 v[18:19], v[44:45], v[18:19]
	s_nop 0
	v_add_f32_e32 v18, v35, v18
	v_add_f32_e32 v35, v18, v19
	v_sub_u32_e32 v18, 0x5fe, v0
	v_ashrrev_i32_e32 v19, 31, v18
	v_lshl_add_u64 v[18:19], v[18:19], 2, s[52:53]
	s_nop 0
	v_sub_u32_e32 v36, 0x8fe, v0
	v_ashrrev_i32_e32 v37, 31, v36
	v_lshl_add_u64 v[36:37], v[36:37], 2, s[52:53]
	s_waitcnt vmcnt(0)
	v_mov_b32_e32 v18, v206
	v_mov_b32_e32 v19, v207
	v_pk_mul_f32 v[18:19], v[46:47], v[18:19]
	s_nop 0
	v_add_f32_e32 v18, v35, v18
	v_add_f32_e32 v35, v18, v19
	v_sub_u32_e32 v18, 0x7fe, v0
	v_ashrrev_i32_e32 v19, 31, v18
	v_lshl_add_u64 v[18:19], v[18:19], 2, s[52:53]
	s_nop 0
	v_sub_u32_e32 v36, 0xafe, v0
	v_ashrrev_i32_e32 v37, 31, v36
	v_lshl_add_u64 v[36:37], v[36:37], 2, s[52:53]
	s_waitcnt vmcnt(0)
	v_mov_b32_e32 v18, v208
	v_mov_b32_e32 v19, v209
	v_pk_mul_f32 v[18:19], v[40:41], v[18:19]
	s_nop 0
	v_add_f32_e32 v18, v35, v18
	v_add_f32_e32 v35, v18, v19
	v_sub_u32_e32 v18, 0x9fe, v0
	v_ashrrev_i32_e32 v19, 31, v18
	v_lshl_add_u64 v[18:19], v[18:19], 2, s[52:53]
	s_nop 0
	v_sub_u32_e32 v36, 0xcfe, v0
	v_ashrrev_i32_e32 v37, 31, v36
	v_lshl_add_u64 v[36:37], v[36:37], 2, s[52:53]
	s_waitcnt vmcnt(0)
	v_mov_b32_e32 v18, v210
	v_mov_b32_e32 v19, v211
	v_pk_mul_f32 v[18:19], v[42:43], v[18:19]
	s_nop 0
	v_add_f32_e32 v18, v35, v18
	v_add_f32_e32 v35, v18, v19
	v_sub_u32_e32 v18, 0xbfe, v0
	v_ashrrev_i32_e32 v19, 31, v18
	v_lshl_add_u64 v[18:19], v[18:19], 2, s[52:53]
	s_nop 0
	s_waitcnt vmcnt(0)
	v_mov_b32_e32 v18, v212
	v_mov_b32_e32 v19, v213
	v_pk_mul_f32 v[14:15], v[14:15], v[18:19]
	s_nop 0
	v_add_f32_e32 v14, v35, v14
	v_add_f32_e32 v35, v14, v15
	v_sub_u32_e32 v14, 0xdfe, v0
	v_sub_u32_e32 v18, 0xefe, v0
	v_ashrrev_i32_e32 v15, 31, v14
	v_ashrrev_i32_e32 v19, 31, v18
	v_lshl_add_u64 v[14:15], v[14:15], 2, s[52:53]
	v_lshl_add_u64 v[18:19], v[18:19], 2, s[52:53]
	s_nop 0
	s_waitcnt vmcnt(0)
	v_mov_b32_e32 v14, v214
	v_mov_b32_e32 v15, v215
	v_pk_mul_f32 v[14:15], v[16:17], v[14:15]
	s_nop 0
	v_add_f32_e32 v14, v35, v14
	v_add_f32_e32 v14, v14, v15

.LBB0_1175:
	v_mov_b32_e32 v15, 0
	s_and_saveexec_b64 s[58:59], s[38:39]
	s_cbranch_execz .LBB0_1177
	v_mad_i64_i32 v[16:17], s[28:29], v16, s91, 0
	v_lshl_add_u64 v[16:17], v[16:17], 2, s[0:1]
	s_mov_b64 s[28:29], 0x1000
	v_lshl_add_u64 v[44:45], v[16:17], 0, s[28:29]
	v_add_co_u32_e32 v16, vcc, 0x1000, v16
	v_sub_u32_e32 v48, -2, v0
	v_mov_b32_e32 v49, v1
	v_addc_co_u32_e32 v17, vcc, 0, v17, vcc
	v_lshl_add_u64 v[48:49], v[48:49], 2, s[52:53]
	v_sub_u32_e32 v216, -2, v0
	v_mov_b32_e32 v217, v1
	v_lshl_add_u64 v[216:217], v[216:217], 2, s[52:53]
	s_mov_b64 s[98:99], 0x1000
	global_load_dword v200, v[216:217], off
	global_load_dword v201, v[216:217], off offset:1024
	global_load_dword v202, v[216:217], off offset:2048
	global_load_dword v203, v[216:217], off offset:3072
	v_lshl_add_u64 v[216:217], v[216:217], 0, s[98:99]
	global_load_dword v204, v[216:217], off
	global_load_dword v205, v[216:217], off offset:1024
	global_load_dword v206, v[216:217], off offset:2048
	global_load_dword v207, v[216:217], off offset:3072
	v_lshl_add_u64 v[216:217], v[216:217], 0, s[98:99]
	global_load_dword v208, v[216:217], off
	global_load_dword v209, v[216:217], off offset:1024
	global_load_dword v210, v[216:217], off offset:2048
	global_load_dword v211, v[216:217], off offset:3072
	v_lshl_add_u64 v[216:217], v[216:217], 0, s[98:99]
	global_load_dword v212, v[216:217], off
	global_load_dword v213, v[216:217], off offset:1024
	global_load_dword v214, v[216:217], off offset:2048
	global_load_dword v215, v[216:217], off offset:3072
	global_load_dwordx4 v[36:39], v[16:17], off
	s_nop 0
	global_load_dwordx4 v[16:19], v[44:45], off offset:48
	global_load_dwordx4 v[40:43], v[44:45], off offset:32
	s_nop 0
	global_load_dwordx4 v[44:47], v[44:45], off offset:16
	s_nop 0
	v_sub_u32_e32 v48, 0xfe, v0
	v_ashrrev_i32_e32 v49, 31, v48
	v_lshl_add_u64 v[48:49], v[48:49], 2, s[52:53]
	s_waitcnt vmcnt(0)
	v_mov_b32_e32 v15, v200
	v_mov_b32_e32 v35, v201
	v_fma_f32 v15, v36, v15, 0
	v_sub_u32_e32 v36, 0x1fe, v0
	s_waitcnt vmcnt(0)
	v_fmac_f32_e32 v15, v37, v35
	v_ashrrev_i32_e32 v37, 31, v36
	v_lshl_add_u64 v[36:37], v[36:37], 2, s[52:53]
	v_sub_u32_e32 v36, 0x2fe, v0
	v_ashrrev_i32_e32 v37, 31, v36
	v_lshl_add_u64 v[36:37], v[36:37], 2, s[52:53]
	s_waitcnt vmcnt(0)
	v_mov_b32_e32 v35, v202
	v_fmac_f32_e32 v15, v38, v35
	v_sub_u32_e32 v36, 0x3fe, v0
	v_sub_u32_e32 v38, 0x4fe, v0
	v_ashrrev_i32_e32 v37, 31, v36
	v_lshl_add_u64 v[36:37], v[36:37], 2, s[52:53]
	s_waitcnt vmcnt(1)
	v_mov_b32_e32 v35, v203
	v_mov_b32_e32 v36, v204
	v_fmac_f32_e32 v15, v39, v35
	v_ashrrev_i32_e32 v39, 31, v38
	v_lshl_add_u64 v[38:39], v[38:39], 2, s[52:53]
	v_sub_u32_e32 v38, 0x6fe, v0
	v_ashrrev_i32_e32 v39, 31, v38
	v_lshl_add_u64 v[38:39], v[38:39], 2, s[52:53]
	s_waitcnt vmcnt(0)
	v_mov_b32_e32 v37, v205
	v_pk_mul_f32 v[36:37], v[44:45], v[36:37]
	s_nop 0
	v_add_f32_e32 v15, v15, v36
	v_sub_u32_e32 v36, 0x5fe, v0
	v_add_f32_e32 v15, v15, v37
	v_ashrrev_i32_e32 v37, 31, v36
	v_lshl_add_u64 v[36:37], v[36:37], 2, s[52:53]
	s_nop 0
	v_sub_u32_e32 v38, 0x8fe, v0
	v_ashrrev_i32_e32 v39, 31, v38
	v_lshl_add_u64 v[38:39], v[38:39], 2, s[52:53]
	s_waitcnt vmcnt(0)
	v_mov_b32_e32 v36, v206
	v_mov_b32_e32 v37, v207
	v_pk_mul_f32 v[36:37], v[46:47], v[36:37]
	s_nop 0
	v_add_f32_e32 v15, v15, v36
	v_sub_u32_e32 v36, 0x7fe, v0
	v_add_f32_e32 v15, v15, v37
	v_ashrrev_i32_e32 v37, 31, v36
	v_lshl_add_u64 v[36:37], v[36:37], 2, s[52:53]
	s_nop 0
	v_sub_u32_e32 v38, 0xafe, v0
	v_ashrrev_i32_e32 v39, 31, v38
	v_lshl_add_u64 v[38:39], v[38:39], 2, s[52:53]
	s_waitcnt vmcnt(0)
	v_mov_b32_e32 v36, v208
	v_mov_b32_e32 v37, v209
	v_pk_mul_f32 v[36:37], v[40:41], v[36:37]
	s_nop 0
	v_add_f32_e32 v15, v15, v36
	v_sub_u32_e32 v36, 0x9fe, v0
	v_add_f32_e32 v15, v15, v37
	v_ashrrev_i32_e32 v37, 31, v36
	v_lshl_add_u64 v[36:37], v[36:37], 2, s[52:53]
	s_nop 0
	v_sub_u32_e32 v38, 0xcfe, v0
	v_ashrrev_i32_e32 v39, 31, v38
	v_lshl_add_u64 v[38:39], v[38:39], 2, s[52:53]
	s_waitcnt vmcnt(0)
	v_mov_b32_e32 v36, v210
	v_mov_b32_e32 v37, v211
	v_pk_mul_f32 v[36:37], v[42:43], v[36:37]
	s_nop 0
	v_add_f32_e32 v15, v15, v36
	v_sub_u32_e32 v36, 0xbfe, v0
	v_add_f32_e32 v15, v15, v37
	v_ashrrev_i32_e32 v37, 31, v36
	v_lshl_add_u64 v[36:37], v[36:37], 2, s[52:53]
	s_nop 0
	s_waitcnt vmcnt(0)
	v_mov_b32_e32 v36, v212
	v_mov_b32_e32 v37, v213
	v_pk_mul_f32 v[16:17], v[16:17], v[36:37]
	s_nop 0
	v_add_f32_e32 v15, v15, v16
	v_sub_u32_e32 v16, 0xdfe, v0
	v_sub_u32_e32 v36, 0xefe, v0
	v_add_f32_e32 v15, v15, v17
	v_ashrrev_i32_e32 v17, 31, v16
	v_ashrrev_i32_e32 v37, 31, v36
	v_lshl_add_u64 v[16:17], v[16:17], 2, s[52:53]
	v_lshl_add_u64 v[36:37], v[36:37], 2, s[52:53]
	s_nop 0
	s_waitcnt vmcnt(0)
	v_mov_b32_e32 v16, v214
	v_mov_b32_e32 v17, v215
	v_pk_mul_f32 v[16:17], v[18:19], v[16:17]
	s_nop 0
	v_add_f32_e32 v15, v15, v16
	v_add_f32_e32 v15, v15, v17

.LBB0_1179:
	v_mov_b32_e32 v16, 0
	s_and_saveexec_b64 s[58:59], s[38:39]
	s_cbranch_execz .LBB0_1181
	v_mad_i64_i32 v[16:17], s[28:29], v17, s91, 0
	v_lshl_add_u64 v[16:17], v[16:17], 2, s[0:1]
	s_mov_b64 s[28:29], 0x1000
	v_lshl_add_u64 v[44:45], v[16:17], 0, s[28:29]
	v_add_co_u32_e32 v16, vcc, 0x1000, v16
	v_sub_u32_e32 v48, -2, v0
	v_mov_b32_e32 v49, v1
	v_addc_co_u32_e32 v17, vcc, 0, v17, vcc
	v_lshl_add_u64 v[48:49], v[48:49], 2, s[52:53]
	v_sub_u32_e32 v216, -2, v0
	v_mov_b32_e32 v217, v1
	v_lshl_add_u64 v[216:217], v[216:217], 2, s[52:53]
	s_mov_b64 s[98:99], 0x1000
	global_load_dword v200, v[216:217], off
	global_load_dword v201, v[216:217], off offset:1024
	global_load_dword v202, v[216:217], off offset:2048
	global_load_dword v203, v[216:217], off offset:3072
	v_lshl_add_u64 v[216:217], v[216:217], 0, s[98:99]
	global_load_dword v204, v[216:217], off
	global_load_dword v205, v[216:217], off offset:1024
	global_load_dword v206, v[216:217], off offset:2048
	global_load_dword v207, v[216:217], off offset:3072
	v_lshl_add_u64 v[216:217], v[216:217], 0, s[98:99]
	global_load_dword v208, v[216:217], off
	global_load_dword v209, v[216:217], off offset:1024
	global_load_dword v210, v[216:217], off offset:2048
	global_load_dword v211, v[216:217], off offset:3072
	v_lshl_add_u64 v[216:217], v[216:217], 0, s[98:99]
	global_load_dword v212, v[216:217], off
	global_load_dword v213, v[216:217], off offset:1024
	global_load_dword v214, v[216:217], off offset:2048
	global_load_dword v215, v[216:217], off offset:3072
	global_load_dwordx4 v[36:39], v[16:17], off
	s_nop 0
	global_load_dwordx4 v[16:19], v[44:45], off offset:48
	global_load_dwordx4 v[40:43], v[44:45], off offset:32
	s_nop 0
	global_load_dwordx4 v[44:47], v[44:45], off offset:16
	s_nop 0
	v_sub_u32_e32 v48, 0xfe, v0
	v_ashrrev_i32_e32 v49, 31, v48
	v_lshl_add_u64 v[48:49], v[48:49], 2, s[52:53]
	s_waitcnt vmcnt(0)
	v_mov_b32_e32 v35, v200
	v_fma_f32 v35, v36, v35, 0
	s_waitcnt vmcnt(0)
	v_mov_b32_e32 v36, v201
	v_fmac_f32_e32 v35, v37, v36
	v_sub_u32_e32 v36, 0x1fe, v0
	v_ashrrev_i32_e32 v37, 31, v36
	v_lshl_add_u64 v[36:37], v[36:37], 2, s[52:53]
	s_waitcnt vmcnt(0)
	v_mov_b32_e32 v36, v202
	v_fmac_f32_e32 v35, v38, v36
	v_sub_u32_e32 v36, 0x2fe, v0
	v_ashrrev_i32_e32 v37, 31, v36
	v_lshl_add_u64 v[36:37], v[36:37], 2, s[52:53]
	v_sub_u32_e32 v38, 0x4fe, v0
	s_waitcnt vmcnt(0)
	v_mov_b32_e32 v36, v203
	v_fmac_f32_e32 v35, v39, v36
	v_sub_u32_e32 v36, 0x3fe, v0
	v_ashrrev_i32_e32 v37, 31, v36
	v_ashrrev_i32_e32 v39, 31, v38
	v_lshl_add_u64 v[36:37], v[36:37], 2, s[52:53]
	v_lshl_add_u64 v[38:39], v[38:39], 2, s[52:53]
	s_nop 0
	v_sub_u32_e32 v38, 0x6fe, v0
	v_ashrrev_i32_e32 v39, 31, v38
	v_lshl_add_u64 v[38:39], v[38:39], 2, s[52:53]
	s_waitcnt vmcnt(0)
	v_mov_b32_e32 v36, v204
	v_mov_b32_e32 v37, v205
	v_pk_mul_f32 v[36:37], v[44:45], v[36:37]
	s_nop 0
	v_add_f32_e32 v35, v35, v36
	v_sub_u32_e32 v36, 0x5fe, v0
	v_add_f32_e32 v35, v35, v37
	v_ashrrev_i32_e32 v37, 31, v36
	v_lshl_add_u64 v[36:37], v[36:37], 2, s[52:53]
	s_nop 0
	v_sub_u32_e32 v38, 0x8fe, v0
	v_ashrrev_i32_e32 v39, 31, v38
	v_lshl_add_u64 v[38:39], v[38:39], 2, s[52:53]
	s_waitcnt vmcnt(0)
	v_mov_b32_e32 v36, v206
	v_mov_b32_e32 v37, v207
	v_pk_mul_f32 v[36:37], v[46:47], v[36:37]
	s_nop 0
	v_add_f32_e32 v35, v35, v36
	v_sub_u32_e32 v36, 0x7fe, v0
	v_add_f32_e32 v35, v35, v37
	v_ashrrev_i32_e32 v37, 31, v36
	v_lshl_add_u64 v[36:37], v[36:37], 2, s[52:53]
	s_nop 0
	v_sub_u32_e32 v38, 0xafe, v0
	v_ashrrev_i32_e32 v39, 31, v38
	v_lshl_add_u64 v[38:39], v[38:39], 2, s[52:53]
	s_waitcnt vmcnt(0)
	v_mov_b32_e32 v36, v208
	v_mov_b32_e32 v37, v209
	v_pk_mul_f32 v[36:37], v[40:41], v[36:37]
	s_nop 0
	v_add_f32_e32 v35, v35, v36
	v_sub_u32_e32 v36, 0x9fe, v0
	v_add_f32_e32 v35, v35, v37
	v_ashrrev_i32_e32 v37, 31, v36
	v_lshl_add_u64 v[36:37], v[36:37], 2, s[52:53]
	s_nop 0
	v_sub_u32_e32 v38, 0xcfe, v0
	v_ashrrev_i32_e32 v39, 31, v38
	v_lshl_add_u64 v[38:39], v[38:39], 2, s[52:53]
	s_waitcnt vmcnt(0)
	v_mov_b32_e32 v36, v210
	v_mov_b32_e32 v37, v211
	v_pk_mul_f32 v[36:37], v[42:43], v[36:37]
	s_nop 0
	v_add_f32_e32 v35, v35, v36
	v_sub_u32_e32 v36, 0xbfe, v0
	v_add_f32_e32 v35, v35, v37
	v_ashrrev_i32_e32 v37, 31, v36
	v_lshl_add_u64 v[36:37], v[36:37], 2, s[52:53]
	s_nop 0
	s_waitcnt vmcnt(0)
	v_mov_b32_e32 v36, v212
	v_mov_b32_e32 v37, v213
	v_pk_mul_f32 v[16:17], v[16:17], v[36:37]
	s_nop 0
	v_add_f32_e32 v16, v35, v16
	v_add_f32_e32 v35, v16, v17
	v_sub_u32_e32 v16, 0xdfe, v0
	v_sub_u32_e32 v36, 0xefe, v0
	v_ashrrev_i32_e32 v17, 31, v16
	v_ashrrev_i32_e32 v37, 31, v36
	v_lshl_add_u64 v[16:17], v[16:17], 2, s[52:53]
	v_lshl_add_u64 v[36:37], v[36:37], 2, s[52:53]
	s_nop 0
	s_waitcnt vmcnt(0)
	v_mov_b32_e32 v16, v214
	v_mov_b32_e32 v17, v215
	v_pk_mul_f32 v[16:17], v[18:19], v[16:17]
	s_nop 0
	v_add_f32_e32 v16, v35, v16
	v_add_f32_e32 v16, v16, v17

.LBB0_1183:
	v_mov_b32_e32 v17, 0
	s_and_saveexec_b64 s[40:41], s[38:39]
	s_cbranch_execz .LBB0_1185
	v_mad_i64_i32 v[18:19], s[28:29], v18, s91, 0
	v_lshl_add_u64 v[18:19], v[18:19], 2, s[0:1]
	s_mov_b64 s[28:29], 0x1000
	v_lshl_add_u64 v[44:45], v[18:19], 0, s[28:29]
	v_add_co_u32_e32 v18, vcc, 0x1000, v18
	v_sub_u32_e32 v48, -2, v0
	v_mov_b32_e32 v49, v1
	v_addc_co_u32_e32 v19, vcc, 0, v19, vcc
	v_lshl_add_u64 v[48:49], v[48:49], 2, s[52:53]
	v_sub_u32_e32 v216, -2, v0
	v_mov_b32_e32 v217, v1
	v_lshl_add_u64 v[216:217], v[216:217], 2, s[52:53]
	s_mov_b64 s[98:99], 0x1000
	global_load_dword v200, v[216:217], off
	global_load_dword v201, v[216:217], off offset:1024
	global_load_dword v202, v[216:217], off offset:2048
	global_load_dword v203, v[216:217], off offset:3072
	v_lshl_add_u64 v[216:217], v[216:217], 0, s[98:99]
	global_load_dword v204, v[216:217], off
	global_load_dword v205, v[216:217], off offset:1024
	global_load_dword v206, v[216:217], off offset:2048
	global_load_dword v207, v[216:217], off offset:3072
	v_lshl_add_u64 v[216:217], v[216:217], 0, s[98:99]
	global_load_dword v208, v[216:217], off
	global_load_dword v209, v[216:217], off offset:1024
	global_load_dword v210, v[216:217], off offset:2048
	global_load_dword v211, v[216:217], off offset:3072
	v_lshl_add_u64 v[216:217], v[216:217], 0, s[98:99]
	global_load_dword v212, v[216:217], off
	global_load_dword v213, v[216:217], off offset:1024
	global_load_dword v214, v[216:217], off offset:2048
	global_load_dword v215, v[216:217], off offset:3072
	global_load_dwordx4 v[36:39], v[18:19], off
	s_nop 0
	global_load_dwordx4 v[18:21], v[44:45], off offset:48
	global_load_dwordx4 v[40:43], v[44:45], off offset:32
	s_nop 0
	global_load_dwordx4 v[44:47], v[44:45], off offset:16
	s_nop 0
	v_sub_u32_e32 v48, 0xfe, v0
	v_ashrrev_i32_e32 v49, 31, v48
	v_lshl_add_u64 v[48:49], v[48:49], 2, s[52:53]
	s_waitcnt vmcnt(0)
	v_mov_b32_e32 v17, v200
	v_mov_b32_e32 v35, v201
	v_fma_f32 v17, v36, v17, 0
	v_sub_u32_e32 v36, 0x1fe, v0
	s_waitcnt vmcnt(0)
	v_fmac_f32_e32 v17, v37, v35
	v_ashrrev_i32_e32 v37, 31, v36
	v_lshl_add_u64 v[36:37], v[36:37], 2, s[52:53]
	v_sub_u32_e32 v36, 0x2fe, v0
	v_ashrrev_i32_e32 v37, 31, v36
	v_lshl_add_u64 v[36:37], v[36:37], 2, s[52:53]
	s_waitcnt vmcnt(0)
	v_mov_b32_e32 v35, v202
	v_fmac_f32_e32 v17, v38, v35
	v_sub_u32_e32 v36, 0x3fe, v0
	v_sub_u32_e32 v38, 0x4fe, v0
	v_ashrrev_i32_e32 v37, 31, v36
	v_lshl_add_u64 v[36:37], v[36:37], 2, s[52:53]
	s_waitcnt vmcnt(1)
	v_mov_b32_e32 v35, v203
	v_mov_b32_e32 v36, v204
	v_fmac_f32_e32 v17, v39, v35
	v_ashrrev_i32_e32 v39, 31, v38
	v_lshl_add_u64 v[38:39], v[38:39], 2, s[52:53]
	v_sub_u32_e32 v38, 0x6fe, v0
	v_ashrrev_i32_e32 v39, 31, v38
	v_lshl_add_u64 v[38:39], v[38:39], 2, s[52:53]
	s_waitcnt vmcnt(0)
	v_mov_b32_e32 v37, v205
	v_pk_mul_f32 v[36:37], v[44:45], v[36:37]
	s_nop 0
	v_add_f32_e32 v17, v17, v36
	v_sub_u32_e32 v36, 0x5fe, v0
	v_add_f32_e32 v17, v17, v37
	v_ashrrev_i32_e32 v37, 31, v36
	v_lshl_add_u64 v[36:37], v[36:37], 2, s[52:53]
	s_nop 0
	v_sub_u32_e32 v38, 0x8fe, v0
	v_ashrrev_i32_e32 v39, 31, v38
	v_lshl_add_u64 v[38:39], v[38:39], 2, s[52:53]
	s_waitcnt vmcnt(0)
	v_mov_b32_e32 v36, v206
	v_mov_b32_e32 v37, v207
	v_pk_mul_f32 v[36:37], v[46:47], v[36:37]
	s_nop 0
	v_add_f32_e32 v17, v17, v36
	v_sub_u32_e32 v36, 0x7fe, v0
	v_add_f32_e32 v17, v17, v37
	v_ashrrev_i32_e32 v37, 31, v36
	v_lshl_add_u64 v[36:37], v[36:37], 2, s[52:53]
	s_nop 0
	v_sub_u32_e32 v38, 0xafe, v0
	v_ashrrev_i32_e32 v39, 31, v38
	v_lshl_add_u64 v[38:39], v[38:39], 2, s[52:53]
	s_waitcnt vmcnt(0)
	v_mov_b32_e32 v36, v208
	v_mov_b32_e32 v37, v209
	v_pk_mul_f32 v[36:37], v[40:41], v[36:37]
	s_nop 0
	v_add_f32_e32 v17, v17, v36
	v_sub_u32_e32 v36, 0x9fe, v0
	v_add_f32_e32 v17, v17, v37
	v_ashrrev_i32_e32 v37, 31, v36
	v_lshl_add_u64 v[36:37], v[36:37], 2, s[52:53]
	s_nop 0
	v_sub_u32_e32 v38, 0xcfe, v0
	v_ashrrev_i32_e32 v39, 31, v38
	v_lshl_add_u64 v[38:39], v[38:39], 2, s[52:53]
	s_waitcnt vmcnt(0)
	v_mov_b32_e32 v36, v210
	v_mov_b32_e32 v37, v211
	v_pk_mul_f32 v[36:37], v[42:43], v[36:37]
	s_nop 0
	v_add_f32_e32 v17, v17, v36
	v_sub_u32_e32 v36, 0xbfe, v0
	v_add_f32_e32 v17, v17, v37
	v_ashrrev_i32_e32 v37, 31, v36
	v_lshl_add_u64 v[36:37], v[36:37], 2, s[52:53]
	s_nop 0
	s_waitcnt vmcnt(0)
	v_mov_b32_e32 v36, v212
	v_mov_b32_e32 v37, v213
	v_pk_mul_f32 v[18:19], v[18:19], v[36:37]
	s_nop 0
	v_add_f32_e32 v17, v17, v18
	v_sub_u32_e32 v18, 0xdfe, v0
	v_sub_u32_e32 v36, 0xefe, v0
	v_add_f32_e32 v17, v17, v19
	v_ashrrev_i32_e32 v19, 31, v18
	v_ashrrev_i32_e32 v37, 31, v36
	v_lshl_add_u64 v[18:19], v[18:19], 2, s[52:53]
	v_lshl_add_u64 v[36:37], v[36:37], 2, s[52:53]
	s_nop 0
	s_waitcnt vmcnt(0)
	v_mov_b32_e32 v18, v214
	v_mov_b32_e32 v19, v215
	v_pk_mul_f32 v[18:19], v[20:21], v[18:19]
	s_nop 0
	v_add_f32_e32 v0, v17, v18
	v_add_f32_e32 v17, v0, v19

.LBB0_1221:
	v_mov_b32_e32 v4, 0
	s_and_saveexec_b64 s[58:59], s[40:41]
	s_cbranch_execz .LBB0_1223
	v_mad_i64_i32 v[4:5], s[28:29], v5, s91, 0
	v_lshl_add_u64 v[4:5], v[4:5], 2, s[0:1]
	s_mov_b64 s[28:29], 0x1000
	v_lshl_add_u64 v[16:17], v[4:5], 0, s[28:29]
	v_add_co_u32_e32 v4, vcc, 0x1000, v4
	v_sub_u32_e32 v26, -2, v0
	v_mov_b32_e32 v27, v1
	v_addc_co_u32_e32 v5, vcc, 0, v5, vcc
	v_lshl_add_u64 v[26:27], v[26:27], 2, s[76:77]
	v_sub_u32_e32 v216, -2, v0
	v_mov_b32_e32 v217, v1
	v_lshl_add_u64 v[216:217], v[216:217], 2, s[76:77]
	s_mov_b64 s[98:99], 0x1000
	global_load_dword v200, v[216:217], off
	global_load_dword v201, v[216:217], off offset:1024
	global_load_dword v202, v[216:217], off offset:2048
	global_load_dword v203, v[216:217], off offset:3072
	v_lshl_add_u64 v[216:217], v[216:217], 0, s[98:99]
	global_load_dword v204, v[216:217], off
	global_load_dword v205, v[216:217], off offset:1024
	global_load_dword v206, v[216:217], off offset:2048
	global_load_dword v207, v[216:217], off offset:3072
	v_lshl_add_u64 v[216:217], v[216:217], 0, s[98:99]
	global_load_dword v208, v[216:217], off
	global_load_dword v209, v[216:217], off offset:1024
	global_load_dword v210, v[216:217], off offset:2048
	global_load_dword v211, v[216:217], off offset:3072
	v_lshl_add_u64 v[216:217], v[216:217], 0, s[98:99]
	global_load_dword v212, v[216:217], off
	global_load_dword v213, v[216:217], off offset:1024
	global_load_dword v214, v[216:217], off offset:2048
	global_load_dword v215, v[216:217], off offset:3072
	global_load_dwordx4 v[8:11], v[4:5], off
	s_nop 0
	global_load_dwordx4 v[4:7], v[16:17], off offset:48
	global_load_dwordx4 v[12:15], v[16:17], off offset:32
	s_nop 0
	global_load_dwordx4 v[16:19], v[16:17], off offset:16
	s_nop 0
	s_waitcnt vmcnt(0)
	v_mov_b32_e32 v26, v200
	v_fma_f32 v28, v8, v26, 0
	v_sub_u32_e32 v26, 0xfe, v0
	v_ashrrev_i32_e32 v27, 31, v26
	v_lshl_add_u64 v[26:27], v[26:27], 2, s[76:77]
	s_waitcnt vmcnt(0)
	v_mov_b32_e32 v8, v201
	v_fmac_f32_e32 v28, v9, v8
	v_sub_u32_e32 v8, 0x1fe, v0
	v_ashrrev_i32_e32 v9, 31, v8
	v_lshl_add_u64 v[8:9], v[8:9], 2, s[76:77]
	s_waitcnt vmcnt(0)
	v_mov_b32_e32 v8, v202
	v_fmac_f32_e32 v28, v10, v8
	v_sub_u32_e32 v8, 0x2fe, v0
	v_ashrrev_i32_e32 v9, 31, v8
	v_lshl_add_u64 v[8:9], v[8:9], 2, s[76:77]
	v_sub_u32_e32 v10, 0x4fe, v0
	s_waitcnt vmcnt(0)
	v_mov_b32_e32 v8, v203
	v_fmac_f32_e32 v28, v11, v8
	v_sub_u32_e32 v8, 0x3fe, v0
	v_ashrrev_i32_e32 v9, 31, v8
	v_ashrrev_i32_e32 v11, 31, v10
	v_lshl_add_u64 v[8:9], v[8:9], 2, s[76:77]
	v_lshl_add_u64 v[10:11], v[10:11], 2, s[76:77]
	s_nop 0
	v_sub_u32_e32 v10, 0x6fe, v0
	v_ashrrev_i32_e32 v11, 31, v10
	v_lshl_add_u64 v[10:11], v[10:11], 2, s[76:77]
	s_waitcnt vmcnt(0)
	v_mov_b32_e32 v8, v204
	v_mov_b32_e32 v9, v205
	v_pk_mul_f32 v[8:9], v[16:17], v[8:9]
	s_nop 0
	v_add_f32_e32 v8, v28, v8
	v_add_f32_e32 v16, v8, v9
	v_sub_u32_e32 v8, 0x5fe, v0
	v_ashrrev_i32_e32 v9, 31, v8
	v_lshl_add_u64 v[8:9], v[8:9], 2, s[76:77]
	s_nop 0
	v_sub_u32_e32 v10, 0x8fe, v0
	v_ashrrev_i32_e32 v11, 31, v10
	v_lshl_add_u64 v[10:11], v[10:11], 2, s[76:77]
	s_waitcnt vmcnt(0)
	v_mov_b32_e32 v8, v206
	v_mov_b32_e32 v9, v207
	v_pk_mul_f32 v[8:9], v[18:19], v[8:9]
	s_nop 0
	v_add_f32_e32 v8, v16, v8
	v_add_f32_e32 v16, v8, v9
	v_sub_u32_e32 v8, 0x7fe, v0
	v_ashrrev_i32_e32 v9, 31, v8
	v_lshl_add_u64 v[8:9], v[8:9], 2, s[76:77]
	s_nop 0
	v_sub_u32_e32 v10, 0xafe, v0
	v_ashrrev_i32_e32 v11, 31, v10
	v_lshl_add_u64 v[10:11], v[10:11], 2, s[76:77]
	s_waitcnt vmcnt(0)
	v_mov_b32_e32 v8, v208
	v_mov_b32_e32 v9, v209
	v_pk_mul_f32 v[8:9], v[12:13], v[8:9]
	s_nop 0
	v_add_f32_e32 v8, v16, v8
	v_add_f32_e32 v12, v8, v9
	v_sub_u32_e32 v8, 0x9fe, v0
	v_ashrrev_i32_e32 v9, 31, v8
	v_lshl_add_u64 v[8:9], v[8:9], 2, s[76:77]
	s_nop 0
	v_sub_u32_e32 v10, 0xcfe, v0
	v_ashrrev_i32_e32 v11, 31, v10
	v_lshl_add_u64 v[10:11], v[10:11], 2, s[76:77]
	s_waitcnt vmcnt(0)
	v_mov_b32_e32 v8, v210
	v_mov_b32_e32 v9, v211
	v_pk_mul_f32 v[8:9], v[14:15], v[8:9]
	s_nop 0
	v_add_f32_e32 v8, v12, v8
	v_add_f32_e32 v12, v8, v9
	v_sub_u32_e32 v8, 0xbfe, v0
	v_ashrrev_i32_e32 v9, 31, v8
	v_lshl_add_u64 v[8:9], v[8:9], 2, s[76:77]
	s_nop 0
	s_waitcnt vmcnt(0)
	v_mov_b32_e32 v8, v212
	v_mov_b32_e32 v9, v213
	v_pk_mul_f32 v[4:5], v[4:5], v[8:9]
	s_nop 0
	v_add_f32_e32 v4, v12, v4
	v_add_f32_e32 v10, v4, v5
	v_sub_u32_e32 v4, 0xdfe, v0
	v_sub_u32_e32 v8, 0xefe, v0
	v_ashrrev_i32_e32 v5, 31, v4
	v_ashrrev_i32_e32 v9, 31, v8
	v_lshl_add_u64 v[4:5], v[4:5], 2, s[76:77]
	v_lshl_add_u64 v[8:9], v[8:9], 2, s[76:77]
	s_nop 0
	s_waitcnt vmcnt(0)
	v_mov_b32_e32 v4, v214
	v_mov_b32_e32 v5, v215
	v_pk_mul_f32 v[4:5], v[6:7], v[4:5]
	s_nop 0
	v_add_f32_e32 v4, v10, v4
	v_add_f32_e32 v4, v4, v5

.LBB0_1225:
	v_mov_b32_e32 v5, 0
	s_and_saveexec_b64 s[58:59], s[40:41]
	s_cbranch_execz .LBB0_1227
	v_mad_i64_i32 v[6:7], s[28:29], v6, s91, 0
	v_lshl_add_u64 v[6:7], v[6:7], 2, s[0:1]
	s_mov_b64 s[28:29], 0x1000
	v_lshl_add_u64 v[18:19], v[6:7], 0, s[28:29]
	v_add_co_u32_e32 v6, vcc, 0x1000, v6
	s_nop 1
	v_addc_co_u32_e32 v7, vcc, 0, v7, vcc
	v_sub_u32_e32 v216, -2, v0
	v_mov_b32_e32 v217, v1
	v_lshl_add_u64 v[216:217], v[216:217], 2, s[76:77]
	s_mov_b64 s[98:99], 0x1000
	global_load_dword v200, v[216:217], off
	global_load_dword v201, v[216:217], off offset:1024
	global_load_dword v202, v[216:217], off offset:2048
	global_load_dword v203, v[216:217], off offset:3072
	v_lshl_add_u64 v[216:217], v[216:217], 0, s[98:99]
	global_load_dword v204, v[216:217], off
	global_load_dword v205, v[216:217], off offset:1024
	global_load_dword v206, v[216:217], off offset:2048
	global_load_dword v207, v[216:217], off offset:3072
	v_lshl_add_u64 v[216:217], v[216:217], 0, s[98:99]
	global_load_dword v208, v[216:217], off
	global_load_dword v209, v[216:217], off offset:1024
	global_load_dword v210, v[216:217], off offset:2048
	global_load_dword v211, v[216:217], off offset:3072
	v_lshl_add_u64 v[216:217], v[216:217], 0, s[98:99]
	global_load_dword v212, v[216:217], off
	global_load_dword v213, v[216:217], off offset:1024
	global_load_dword v214, v[216:217], off offset:2048
	global_load_dword v215, v[216:217], off offset:3072
	global_load_dwordx4 v[10:13], v[6:7], off
	s_nop 0
	global_load_dwordx4 v[6:9], v[18:19], off offset:48
	global_load_dwordx4 v[14:17], v[18:19], off offset:32
	global_load_dwordx4 v[26:29], v[18:19], off offset:16
	v_sub_u32_e32 v18, -2, v0
	v_mov_b32_e32 v19, v1
	v_lshl_add_u64 v[18:19], v[18:19], 2, s[76:77]
	v_sub_u32_e32 v18, 0xfe, v0
	v_ashrrev_i32_e32 v19, 31, v18
	v_lshl_add_u64 v[18:19], v[18:19], 2, s[76:77]
	s_waitcnt vmcnt(0)
	v_mov_b32_e32 v5, v200
	v_fma_f32 v5, v10, v5, 0
	s_waitcnt vmcnt(0)
	v_mov_b32_e32 v10, v201
	v_fmac_f32_e32 v5, v11, v10
	v_sub_u32_e32 v10, 0x1fe, v0
	v_ashrrev_i32_e32 v11, 31, v10
	v_lshl_add_u64 v[10:11], v[10:11], 2, s[76:77]
	s_waitcnt vmcnt(0)
	v_mov_b32_e32 v10, v202
	v_fmac_f32_e32 v5, v12, v10
	v_sub_u32_e32 v10, 0x2fe, v0
	v_ashrrev_i32_e32 v11, 31, v10
	v_lshl_add_u64 v[10:11], v[10:11], 2, s[76:77]
	v_sub_u32_e32 v12, 0x4fe, v0
	s_waitcnt vmcnt(0)
	v_mov_b32_e32 v10, v203
	v_fmac_f32_e32 v5, v13, v10
	v_sub_u32_e32 v10, 0x3fe, v0
	v_ashrrev_i32_e32 v11, 31, v10
	v_ashrrev_i32_e32 v13, 31, v12
	v_lshl_add_u64 v[10:11], v[10:11], 2, s[76:77]
	v_lshl_add_u64 v[12:13], v[12:13], 2, s[76:77]
	s_nop 0
	v_sub_u32_e32 v12, 0x6fe, v0
	v_ashrrev_i32_e32 v13, 31, v12
	v_lshl_add_u64 v[12:13], v[12:13], 2, s[76:77]
	s_waitcnt vmcnt(0)
	v_mov_b32_e32 v10, v204
	v_mov_b32_e32 v11, v205
	v_pk_mul_f32 v[10:11], v[26:27], v[10:11]
	s_nop 0
	v_add_f32_e32 v5, v5, v10
	v_sub_u32_e32 v10, 0x5fe, v0
	v_add_f32_e32 v5, v5, v11
	v_ashrrev_i32_e32 v11, 31, v10
	v_lshl_add_u64 v[10:11], v[10:11], 2, s[76:77]
	s_nop 0
	v_sub_u32_e32 v12, 0x8fe, v0
	v_ashrrev_i32_e32 v13, 31, v12
	v_lshl_add_u64 v[12:13], v[12:13], 2, s[76:77]
	s_waitcnt vmcnt(0)
	v_mov_b32_e32 v10, v206
	v_mov_b32_e32 v11, v207
	v_pk_mul_f32 v[10:11], v[28:29], v[10:11]
	s_nop 0
	v_add_f32_e32 v5, v5, v10
	v_sub_u32_e32 v10, 0x7fe, v0
	v_add_f32_e32 v5, v5, v11
	v_ashrrev_i32_e32 v11, 31, v10
	v_lshl_add_u64 v[10:11], v[10:11], 2, s[76:77]
	s_nop 0
	v_sub_u32_e32 v12, 0xafe, v0
	v_ashrrev_i32_e32 v13, 31, v12
	v_lshl_add_u64 v[12:13], v[12:13], 2, s[76:77]
	s_waitcnt vmcnt(0)
	v_mov_b32_e32 v10, v208
	v_mov_b32_e32 v11, v209
	v_pk_mul_f32 v[10:11], v[14:15], v[10:11]
	s_nop 0
	v_add_f32_e32 v5, v5, v10
	v_sub_u32_e32 v10, 0x9fe, v0
	v_add_f32_e32 v5, v5, v11
	v_ashrrev_i32_e32 v11, 31, v10
	v_lshl_add_u64 v[10:11], v[10:11], 2, s[76:77]
	s_nop 0
	v_sub_u32_e32 v12, 0xcfe, v0
	v_ashrrev_i32_e32 v13, 31, v12
	v_lshl_add_u64 v[12:13], v[12:13], 2, s[76:77]
	s_waitcnt vmcnt(0)
	v_mov_b32_e32 v10, v210
	v_mov_b32_e32 v11, v211
	v_pk_mul_f32 v[10:11], v[16:17], v[10:11]
	s_nop 0
	v_add_f32_e32 v5, v5, v10
	v_sub_u32_e32 v10, 0xbfe, v0
	v_add_f32_e32 v5, v5, v11
	v_ashrrev_i32_e32 v11, 31, v10
	v_lshl_add_u64 v[10:11], v[10:11], 2, s[76:77]
	s_nop 0
	s_waitcnt vmcnt(0)
	v_mov_b32_e32 v10, v212
	v_mov_b32_e32 v11, v213
	v_pk_mul_f32 v[6:7], v[6:7], v[10:11]
	s_nop 0
	v_add_f32_e32 v5, v5, v6
	v_sub_u32_e32 v6, 0xdfe, v0
	v_sub_u32_e32 v10, 0xefe, v0
	v_add_f32_e32 v5, v5, v7
	v_ashrrev_i32_e32 v7, 31, v6
	v_ashrrev_i32_e32 v11, 31, v10
	v_lshl_add_u64 v[6:7], v[6:7], 2, s[76:77]
	v_lshl_add_u64 v[10:11], v[10:11], 2, s[76:77]
	s_nop 0
	s_waitcnt vmcnt(0)
	v_mov_b32_e32 v6, v214
	v_mov_b32_e32 v7, v215
	v_pk_mul_f32 v[6:7], v[8:9], v[6:7]
	s_nop 0
	v_add_f32_e32 v5, v5, v6
	v_add_f32_e32 v5, v5, v7

.LBB0_1229:
	v_mov_b32_e32 v6, 0
	s_and_saveexec_b64 s[58:59], s[40:41]
	s_cbranch_execz .LBB0_1231
	v_mad_i64_i32 v[6:7], s[28:29], v7, s91, 0
	v_lshl_add_u64 v[6:7], v[6:7], 2, s[0:1]
	s_mov_b64 s[28:29], 0x1000
	v_lshl_add_u64 v[18:19], v[6:7], 0, s[28:29]
	v_add_co_u32_e32 v6, vcc, 0x1000, v6
	s_nop 1
	v_addc_co_u32_e32 v7, vcc, 0, v7, vcc
	v_sub_u32_e32 v216, -2, v0
	v_mov_b32_e32 v217, v1
	v_lshl_add_u64 v[216:217], v[216:217], 2, s[76:77]
	s_mov_b64 s[98:99], 0x1000
	global_load_dword v200, v[216:217], off
	global_load_dword v201, v[216:217], off offset:1024
	global_load_dword v202, v[216:217], off offset:2048
	global_load_dword v203, v[216:217], off offset:3072
	v_lshl_add_u64 v[216:217], v[216:217], 0, s[98:99]
	global_load_dword v204, v[216:217], off
	global_load_dword v205, v[216:217], off offset:1024
	global_load_dword v206, v[216:217], off offset:2048
	global_load_dword v207, v[216:217], off offset:3072
	v_lshl_add_u64 v[216:217], v[216:217], 0, s[98:99]
	global_load_dword v208, v[216:217], off
	global_load_dword v209, v[216:217], off offset:1024
	global_load_dword v210, v[216:217], off offset:2048
	global_load_dword v211, v[216:217], off offset:3072
	v_lshl_add_u64 v[216:217], v[216:217], 0, s[98:99]
	global_load_dword v212, v[216:217], off
	global_load_dword v213, v[216:217], off offset:1024
	global_load_dword v214, v[216:217], off offset:2048
	global_load_dword v215, v[216:217], off offset:3072
	global_load_dwordx4 v[10:13], v[6:7], off
	s_nop 0
	global_load_dwordx4 v[6:9], v[18:19], off offset:48
	global_load_dwordx4 v[14:17], v[18:19], off offset:32
	global_load_dwordx4 v[26:29], v[18:19], off offset:16
	v_sub_u32_e32 v18, -2, v0
	v_mov_b32_e32 v19, v1
	v_lshl_add_u64 v[18:19], v[18:19], 2, s[76:77]
	s_waitcnt vmcnt(0)
	v_mov_b32_e32 v18, v200
	v_fma_f32 v30, v10, v18, 0
	v_sub_u32_e32 v18, 0xfe, v0
	v_ashrrev_i32_e32 v19, 31, v18
	v_lshl_add_u64 v[18:19], v[18:19], 2, s[76:77]
	s_waitcnt vmcnt(0)
	v_mov_b32_e32 v10, v201
	v_fmac_f32_e32 v30, v11, v10
	v_sub_u32_e32 v10, 0x1fe, v0
	v_ashrrev_i32_e32 v11, 31, v10
	v_lshl_add_u64 v[10:11], v[10:11], 2, s[76:77]
	s_waitcnt vmcnt(0)
	v_mov_b32_e32 v10, v202
	v_fmac_f32_e32 v30, v12, v10
	v_sub_u32_e32 v10, 0x2fe, v0
	v_ashrrev_i32_e32 v11, 31, v10
	v_lshl_add_u64 v[10:11], v[10:11], 2, s[76:77]
	v_sub_u32_e32 v12, 0x4fe, v0
	s_waitcnt vmcnt(0)
	v_mov_b32_e32 v10, v203
	v_fmac_f32_e32 v30, v13, v10
	v_sub_u32_e32 v10, 0x3fe, v0
	v_ashrrev_i32_e32 v11, 31, v10
	v_ashrrev_i32_e32 v13, 31, v12
	v_lshl_add_u64 v[10:11], v[10:11], 2, s[76:77]
	v_lshl_add_u64 v[12:13], v[12:13], 2, s[76:77]
	s_nop 0
	v_sub_u32_e32 v12, 0x6fe, v0
	v_ashrrev_i32_e32 v13, 31, v12
	v_lshl_add_u64 v[12:13], v[12:13], 2, s[76:77]
	s_waitcnt vmcnt(0)
	v_mov_b32_e32 v10, v204
	v_mov_b32_e32 v11, v205
	v_pk_mul_f32 v[10:11], v[26:27], v[10:11]
	s_nop 0
	v_add_f32_e32 v10, v30, v10
	v_add_f32_e32 v18, v10, v11
	v_sub_u32_e32 v10, 0x5fe, v0
	v_ashrrev_i32_e32 v11, 31, v10
	v_lshl_add_u64 v[10:11], v[10:11], 2, s[76:77]
	s_nop 0
	v_sub_u32_e32 v12, 0x8fe, v0
	v_ashrrev_i32_e32 v13, 31, v12
	v_lshl_add_u64 v[12:13], v[12:13], 2, s[76:77]
	s_waitcnt vmcnt(0)
	v_mov_b32_e32 v10, v206
	v_mov_b32_e32 v11, v207
	v_pk_mul_f32 v[10:11], v[28:29], v[10:11]
	s_nop 0
	v_add_f32_e32 v10, v18, v10
	v_add_f32_e32 v18, v10, v11
	v_sub_u32_e32 v10, 0x7fe, v0
	v_ashrrev_i32_e32 v11, 31, v10
	v_lshl_add_u64 v[10:11], v[10:11], 2, s[76:77]
	s_nop 0
	v_sub_u32_e32 v12, 0xafe, v0
	v_ashrrev_i32_e32 v13, 31, v12
	v_lshl_add_u64 v[12:13], v[12:13], 2, s[76:77]
	s_waitcnt vmcnt(0)
	v_mov_b32_e32 v10, v208
	v_mov_b32_e32 v11, v209
	v_pk_mul_f32 v[10:11], v[14:15], v[10:11]
	s_nop 0
	v_add_f32_e32 v10, v18, v10
	v_add_f32_e32 v14, v10, v11
	v_sub_u32_e32 v10, 0x9fe, v0
	v_ashrrev_i32_e32 v11, 31, v10
	v_lshl_add_u64 v[10:11], v[10:11], 2, s[76:77]
	s_nop 0
	v_sub_u32_e32 v12, 0xcfe, v0
	v_ashrrev_i32_e32 v13, 31, v12
	v_lshl_add_u64 v[12:13], v[12:13], 2, s[76:77]
	s_waitcnt vmcnt(0)
	v_mov_b32_e32 v10, v210
	v_mov_b32_e32 v11, v211
	v_pk_mul_f32 v[10:11], v[16:17], v[10:11]
	s_nop 0
	v_add_f32_e32 v10, v14, v10
	v_add_f32_e32 v14, v10, v11
	v_sub_u32_e32 v10, 0xbfe, v0
	v_ashrrev_i32_e32 v11, 31, v10
	v_lshl_add_u64 v[10:11], v[10:11], 2, s[76:77]
	s_nop 0
	s_waitcnt vmcnt(0)
	v_mov_b32_e32 v10, v212
	v_mov_b32_e32 v11, v213
	v_pk_mul_f32 v[6:7], v[6:7], v[10:11]
	s_nop 0
	v_add_f32_e32 v6, v14, v6
	v_add_f32_e32 v12, v6, v7
	v_sub_u32_e32 v6, 0xdfe, v0
	v_sub_u32_e32 v10, 0xefe, v0
	v_ashrrev_i32_e32 v7, 31, v6
	v_ashrrev_i32_e32 v11, 31, v10
	v_lshl_add_u64 v[6:7], v[6:7], 2, s[76:77]
	v_lshl_add_u64 v[10:11], v[10:11], 2, s[76:77]
	s_nop 0
	s_waitcnt vmcnt(0)
	v_mov_b32_e32 v6, v214
	v_mov_b32_e32 v7, v215
	v_pk_mul_f32 v[6:7], v[8:9], v[6:7]
	s_nop 0
	v_add_f32_e32 v6, v12, v6
	v_add_f32_e32 v6, v6, v7

.LBB0_1233:
	v_mov_b32_e32 v7, 0
	s_and_saveexec_b64 s[58:59], s[40:41]
	s_cbranch_execz .LBB0_1235
	v_mad_i64_i32 v[8:9], s[28:29], v8, s91, 0
	v_lshl_add_u64 v[8:9], v[8:9], 2, s[0:1]
	s_mov_b64 s[28:29], 0x1000
	v_lshl_add_u64 v[26:27], v[8:9], 0, s[28:29]
	v_add_co_u32_e32 v8, vcc, 0x1000, v8
	v_sub_u32_e32 v30, -2, v0
	v_mov_b32_e32 v31, v1
	v_addc_co_u32_e32 v9, vcc, 0, v9, vcc
	v_lshl_add_u64 v[30:31], v[30:31], 2, s[76:77]
	v_sub_u32_e32 v216, -2, v0
	v_mov_b32_e32 v217, v1
	v_lshl_add_u64 v[216:217], v[216:217], 2, s[76:77]
	s_mov_b64 s[98:99], 0x1000
	global_load_dword v200, v[216:217], off
	global_load_dword v201, v[216:217], off offset:1024
	global_load_dword v202, v[216:217], off offset:2048
	global_load_dword v203, v[216:217], off offset:3072
	v_lshl_add_u64 v[216:217], v[216:217], 0, s[98:99]
	global_load_dword v204, v[216:217], off
	global_load_dword v205, v[216:217], off offset:1024
	global_load_dword v206, v[216:217], off offset:2048
	global_load_dword v207, v[216:217], off offset:3072
	v_lshl_add_u64 v[216:217], v[216:217], 0, s[98:99]
	global_load_dword v208, v[216:217], off
	global_load_dword v209, v[216:217], off offset:1024
	global_load_dword v210, v[216:217], off offset:2048
	global_load_dword v211, v[216:217], off offset:3072
	v_lshl_add_u64 v[216:217], v[216:217], 0, s[98:99]
	global_load_dword v212, v[216:217], off
	global_load_dword v213, v[216:217], off offset:1024
	global_load_dword v214, v[216:217], off offset:2048
	global_load_dword v215, v[216:217], off offset:3072
	global_load_dwordx4 v[12:15], v[8:9], off
	s_nop 0
	global_load_dwordx4 v[8:11], v[26:27], off offset:48
	global_load_dwordx4 v[16:19], v[26:27], off offset:32
	s_nop 0
	global_load_dwordx4 v[26:29], v[26:27], off offset:16
	s_nop 0
	v_sub_u32_e32 v30, 0xfe, v0
	v_ashrrev_i32_e32 v31, 31, v30
	v_lshl_add_u64 v[30:31], v[30:31], 2, s[76:77]
	s_waitcnt vmcnt(0)
	v_mov_b32_e32 v7, v200
	v_fma_f32 v7, v12, v7, 0
	s_waitcnt vmcnt(0)
	v_mov_b32_e32 v12, v201
	v_fmac_f32_e32 v7, v13, v12
	v_sub_u32_e32 v12, 0x1fe, v0
	v_ashrrev_i32_e32 v13, 31, v12
	v_lshl_add_u64 v[12:13], v[12:13], 2, s[76:77]
	s_waitcnt vmcnt(0)
	v_mov_b32_e32 v12, v202
	v_fmac_f32_e32 v7, v14, v12
	v_sub_u32_e32 v12, 0x2fe, v0
	v_ashrrev_i32_e32 v13, 31, v12
	v_lshl_add_u64 v[12:13], v[12:13], 2, s[76:77]
	v_sub_u32_e32 v14, 0x4fe, v0
	s_waitcnt vmcnt(0)
	v_mov_b32_e32 v12, v203
	v_fmac_f32_e32 v7, v15, v12
	v_sub_u32_e32 v12, 0x3fe, v0
	v_ashrrev_i32_e32 v13, 31, v12
	v_ashrrev_i32_e32 v15, 31, v14
	v_lshl_add_u64 v[12:13], v[12:13], 2, s[76:77]
	v_lshl_add_u64 v[14:15], v[14:15], 2, s[76:77]
	s_nop 0
	v_sub_u32_e32 v14, 0x6fe, v0
	v_ashrrev_i32_e32 v15, 31, v14
	v_lshl_add_u64 v[14:15], v[14:15], 2, s[76:77]
	s_waitcnt vmcnt(0)
	v_mov_b32_e32 v12, v204
	v_mov_b32_e32 v13, v205
	v_pk_mul_f32 v[12:13], v[26:27], v[12:13]
	s_nop 0
	v_add_f32_e32 v7, v7, v12
	v_sub_u32_e32 v12, 0x5fe, v0
	v_add_f32_e32 v7, v7, v13
	v_ashrrev_i32_e32 v13, 31, v12
	v_lshl_add_u64 v[12:13], v[12:13], 2, s[76:77]
	s_nop 0
	v_sub_u32_e32 v14, 0x8fe, v0
	v_ashrrev_i32_e32 v15, 31, v14
	v_lshl_add_u64 v[14:15], v[14:15], 2, s[76:77]
	s_waitcnt vmcnt(0)
	v_mov_b32_e32 v12, v206
	v_mov_b32_e32 v13, v207
	v_pk_mul_f32 v[12:13], v[28:29], v[12:13]
	s_nop 0
	v_add_f32_e32 v7, v7, v12
	v_sub_u32_e32 v12, 0x7fe, v0
	v_add_f32_e32 v7, v7, v13
	v_ashrrev_i32_e32 v13, 31, v12
	v_lshl_add_u64 v[12:13], v[12:13], 2, s[76:77]
	s_nop 0
	v_sub_u32_e32 v14, 0xafe, v0
	v_ashrrev_i32_e32 v15, 31, v14
	v_lshl_add_u64 v[14:15], v[14:15], 2, s[76:77]
	s_waitcnt vmcnt(0)
	v_mov_b32_e32 v12, v208
	v_mov_b32_e32 v13, v209
	v_pk_mul_f32 v[12:13], v[16:17], v[12:13]
	s_nop 0
	v_add_f32_e32 v7, v7, v12
	v_sub_u32_e32 v12, 0x9fe, v0
	v_add_f32_e32 v7, v7, v13
	v_ashrrev_i32_e32 v13, 31, v12
	v_lshl_add_u64 v[12:13], v[12:13], 2, s[76:77]
	s_nop 0
	v_sub_u32_e32 v14, 0xcfe, v0
	v_ashrrev_i32_e32 v15, 31, v14
	v_lshl_add_u64 v[14:15], v[14:15], 2, s[76:77]
	s_waitcnt vmcnt(0)
	v_mov_b32_e32 v12, v210
	v_mov_b32_e32 v13, v211
	v_pk_mul_f32 v[12:13], v[18:19], v[12:13]
	s_nop 0
	v_add_f32_e32 v7, v7, v12
	v_sub_u32_e32 v12, 0xbfe, v0
	v_add_f32_e32 v7, v7, v13
	v_ashrrev_i32_e32 v13, 31, v12
	v_lshl_add_u64 v[12:13], v[12:13], 2, s[76:77]
	s_nop 0
	s_waitcnt vmcnt(0)
	v_mov_b32_e32 v12, v212
	v_mov_b32_e32 v13, v213
	v_pk_mul_f32 v[8:9], v[8:9], v[12:13]
	s_nop 0
	v_add_f32_e32 v7, v7, v8
	v_sub_u32_e32 v8, 0xdfe, v0
	v_sub_u32_e32 v12, 0xefe, v0
	v_add_f32_e32 v7, v7, v9
	v_ashrrev_i32_e32 v9, 31, v8
	v_ashrrev_i32_e32 v13, 31, v12
	v_lshl_add_u64 v[8:9], v[8:9], 2, s[76:77]
	v_lshl_add_u64 v[12:13], v[12:13], 2, s[76:77]
	s_nop 0
	s_waitcnt vmcnt(0)
	v_mov_b32_e32 v8, v214
	v_mov_b32_e32 v9, v215
	v_pk_mul_f32 v[8:9], v[10:11], v[8:9]
	s_nop 0
	v_add_f32_e32 v7, v7, v8
	v_add_f32_e32 v7, v7, v9

.LBB0_1237:
	v_mov_b32_e32 v8, 0
	s_and_saveexec_b64 s[58:59], s[40:41]
	s_cbranch_execz .LBB0_1239
	v_mad_i64_i32 v[8:9], s[28:29], v9, s91, 0
	v_lshl_add_u64 v[8:9], v[8:9], 2, s[0:1]
	s_mov_b64 s[28:29], 0x1000
	v_lshl_add_u64 v[26:27], v[8:9], 0, s[28:29]
	v_add_co_u32_e32 v8, vcc, 0x1000, v8
	v_sub_u32_e32 v30, -2, v0
	v_mov_b32_e32 v31, v1
	v_addc_co_u32_e32 v9, vcc, 0, v9, vcc
	v_lshl_add_u64 v[30:31], v[30:31], 2, s[76:77]
	v_sub_u32_e32 v216, -2, v0
	v_mov_b32_e32 v217, v1
	v_lshl_add_u64 v[216:217], v[216:217], 2, s[76:77]
	s_mov_b64 s[98:99], 0x1000
	global_load_dword v200, v[216:217], off
	global_load_dword v201, v[216:217], off offset:1024
	global_load_dword v202, v[216:217], off offset:2048
	global_load_dword v203, v[216:217], off offset:3072
	v_lshl_add_u64 v[216:217], v[216:217], 0, s[98:99]
	global_load_dword v204, v[216:217], off
	global_load_dword v205, v[216:217], off offset:1024
	global_load_dword v206, v[216:217], off offset:2048
	global_load_dword v207, v[216:217], off offset:3072
	v_lshl_add_u64 v[216:217], v[216:217], 0, s[98:99]
	global_load_dword v208, v[216:217], off
	global_load_dword v209, v[216:217], off offset:1024
	global_load_dword v210, v[216:217], off offset:2048
	global_load_dword v211, v[216:217], off offset:3072
	v_lshl_add_u64 v[216:217], v[216:217], 0, s[98:99]
	global_load_dword v212, v[216:217], off
	global_load_dword v213, v[216:217], off offset:1024
	global_load_dword v214, v[216:217], off offset:2048
	global_load_dword v215, v[216:217], off offset:3072
	global_load_dwordx4 v[12:15], v[8:9], off
	s_nop 0
	global_load_dwordx4 v[8:11], v[26:27], off offset:48
	global_load_dwordx4 v[16:19], v[26:27], off offset:32
	s_nop 0
	global_load_dwordx4 v[26:29], v[26:27], off offset:16
	s_nop 0
	s_waitcnt vmcnt(0)
	v_mov_b32_e32 v30, v200
	v_fma_f32 v32, v12, v30, 0
	v_sub_u32_e32 v30, 0xfe, v0
	v_ashrrev_i32_e32 v31, 31, v30
	v_lshl_add_u64 v[30:31], v[30:31], 2, s[76:77]
	s_waitcnt vmcnt(0)
	v_mov_b32_e32 v12, v201
	v_fmac_f32_e32 v32, v13, v12
	v_sub_u32_e32 v12, 0x1fe, v0
	v_ashrrev_i32_e32 v13, 31, v12
	v_lshl_add_u64 v[12:13], v[12:13], 2, s[76:77]
	s_waitcnt vmcnt(0)
	v_mov_b32_e32 v12, v202
	v_fmac_f32_e32 v32, v14, v12
	v_sub_u32_e32 v12, 0x2fe, v0
	v_ashrrev_i32_e32 v13, 31, v12
	v_lshl_add_u64 v[12:13], v[12:13], 2, s[76:77]
	v_sub_u32_e32 v14, 0x4fe, v0
	s_waitcnt vmcnt(0)
	v_mov_b32_e32 v12, v203
	v_fmac_f32_e32 v32, v15, v12
	v_sub_u32_e32 v12, 0x3fe, v0
	v_ashrrev_i32_e32 v13, 31, v12
	v_ashrrev_i32_e32 v15, 31, v14
	v_lshl_add_u64 v[12:13], v[12:13], 2, s[76:77]
	v_lshl_add_u64 v[14:15], v[14:15], 2, s[76:77]
	s_nop 0
	v_sub_u32_e32 v14, 0x6fe, v0
	v_ashrrev_i32_e32 v15, 31, v14
	v_lshl_add_u64 v[14:15], v[14:15], 2, s[76:77]
	s_waitcnt vmcnt(0)
	v_mov_b32_e32 v12, v204
	v_mov_b32_e32 v13, v205
	v_pk_mul_f32 v[12:13], v[26:27], v[12:13]
	s_nop 0
	v_add_f32_e32 v12, v32, v12
	v_add_f32_e32 v26, v12, v13
	v_sub_u32_e32 v12, 0x5fe, v0
	v_ashrrev_i32_e32 v13, 31, v12
	v_lshl_add_u64 v[12:13], v[12:13], 2, s[76:77]
	s_nop 0
	v_sub_u32_e32 v14, 0x8fe, v0
	v_ashrrev_i32_e32 v15, 31, v14
	v_lshl_add_u64 v[14:15], v[14:15], 2, s[76:77]
	s_waitcnt vmcnt(0)
	v_mov_b32_e32 v12, v206
	v_mov_b32_e32 v13, v207
	v_pk_mul_f32 v[12:13], v[28:29], v[12:13]
	s_nop 0
	v_add_f32_e32 v12, v26, v12
	v_add_f32_e32 v26, v12, v13
	v_sub_u32_e32 v12, 0x7fe, v0
	v_ashrrev_i32_e32 v13, 31, v12
	v_lshl_add_u64 v[12:13], v[12:13], 2, s[76:77]
	s_nop 0
	v_sub_u32_e32 v14, 0xafe, v0
	v_ashrrev_i32_e32 v15, 31, v14
	v_lshl_add_u64 v[14:15], v[14:15], 2, s[76:77]
	s_waitcnt vmcnt(0)
	v_mov_b32_e32 v12, v208
	v_mov_b32_e32 v13, v209
	v_pk_mul_f32 v[12:13], v[16:17], v[12:13]
	s_nop 0
	v_add_f32_e32 v12, v26, v12
	v_add_f32_e32 v16, v12, v13
	v_sub_u32_e32 v12, 0x9fe, v0
	v_ashrrev_i32_e32 v13, 31, v12
	v_lshl_add_u64 v[12:13], v[12:13], 2, s[76:77]
	s_nop 0
	v_sub_u32_e32 v14, 0xcfe, v0
	v_ashrrev_i32_e32 v15, 31, v14
	v_lshl_add_u64 v[14:15], v[14:15], 2, s[76:77]
	s_waitcnt vmcnt(0)
	v_mov_b32_e32 v12, v210
	v_mov_b32_e32 v13, v211
	v_pk_mul_f32 v[12:13], v[18:19], v[12:13]
	s_nop 0
	v_add_f32_e32 v12, v16, v12
	v_add_f32_e32 v16, v12, v13
	v_sub_u32_e32 v12, 0xbfe, v0
	v_ashrrev_i32_e32 v13, 31, v12
	v_lshl_add_u64 v[12:13], v[12:13], 2, s[76:77]
	s_nop 0
	s_waitcnt vmcnt(0)
	v_mov_b32_e32 v12, v212
	v_mov_b32_e32 v13, v213
	v_pk_mul_f32 v[8:9], v[8:9], v[12:13]
	s_nop 0
	v_add_f32_e32 v8, v16, v8
	v_add_f32_e32 v14, v8, v9
	v_sub_u32_e32 v8, 0xdfe, v0
	v_sub_u32_e32 v12, 0xefe, v0
	v_ashrrev_i32_e32 v9, 31, v8
	v_ashrrev_i32_e32 v13, 31, v12
	v_lshl_add_u64 v[8:9], v[8:9], 2, s[76:77]
	v_lshl_add_u64 v[12:13], v[12:13], 2, s[76:77]
	s_nop 0
	s_waitcnt vmcnt(0)
	v_mov_b32_e32 v8, v214
	v_mov_b32_e32 v9, v215
	v_pk_mul_f32 v[8:9], v[10:11], v[8:9]
	s_nop 0
	v_add_f32_e32 v8, v14, v8
	v_add_f32_e32 v8, v8, v9

.LBB0_1241:
	v_mov_b32_e32 v9, 0
	s_and_saveexec_b64 s[58:59], s[40:41]
	s_cbranch_execz .LBB0_1243
	v_mad_i64_i32 v[10:11], s[28:29], v10, s91, 0
	v_lshl_add_u64 v[10:11], v[10:11], 2, s[0:1]
	s_mov_b64 s[28:29], 0x1000
	v_lshl_add_u64 v[18:19], v[10:11], 0, s[28:29]
	v_add_co_u32_e32 v10, vcc, 0x1000, v10
	s_nop 1
	v_addc_co_u32_e32 v11, vcc, 0, v11, vcc
	v_sub_u32_e32 v216, -2, v0
	v_mov_b32_e32 v217, v1
	v_lshl_add_u64 v[216:217], v[216:217], 2, s[76:77]
	s_mov_b64 s[98:99], 0x1000
	global_load_dword v200, v[216:217], off
	global_load_dword v201, v[216:217], off offset:1024
	global_load_dword v202, v[216:217], off offset:2048
	global_load_dword v203, v[216:217], off offset:3072
	v_lshl_add_u64 v[216:217], v[216:217], 0, s[98:99]
	global_load_dword v204, v[216:217], off
	global_load_dword v205, v[216:217], off offset:1024
	global_load_dword v206, v[216:217], off offset:2048
	global_load_dword v207, v[216:217], off offset:3072
	v_lshl_add_u64 v[216:217], v[216:217], 0, s[98:99]
	global_load_dword v208, v[216:217], off
	global_load_dword v209, v[216:217], off offset:1024
	global_load_dword v210, v[216:217], off offset:2048
	global_load_dword v211, v[216:217], off offset:3072
	v_lshl_add_u64 v[216:217], v[216:217], 0, s[98:99]
	global_load_dword v212, v[216:217], off
	global_load_dword v213, v[216:217], off offset:1024
	global_load_dword v214, v[216:217], off offset:2048
	global_load_dword v215, v[216:217], off offset:3072
	global_load_dwordx4 v[14:17], v[10:11], off
	s_nop 0
	global_load_dwordx4 v[10:13], v[18:19], off offset:48
	global_load_dwordx4 v[26:29], v[18:19], off offset:32
	global_load_dwordx4 v[30:33], v[18:19], off offset:16
	v_sub_u32_e32 v18, -2, v0
	v_mov_b32_e32 v19, v1
	v_lshl_add_u64 v[18:19], v[18:19], 2, s[76:77]
	v_sub_u32_e32 v18, 0xfe, v0
	v_ashrrev_i32_e32 v19, 31, v18
	v_lshl_add_u64 v[18:19], v[18:19], 2, s[76:77]
	s_waitcnt vmcnt(0)
	v_mov_b32_e32 v9, v200
	v_fma_f32 v9, v14, v9, 0
	s_waitcnt vmcnt(0)
	v_mov_b32_e32 v14, v201
	v_fmac_f32_e32 v9, v15, v14
	v_sub_u32_e32 v14, 0x1fe, v0
	v_ashrrev_i32_e32 v15, 31, v14
	v_lshl_add_u64 v[14:15], v[14:15], 2, s[76:77]
	s_waitcnt vmcnt(0)
	v_mov_b32_e32 v14, v202
	v_fmac_f32_e32 v9, v16, v14
	v_sub_u32_e32 v14, 0x2fe, v0
	v_ashrrev_i32_e32 v15, 31, v14
	v_lshl_add_u64 v[14:15], v[14:15], 2, s[76:77]
	v_sub_u32_e32 v16, 0x4fe, v0
	s_waitcnt vmcnt(0)
	v_mov_b32_e32 v14, v203
	v_fmac_f32_e32 v9, v17, v14
	v_sub_u32_e32 v14, 0x3fe, v0
	v_ashrrev_i32_e32 v15, 31, v14
	v_ashrrev_i32_e32 v17, 31, v16
	v_lshl_add_u64 v[14:15], v[14:15], 2, s[76:77]
	v_lshl_add_u64 v[16:17], v[16:17], 2, s[76:77]
	s_nop 0
	v_sub_u32_e32 v16, 0x6fe, v0
	v_ashrrev_i32_e32 v17, 31, v16
	v_lshl_add_u64 v[16:17], v[16:17], 2, s[76:77]
	s_waitcnt vmcnt(0)
	v_mov_b32_e32 v14, v204
	v_mov_b32_e32 v15, v205
	v_pk_mul_f32 v[14:15], v[30:31], v[14:15]
	s_nop 0
	v_add_f32_e32 v9, v9, v14
	v_sub_u32_e32 v14, 0x5fe, v0
	v_add_f32_e32 v9, v9, v15
	v_ashrrev_i32_e32 v15, 31, v14
	v_lshl_add_u64 v[14:15], v[14:15], 2, s[76:77]
	s_nop 0
	v_sub_u32_e32 v16, 0x8fe, v0
	v_ashrrev_i32_e32 v17, 31, v16
	v_lshl_add_u64 v[16:17], v[16:17], 2, s[76:77]
	s_waitcnt vmcnt(0)
	v_mov_b32_e32 v14, v206
	v_mov_b32_e32 v15, v207
	v_pk_mul_f32 v[14:15], v[32:33], v[14:15]
	s_nop 0
	v_add_f32_e32 v9, v9, v14
	v_sub_u32_e32 v14, 0x7fe, v0
	v_add_f32_e32 v9, v9, v15
	v_ashrrev_i32_e32 v15, 31, v14
	v_lshl_add_u64 v[14:15], v[14:15], 2, s[76:77]
	s_nop 0
	v_sub_u32_e32 v16, 0xafe, v0
	v_ashrrev_i32_e32 v17, 31, v16
	v_lshl_add_u64 v[16:17], v[16:17], 2, s[76:77]
	s_waitcnt vmcnt(0)
	v_mov_b32_e32 v14, v208
	v_mov_b32_e32 v15, v209
	v_pk_mul_f32 v[14:15], v[26:27], v[14:15]
	s_nop 0
	v_add_f32_e32 v9, v9, v14
	v_sub_u32_e32 v14, 0x9fe, v0
	v_add_f32_e32 v9, v9, v15
	v_ashrrev_i32_e32 v15, 31, v14
	v_lshl_add_u64 v[14:15], v[14:15], 2, s[76:77]
	s_nop 0
	v_sub_u32_e32 v16, 0xcfe, v0
	v_ashrrev_i32_e32 v17, 31, v16
	v_lshl_add_u64 v[16:17], v[16:17], 2, s[76:77]
	s_waitcnt vmcnt(0)
	v_mov_b32_e32 v14, v210
	v_mov_b32_e32 v15, v211
	v_pk_mul_f32 v[14:15], v[28:29], v[14:15]
	s_nop 0
	v_add_f32_e32 v9, v9, v14
	v_sub_u32_e32 v14, 0xbfe, v0
	v_add_f32_e32 v9, v9, v15
	v_ashrrev_i32_e32 v15, 31, v14
	v_lshl_add_u64 v[14:15], v[14:15], 2, s[76:77]
	s_nop 0
	s_waitcnt vmcnt(0)
	v_mov_b32_e32 v14, v212
	v_mov_b32_e32 v15, v213
	v_pk_mul_f32 v[10:11], v[10:11], v[14:15]
	s_nop 0
	v_add_f32_e32 v9, v9, v10
	v_sub_u32_e32 v10, 0xdfe, v0
	v_sub_u32_e32 v14, 0xefe, v0
	v_add_f32_e32 v9, v9, v11
	v_ashrrev_i32_e32 v11, 31, v10
	v_ashrrev_i32_e32 v15, 31, v14
	v_lshl_add_u64 v[10:11], v[10:11], 2, s[76:77]
	v_lshl_add_u64 v[14:15], v[14:15], 2, s[76:77]
	s_nop 0
	s_waitcnt vmcnt(0)
	v_mov_b32_e32 v10, v214
	v_mov_b32_e32 v11, v215
	v_pk_mul_f32 v[10:11], v[12:13], v[10:11]
	s_nop 0
	v_add_f32_e32 v9, v9, v10
	v_add_f32_e32 v9, v9, v11

.LBB0_1245:
	v_mov_b32_e32 v10, 0
	s_and_saveexec_b64 s[58:59], s[40:41]
	s_cbranch_execz .LBB0_1247
	v_mad_i64_i32 v[10:11], s[28:29], v11, s91, 0
	v_lshl_add_u64 v[10:11], v[10:11], 2, s[0:1]
	s_mov_b64 s[28:29], 0x1000
	v_lshl_add_u64 v[18:19], v[10:11], 0, s[28:29]
	v_add_co_u32_e32 v10, vcc, 0x1000, v10
	s_nop 1
	v_addc_co_u32_e32 v11, vcc, 0, v11, vcc
	v_sub_u32_e32 v216, -2, v0
	v_mov_b32_e32 v217, v1
	v_lshl_add_u64 v[216:217], v[216:217], 2, s[76:77]
	s_mov_b64 s[98:99], 0x1000
	global_load_dword v200, v[216:217], off
	global_load_dword v201, v[216:217], off offset:1024
	global_load_dword v202, v[216:217], off offset:2048
	global_load_dword v203, v[216:217], off offset:3072
	v_lshl_add_u64 v[216:217], v[216:217], 0, s[98:99]
	global_load_dword v204, v[216:217], off
	global_load_dword v205, v[216:217], off offset:1024
	global_load_dword v206, v[216:217], off offset:2048
	global_load_dword v207, v[216:217], off offset:3072
	v_lshl_add_u64 v[216:217], v[216:217], 0, s[98:99]
	global_load_dword v208, v[216:217], off
	global_load_dword v209, v[216:217], off offset:1024
	global_load_dword v210, v[216:217], off offset:2048
	global_load_dword v211, v[216:217], off offset:3072
	v_lshl_add_u64 v[216:217], v[216:217], 0, s[98:99]
	global_load_dword v212, v[216:217], off
	global_load_dword v213, v[216:217], off offset:1024
	global_load_dword v214, v[216:217], off offset:2048
	global_load_dword v215, v[216:217], off offset:3072
	global_load_dwordx4 v[14:17], v[10:11], off
	s_nop 0
	global_load_dwordx4 v[10:13], v[18:19], off offset:48
	global_load_dwordx4 v[26:29], v[18:19], off offset:32
	global_load_dwordx4 v[30:33], v[18:19], off offset:16
	v_sub_u32_e32 v18, -2, v0
	v_mov_b32_e32 v19, v1
	v_lshl_add_u64 v[18:19], v[18:19], 2, s[76:77]
	s_waitcnt vmcnt(0)
	v_mov_b32_e32 v18, v200
	v_fma_f32 v34, v14, v18, 0
	v_sub_u32_e32 v18, 0xfe, v0
	v_ashrrev_i32_e32 v19, 31, v18
	v_lshl_add_u64 v[18:19], v[18:19], 2, s[76:77]
	s_waitcnt vmcnt(0)
	v_mov_b32_e32 v14, v201
	v_fmac_f32_e32 v34, v15, v14
	v_sub_u32_e32 v14, 0x1fe, v0
	v_ashrrev_i32_e32 v15, 31, v14
	v_lshl_add_u64 v[14:15], v[14:15], 2, s[76:77]
	s_waitcnt vmcnt(0)
	v_mov_b32_e32 v14, v202
	v_fmac_f32_e32 v34, v16, v14
	v_sub_u32_e32 v14, 0x2fe, v0
	v_ashrrev_i32_e32 v15, 31, v14
	v_lshl_add_u64 v[14:15], v[14:15], 2, s[76:77]
	v_sub_u32_e32 v16, 0x4fe, v0
	s_waitcnt vmcnt(0)
	v_mov_b32_e32 v14, v203
	v_fmac_f32_e32 v34, v17, v14
	v_sub_u32_e32 v14, 0x3fe, v0
	v_ashrrev_i32_e32 v15, 31, v14
	v_ashrrev_i32_e32 v17, 31, v16
	v_lshl_add_u64 v[14:15], v[14:15], 2, s[76:77]
	v_lshl_add_u64 v[16:17], v[16:17], 2, s[76:77]
	s_nop 0
	v_sub_u32_e32 v16, 0x6fe, v0
	v_ashrrev_i32_e32 v17, 31, v16
	v_lshl_add_u64 v[16:17], v[16:17], 2, s[76:77]
	s_waitcnt vmcnt(0)
	v_mov_b32_e32 v14, v204
	v_mov_b32_e32 v15, v205
	v_pk_mul_f32 v[14:15], v[30:31], v[14:15]
	s_nop 0
	v_add_f32_e32 v14, v34, v14
	v_add_f32_e32 v18, v14, v15
	v_sub_u32_e32 v14, 0x5fe, v0
	v_ashrrev_i32_e32 v15, 31, v14
	v_lshl_add_u64 v[14:15], v[14:15], 2, s[76:77]
	s_nop 0
	v_sub_u32_e32 v16, 0x8fe, v0
	v_ashrrev_i32_e32 v17, 31, v16
	v_lshl_add_u64 v[16:17], v[16:17], 2, s[76:77]
	s_waitcnt vmcnt(0)
	v_mov_b32_e32 v14, v206
	v_mov_b32_e32 v15, v207
	v_pk_mul_f32 v[14:15], v[32:33], v[14:15]
	s_nop 0
	v_add_f32_e32 v14, v18, v14
	v_add_f32_e32 v18, v14, v15
	v_sub_u32_e32 v14, 0x7fe, v0
	v_ashrrev_i32_e32 v15, 31, v14
	v_lshl_add_u64 v[14:15], v[14:15], 2, s[76:77]
	s_nop 0
	v_sub_u32_e32 v16, 0xafe, v0
	v_ashrrev_i32_e32 v17, 31, v16
	v_lshl_add_u64 v[16:17], v[16:17], 2, s[76:77]
	s_waitcnt vmcnt(0)
	v_mov_b32_e32 v14, v208
	v_mov_b32_e32 v15, v209
	v_pk_mul_f32 v[14:15], v[26:27], v[14:15]
	s_nop 0
	v_add_f32_e32 v14, v18, v14
	v_add_f32_e32 v18, v14, v15
	v_sub_u32_e32 v14, 0x9fe, v0
	v_ashrrev_i32_e32 v15, 31, v14
	v_lshl_add_u64 v[14:15], v[14:15], 2, s[76:77]
	s_nop 0
	v_sub_u32_e32 v16, 0xcfe, v0
	v_ashrrev_i32_e32 v17, 31, v16
	v_lshl_add_u64 v[16:17], v[16:17], 2, s[76:77]
	s_waitcnt vmcnt(0)
	v_mov_b32_e32 v14, v210
	v_mov_b32_e32 v15, v211
	v_pk_mul_f32 v[14:15], v[28:29], v[14:15]
	s_nop 0
	v_add_f32_e32 v14, v18, v14
	v_add_f32_e32 v18, v14, v15
	v_sub_u32_e32 v14, 0xbfe, v0
	v_ashrrev_i32_e32 v15, 31, v14
	v_lshl_add_u64 v[14:15], v[14:15], 2, s[76:77]
	s_nop 0
	s_waitcnt vmcnt(0)
	v_mov_b32_e32 v14, v212
	v_mov_b32_e32 v15, v213
	v_pk_mul_f32 v[10:11], v[10:11], v[14:15]
	s_nop 0
	v_add_f32_e32 v10, v18, v10
	v_add_f32_e32 v16, v10, v11
	v_sub_u32_e32 v10, 0xdfe, v0
	v_sub_u32_e32 v14, 0xefe, v0
	v_ashrrev_i32_e32 v11, 31, v10
	v_ashrrev_i32_e32 v15, 31, v14
	v_lshl_add_u64 v[10:11], v[10:11], 2, s[76:77]
	v_lshl_add_u64 v[14:15], v[14:15], 2, s[76:77]
	s_nop 0
	s_waitcnt vmcnt(0)
	v_mov_b32_e32 v10, v214
	v_mov_b32_e32 v11, v215
	v_pk_mul_f32 v[10:11], v[12:13], v[10:11]
	s_nop 0
	v_add_f32_e32 v10, v16, v10
	v_add_f32_e32 v10, v10, v11

.LBB0_1249:
	v_mov_b32_e32 v11, 0
	s_and_saveexec_b64 s[58:59], s[40:41]
	s_cbranch_execz .LBB0_1251
	v_mad_i64_i32 v[12:13], s[28:29], v12, s91, 0
	v_lshl_add_u64 v[12:13], v[12:13], 2, s[0:1]
	s_mov_b64 s[28:29], 0x1000
	v_lshl_add_u64 v[30:31], v[12:13], 0, s[28:29]
	v_add_co_u32_e32 v12, vcc, 0x1000, v12
	v_sub_u32_e32 v34, -2, v0
	v_mov_b32_e32 v35, v1
	v_addc_co_u32_e32 v13, vcc, 0, v13, vcc
	v_lshl_add_u64 v[34:35], v[34:35], 2, s[76:77]
	v_sub_u32_e32 v216, -2, v0
	v_mov_b32_e32 v217, v1
	v_lshl_add_u64 v[216:217], v[216:217], 2, s[76:77]
	s_mov_b64 s[98:99], 0x1000
	global_load_dword v200, v[216:217], off
	global_load_dword v201, v[216:217], off offset:1024
	global_load_dword v202, v[216:217], off offset:2048
	global_load_dword v203, v[216:217], off offset:3072
	v_lshl_add_u64 v[216:217], v[216:217], 0, s[98:99]
	global_load_dword v204, v[216:217], off
	global_load_dword v205, v[216:217], off offset:1024
	global_load_dword v206, v[216:217], off offset:2048
	global_load_dword v207, v[216:217], off offset:3072
	v_lshl_add_u64 v[216:217], v[216:217], 0, s[98:99]
	global_load_dword v208, v[216:217], off
	global_load_dword v209, v[216:217], off offset:1024
	global_load_dword v210, v[216:217], off offset:2048
	global_load_dword v211, v[216:217], off offset:3072
	v_lshl_add_u64 v[216:217], v[216:217], 0, s[98:99]
	global_load_dword v212, v[216:217], off
	global_load_dword v213, v[216:217], off offset:1024
	global_load_dword v214, v[216:217], off offset:2048
	global_load_dword v215, v[216:217], off offset:3072
	global_load_dwordx4 v[16:19], v[12:13], off
	s_nop 0
	global_load_dwordx4 v[12:15], v[30:31], off offset:48
	global_load_dwordx4 v[26:29], v[30:31], off offset:32
	s_nop 0
	global_load_dwordx4 v[30:33], v[30:31], off offset:16
	s_nop 0
	v_sub_u32_e32 v34, 0xfe, v0
	v_ashrrev_i32_e32 v35, 31, v34
	v_lshl_add_u64 v[34:35], v[34:35], 2, s[76:77]
	s_waitcnt vmcnt(0)
	v_mov_b32_e32 v11, v200
	v_fma_f32 v11, v16, v11, 0
	s_waitcnt vmcnt(0)
	v_mov_b32_e32 v16, v201
	v_fmac_f32_e32 v11, v17, v16
	v_sub_u32_e32 v16, 0x1fe, v0
	v_ashrrev_i32_e32 v17, 31, v16
	v_lshl_add_u64 v[16:17], v[16:17], 2, s[76:77]
	s_waitcnt vmcnt(0)
	v_mov_b32_e32 v16, v202
	v_fmac_f32_e32 v11, v18, v16
	v_sub_u32_e32 v16, 0x2fe, v0
	v_ashrrev_i32_e32 v17, 31, v16
	v_lshl_add_u64 v[16:17], v[16:17], 2, s[76:77]
	v_sub_u32_e32 v18, 0x4fe, v0
	s_waitcnt vmcnt(0)
	v_mov_b32_e32 v16, v203
	v_fmac_f32_e32 v11, v19, v16
	v_sub_u32_e32 v16, 0x3fe, v0
	v_ashrrev_i32_e32 v17, 31, v16
	v_ashrrev_i32_e32 v19, 31, v18
	v_lshl_add_u64 v[16:17], v[16:17], 2, s[76:77]
	v_lshl_add_u64 v[18:19], v[18:19], 2, s[76:77]
	s_nop 0
	v_sub_u32_e32 v18, 0x6fe, v0
	v_ashrrev_i32_e32 v19, 31, v18
	v_lshl_add_u64 v[18:19], v[18:19], 2, s[76:77]
	s_waitcnt vmcnt(0)
	v_mov_b32_e32 v16, v204
	v_mov_b32_e32 v17, v205
	v_pk_mul_f32 v[16:17], v[30:31], v[16:17]
	s_nop 0
	v_add_f32_e32 v11, v11, v16
	v_sub_u32_e32 v16, 0x5fe, v0
	v_add_f32_e32 v11, v11, v17
	v_ashrrev_i32_e32 v17, 31, v16
	v_lshl_add_u64 v[16:17], v[16:17], 2, s[76:77]
	s_nop 0
	v_sub_u32_e32 v18, 0x8fe, v0
	v_ashrrev_i32_e32 v19, 31, v18
	v_lshl_add_u64 v[18:19], v[18:19], 2, s[76:77]
	s_waitcnt vmcnt(0)
	v_mov_b32_e32 v16, v206
	v_mov_b32_e32 v17, v207
	v_pk_mul_f32 v[16:17], v[32:33], v[16:17]
	s_nop 0
	v_add_f32_e32 v11, v11, v16
	v_sub_u32_e32 v16, 0x7fe, v0
	v_add_f32_e32 v11, v11, v17
	v_ashrrev_i32_e32 v17, 31, v16
	v_lshl_add_u64 v[16:17], v[16:17], 2, s[76:77]
	s_nop 0
	v_sub_u32_e32 v18, 0xafe, v0
	v_ashrrev_i32_e32 v19, 31, v18
	v_lshl_add_u64 v[18:19], v[18:19], 2, s[76:77]
	s_waitcnt vmcnt(0)
	v_mov_b32_e32 v16, v208
	v_mov_b32_e32 v17, v209
	v_pk_mul_f32 v[16:17], v[26:27], v[16:17]
	s_nop 0
	v_add_f32_e32 v11, v11, v16
	v_sub_u32_e32 v16, 0x9fe, v0
	v_add_f32_e32 v11, v11, v17
	v_ashrrev_i32_e32 v17, 31, v16
	v_lshl_add_u64 v[16:17], v[16:17], 2, s[76:77]
	s_nop 0
	v_sub_u32_e32 v18, 0xcfe, v0
	v_ashrrev_i32_e32 v19, 31, v18
	v_lshl_add_u64 v[18:19], v[18:19], 2, s[76:77]
	s_waitcnt vmcnt(0)
	v_mov_b32_e32 v16, v210
	v_mov_b32_e32 v17, v211
	v_pk_mul_f32 v[16:17], v[28:29], v[16:17]
	s_nop 0
	v_add_f32_e32 v11, v11, v16
	v_sub_u32_e32 v16, 0xbfe, v0
	v_add_f32_e32 v11, v11, v17
	v_ashrrev_i32_e32 v17, 31, v16
	v_lshl_add_u64 v[16:17], v[16:17], 2, s[76:77]
	s_nop 0
	s_waitcnt vmcnt(0)
	v_mov_b32_e32 v16, v212
	v_mov_b32_e32 v17, v213
	v_pk_mul_f32 v[12:13], v[12:13], v[16:17]
	s_nop 0
	v_add_f32_e32 v11, v11, v12
	v_sub_u32_e32 v12, 0xdfe, v0
	v_sub_u32_e32 v16, 0xefe, v0
	v_add_f32_e32 v11, v11, v13
	v_ashrrev_i32_e32 v13, 31, v12
	v_ashrrev_i32_e32 v17, 31, v16
	v_lshl_add_u64 v[12:13], v[12:13], 2, s[76:77]
	v_lshl_add_u64 v[16:17], v[16:17], 2, s[76:77]
	s_nop 0
	s_waitcnt vmcnt(0)
	v_mov_b32_e32 v12, v214
	v_mov_b32_e32 v13, v215
	v_pk_mul_f32 v[12:13], v[14:15], v[12:13]
	s_nop 0
	v_add_f32_e32 v11, v11, v12
	v_add_f32_e32 v11, v11, v13

.LBB0_1253:
	v_mov_b32_e32 v12, 0
	s_and_saveexec_b64 s[58:59], s[40:41]
	s_cbranch_execz .LBB0_1255
	v_mad_i64_i32 v[12:13], s[28:29], v13, s91, 0
	v_lshl_add_u64 v[12:13], v[12:13], 2, s[0:1]
	s_mov_b64 s[28:29], 0x1000
	v_lshl_add_u64 v[30:31], v[12:13], 0, s[28:29]
	v_add_co_u32_e32 v12, vcc, 0x1000, v12
	v_sub_u32_e32 v34, -2, v0
	v_mov_b32_e32 v35, v1
	v_addc_co_u32_e32 v13, vcc, 0, v13, vcc
	v_lshl_add_u64 v[34:35], v[34:35], 2, s[76:77]
	v_sub_u32_e32 v216, -2, v0
	v_mov_b32_e32 v217, v1
	v_lshl_add_u64 v[216:217], v[216:217], 2, s[76:77]
	s_mov_b64 s[98:99], 0x1000
	global_load_dword v200, v[216:217], off
	global_load_dword v201, v[216:217], off offset:1024
	global_load_dword v202, v[216:217], off offset:2048
	global_load_dword v203, v[216:217], off offset:3072
	v_lshl_add_u64 v[216:217], v[216:217], 0, s[98:99]
	global_load_dword v204, v[216:217], off
	global_load_dword v205, v[216:217], off offset:1024
	global_load_dword v206, v[216:217], off offset:2048
	global_load_dword v207, v[216:217], off offset:3072
	v_lshl_add_u64 v[216:217], v[216:217], 0, s[98:99]
	global_load_dword v208, v[216:217], off
	global_load_dword v209, v[216:217], off offset:1024
	global_load_dword v210, v[216:217], off offset:2048
	global_load_dword v211, v[216:217], off offset:3072
	v_lshl_add_u64 v[216:217], v[216:217], 0, s[98:99]
	global_load_dword v212, v[216:217], off
	global_load_dword v213, v[216:217], off offset:1024
	global_load_dword v214, v[216:217], off offset:2048
	global_load_dword v215, v[216:217], off offset:3072
	global_load_dwordx4 v[16:19], v[12:13], off
	s_nop 0
	global_load_dwordx4 v[12:15], v[30:31], off offset:48
	global_load_dwordx4 v[26:29], v[30:31], off offset:32
	s_nop 0
	global_load_dwordx4 v[30:33], v[30:31], off offset:16
	s_nop 0
	s_waitcnt vmcnt(0)
	v_mov_b32_e32 v34, v200
	v_fma_f32 v36, v16, v34, 0
	v_sub_u32_e32 v34, 0xfe, v0
	v_ashrrev_i32_e32 v35, 31, v34
	v_lshl_add_u64 v[34:35], v[34:35], 2, s[76:77]
	s_waitcnt vmcnt(0)
	v_mov_b32_e32 v16, v201
	v_fmac_f32_e32 v36, v17, v16
	v_sub_u32_e32 v16, 0x1fe, v0
	v_ashrrev_i32_e32 v17, 31, v16
	v_lshl_add_u64 v[16:17], v[16:17], 2, s[76:77]
	s_waitcnt vmcnt(0)
	v_mov_b32_e32 v16, v202
	v_fmac_f32_e32 v36, v18, v16
	v_sub_u32_e32 v16, 0x2fe, v0
	v_ashrrev_i32_e32 v17, 31, v16
	v_lshl_add_u64 v[16:17], v[16:17], 2, s[76:77]
	v_sub_u32_e32 v18, 0x4fe, v0
	s_waitcnt vmcnt(0)
	v_mov_b32_e32 v16, v203
	v_fmac_f32_e32 v36, v19, v16
	v_sub_u32_e32 v16, 0x3fe, v0
	v_ashrrev_i32_e32 v17, 31, v16
	v_ashrrev_i32_e32 v19, 31, v18
	v_lshl_add_u64 v[16:17], v[16:17], 2, s[76:77]
	v_lshl_add_u64 v[18:19], v[18:19], 2, s[76:77]
	s_nop 0
	v_sub_u32_e32 v18, 0x6fe, v0
	v_ashrrev_i32_e32 v19, 31, v18
	v_lshl_add_u64 v[18:19], v[18:19], 2, s[76:77]
	s_waitcnt vmcnt(0)
	v_mov_b32_e32 v16, v204
	v_mov_b32_e32 v17, v205
	v_pk_mul_f32 v[16:17], v[30:31], v[16:17]
	s_nop 0
	v_add_f32_e32 v16, v36, v16
	v_add_f32_e32 v30, v16, v17
	v_sub_u32_e32 v16, 0x5fe, v0
	v_ashrrev_i32_e32 v17, 31, v16
	v_lshl_add_u64 v[16:17], v[16:17], 2, s[76:77]
	s_nop 0
	v_sub_u32_e32 v18, 0x8fe, v0
	v_ashrrev_i32_e32 v19, 31, v18
	v_lshl_add_u64 v[18:19], v[18:19], 2, s[76:77]
	s_waitcnt vmcnt(0)
	v_mov_b32_e32 v16, v206
	v_mov_b32_e32 v17, v207
	v_pk_mul_f32 v[16:17], v[32:33], v[16:17]
	s_nop 0
	v_add_f32_e32 v16, v30, v16
	v_add_f32_e32 v30, v16, v17
	v_sub_u32_e32 v16, 0x7fe, v0
	v_ashrrev_i32_e32 v17, 31, v16
	v_lshl_add_u64 v[16:17], v[16:17], 2, s[76:77]
	s_nop 0
	v_sub_u32_e32 v18, 0xafe, v0
	v_ashrrev_i32_e32 v19, 31, v18
	v_lshl_add_u64 v[18:19], v[18:19], 2, s[76:77]
	s_waitcnt vmcnt(0)
	v_mov_b32_e32 v16, v208
	v_mov_b32_e32 v17, v209
	v_pk_mul_f32 v[16:17], v[26:27], v[16:17]
	s_nop 0
	v_add_f32_e32 v16, v30, v16
	v_add_f32_e32 v26, v16, v17
	v_sub_u32_e32 v16, 0x9fe, v0
	v_ashrrev_i32_e32 v17, 31, v16
	v_lshl_add_u64 v[16:17], v[16:17], 2, s[76:77]
	s_nop 0
	v_sub_u32_e32 v18, 0xcfe, v0
	v_ashrrev_i32_e32 v19, 31, v18
	v_lshl_add_u64 v[18:19], v[18:19], 2, s[76:77]
	s_waitcnt vmcnt(0)
	v_mov_b32_e32 v16, v210
	v_mov_b32_e32 v17, v211
	v_pk_mul_f32 v[16:17], v[28:29], v[16:17]
	s_nop 0
	v_add_f32_e32 v16, v26, v16
	v_add_f32_e32 v26, v16, v17
	v_sub_u32_e32 v16, 0xbfe, v0
	v_ashrrev_i32_e32 v17, 31, v16
	v_lshl_add_u64 v[16:17], v[16:17], 2, s[76:77]
	s_nop 0
	s_waitcnt vmcnt(0)
	v_mov_b32_e32 v16, v212
	v_mov_b32_e32 v17, v213
	v_pk_mul_f32 v[12:13], v[12:13], v[16:17]
	s_nop 0
	v_add_f32_e32 v12, v26, v12
	v_add_f32_e32 v18, v12, v13
	v_sub_u32_e32 v12, 0xdfe, v0
	v_sub_u32_e32 v16, 0xefe, v0
	v_ashrrev_i32_e32 v13, 31, v12
	v_ashrrev_i32_e32 v17, 31, v16
	v_lshl_add_u64 v[12:13], v[12:13], 2, s[76:77]
	v_lshl_add_u64 v[16:17], v[16:17], 2, s[76:77]
	s_nop 0
	s_waitcnt vmcnt(0)
	v_mov_b32_e32 v12, v214
	v_mov_b32_e32 v13, v215
	v_pk_mul_f32 v[12:13], v[14:15], v[12:13]
	s_nop 0
	v_add_f32_e32 v12, v18, v12
	v_add_f32_e32 v12, v12, v13

.LBB0_1257:
	v_mov_b32_e32 v13, 0
	s_and_saveexec_b64 s[58:59], s[40:41]
	s_cbranch_execz .LBB0_1259
	v_mad_i64_i32 v[14:15], s[28:29], v14, s91, 0
	v_lshl_add_u64 v[14:15], v[14:15], 2, s[0:1]
	s_mov_b64 s[28:29], 0x1000
	v_lshl_add_u64 v[18:19], v[14:15], 0, s[28:29]
	v_add_co_u32_e32 v14, vcc, 0x1000, v14
	s_nop 1
	v_addc_co_u32_e32 v15, vcc, 0, v15, vcc
	v_sub_u32_e32 v216, -2, v0
	v_mov_b32_e32 v217, v1
	v_lshl_add_u64 v[216:217], v[216:217], 2, s[76:77]
	s_mov_b64 s[98:99], 0x1000
	global_load_dword v200, v[216:217], off
	global_load_dword v201, v[216:217], off offset:1024
	global_load_dword v202, v[216:217], off offset:2048
	global_load_dword v203, v[216:217], off offset:3072
	v_lshl_add_u64 v[216:217], v[216:217], 0, s[98:99]
	global_load_dword v204, v[216:217], off
	global_load_dword v205, v[216:217], off offset:1024
	global_load_dword v206, v[216:217], off offset:2048
	global_load_dword v207, v[216:217], off offset:3072
	v_lshl_add_u64 v[216:217], v[216:217], 0, s[98:99]
	global_load_dword v208, v[216:217], off
	global_load_dword v209, v[216:217], off offset:1024
	global_load_dword v210, v[216:217], off offset:2048
	global_load_dword v211, v[216:217], off offset:3072
	v_lshl_add_u64 v[216:217], v[216:217], 0, s[98:99]
	global_load_dword v212, v[216:217], off
	global_load_dword v213, v[216:217], off offset:1024
	global_load_dword v214, v[216:217], off offset:2048
	global_load_dword v215, v[216:217], off offset:3072
	global_load_dwordx4 v[26:29], v[14:15], off
	s_nop 0
	global_load_dwordx4 v[14:17], v[18:19], off offset:48
	global_load_dwordx4 v[30:33], v[18:19], off offset:32
	global_load_dwordx4 v[34:37], v[18:19], off offset:16
	v_sub_u32_e32 v18, -2, v0
	v_mov_b32_e32 v19, v1
	v_lshl_add_u64 v[18:19], v[18:19], 2, s[76:77]
	v_sub_u32_e32 v18, 0xfe, v0
	v_ashrrev_i32_e32 v19, 31, v18
	v_lshl_add_u64 v[18:19], v[18:19], 2, s[76:77]
	s_waitcnt vmcnt(0)
	v_mov_b32_e32 v13, v200
	v_mov_b32_e32 v18, v201
	v_fma_f32 v13, v26, v13, 0
	v_sub_u32_e32 v26, 0x4fe, v0
	s_waitcnt vmcnt(0)
	v_fmac_f32_e32 v13, v27, v18
	v_sub_u32_e32 v18, 0x1fe, v0
	v_ashrrev_i32_e32 v19, 31, v18
	v_lshl_add_u64 v[18:19], v[18:19], 2, s[76:77]
	v_ashrrev_i32_e32 v27, 31, v26
	v_lshl_add_u64 v[26:27], v[26:27], 2, s[76:77]
	s_waitcnt vmcnt(0)
	v_mov_b32_e32 v18, v202
	v_fmac_f32_e32 v13, v28, v18
	v_sub_u32_e32 v18, 0x2fe, v0
	v_ashrrev_i32_e32 v19, 31, v18
	v_lshl_add_u64 v[18:19], v[18:19], 2, s[76:77]
	s_waitcnt vmcnt(0)
	v_mov_b32_e32 v18, v203
	v_fmac_f32_e32 v13, v29, v18
	v_sub_u32_e32 v18, 0x3fe, v0
	v_ashrrev_i32_e32 v19, 31, v18
	v_lshl_add_u64 v[18:19], v[18:19], 2, s[76:77]
	s_nop 0
	v_sub_u32_e32 v26, 0x6fe, v0
	v_ashrrev_i32_e32 v27, 31, v26
	v_lshl_add_u64 v[26:27], v[26:27], 2, s[76:77]
	s_waitcnt vmcnt(0)
	v_mov_b32_e32 v18, v204
	v_mov_b32_e32 v19, v205
	v_pk_mul_f32 v[18:19], v[34:35], v[18:19]
	s_nop 0
	v_add_f32_e32 v13, v13, v18
	v_sub_u32_e32 v18, 0x5fe, v0
	v_add_f32_e32 v13, v13, v19
	v_ashrrev_i32_e32 v19, 31, v18
	v_lshl_add_u64 v[18:19], v[18:19], 2, s[76:77]
	s_nop 0
	v_sub_u32_e32 v26, 0x8fe, v0
	v_ashrrev_i32_e32 v27, 31, v26
	v_lshl_add_u64 v[26:27], v[26:27], 2, s[76:77]
	s_waitcnt vmcnt(0)
	v_mov_b32_e32 v18, v206
	v_mov_b32_e32 v19, v207
	v_pk_mul_f32 v[18:19], v[36:37], v[18:19]
	s_nop 0
	v_add_f32_e32 v13, v13, v18
	v_sub_u32_e32 v18, 0x7fe, v0
	v_add_f32_e32 v13, v13, v19
	v_ashrrev_i32_e32 v19, 31, v18
	v_lshl_add_u64 v[18:19], v[18:19], 2, s[76:77]
	s_nop 0
	v_sub_u32_e32 v26, 0xafe, v0
	v_ashrrev_i32_e32 v27, 31, v26
	v_lshl_add_u64 v[26:27], v[26:27], 2, s[76:77]
	s_waitcnt vmcnt(0)
	v_mov_b32_e32 v18, v208
	v_mov_b32_e32 v19, v209
	v_pk_mul_f32 v[18:19], v[30:31], v[18:19]
	s_nop 0
	v_add_f32_e32 v13, v13, v18
	v_sub_u32_e32 v18, 0x9fe, v0
	v_add_f32_e32 v13, v13, v19
	v_ashrrev_i32_e32 v19, 31, v18
	v_lshl_add_u64 v[18:19], v[18:19], 2, s[76:77]
	s_nop 0
	v_sub_u32_e32 v26, 0xcfe, v0
	v_ashrrev_i32_e32 v27, 31, v26
	v_lshl_add_u64 v[26:27], v[26:27], 2, s[76:77]
	s_waitcnt vmcnt(0)
	v_mov_b32_e32 v18, v210
	v_mov_b32_e32 v19, v211
	v_pk_mul_f32 v[18:19], v[32:33], v[18:19]
	s_nop 0
	v_add_f32_e32 v13, v13, v18
	v_sub_u32_e32 v18, 0xbfe, v0
	v_add_f32_e32 v13, v13, v19
	v_ashrrev_i32_e32 v19, 31, v18
	v_lshl_add_u64 v[18:19], v[18:19], 2, s[76:77]
	s_nop 0
	s_waitcnt vmcnt(0)
	v_mov_b32_e32 v18, v212
	v_mov_b32_e32 v19, v213
	v_pk_mul_f32 v[14:15], v[14:15], v[18:19]
	s_nop 0
	v_add_f32_e32 v13, v13, v14
	v_sub_u32_e32 v14, 0xdfe, v0
	v_sub_u32_e32 v18, 0xefe, v0
	v_add_f32_e32 v13, v13, v15
	v_ashrrev_i32_e32 v15, 31, v14
	v_ashrrev_i32_e32 v19, 31, v18
	v_lshl_add_u64 v[14:15], v[14:15], 2, s[76:77]
	v_lshl_add_u64 v[18:19], v[18:19], 2, s[76:77]
	s_nop 0
	s_waitcnt vmcnt(0)
	v_mov_b32_e32 v14, v214
	v_mov_b32_e32 v15, v215
	v_pk_mul_f32 v[14:15], v[16:17], v[14:15]
	s_nop 0
	v_add_f32_e32 v13, v13, v14
	v_add_f32_e32 v13, v13, v15

.LBB0_1261:
	v_mov_b32_e32 v14, 0
	s_and_saveexec_b64 s[58:59], s[40:41]
	s_cbranch_execz .LBB0_1263
	v_mad_i64_i32 v[14:15], s[28:29], v15, s91, 0
	v_lshl_add_u64 v[14:15], v[14:15], 2, s[0:1]
	s_mov_b64 s[28:29], 0x1000
	v_lshl_add_u64 v[18:19], v[14:15], 0, s[28:29]
	v_add_co_u32_e32 v14, vcc, 0x1000, v14
	s_nop 1
	v_addc_co_u32_e32 v15, vcc, 0, v15, vcc
	v_sub_u32_e32 v216, -2, v0
	v_mov_b32_e32 v217, v1
	v_lshl_add_u64 v[216:217], v[216:217], 2, s[76:77]
	s_mov_b64 s[98:99], 0x1000
	global_load_dword v200, v[216:217], off
	global_load_dword v201, v[216:217], off offset:1024
	global_load_dword v202, v[216:217], off offset:2048
	global_load_dword v203, v[216:217], off offset:3072
	v_lshl_add_u64 v[216:217], v[216:217], 0, s[98:99]
	global_load_dword v204, v[216:217], off
	global_load_dword v205, v[216:217], off offset:1024
	global_load_dword v206, v[216:217], off offset:2048
	global_load_dword v207, v[216:217], off offset:3072
	v_lshl_add_u64 v[216:217], v[216:217], 0, s[98:99]
	global_load_dword v208, v[216:217], off
	global_load_dword v209, v[216:217], off offset:1024
	global_load_dword v210, v[216:217], off offset:2048
	global_load_dword v211, v[216:217], off offset:3072
	v_lshl_add_u64 v[216:217], v[216:217], 0, s[98:99]
	global_load_dword v212, v[216:217], off
	global_load_dword v213, v[216:217], off offset:1024
	global_load_dword v214, v[216:217], off offset:2048
	global_load_dword v215, v[216:217], off offset:3072
	global_load_dwordx4 v[26:29], v[14:15], off
	s_nop 0
	global_load_dwordx4 v[14:17], v[18:19], off offset:48
	global_load_dwordx4 v[30:33], v[18:19], off offset:32
	global_load_dwordx4 v[34:37], v[18:19], off offset:16
	v_sub_u32_e32 v18, -2, v0
	v_mov_b32_e32 v19, v1
	v_lshl_add_u64 v[18:19], v[18:19], 2, s[76:77]
	s_waitcnt vmcnt(0)
	v_mov_b32_e32 v18, v200
	v_fma_f32 v38, v26, v18, 0
	v_sub_u32_e32 v18, 0xfe, v0
	v_ashrrev_i32_e32 v19, 31, v18
	v_lshl_add_u64 v[18:19], v[18:19], 2, s[76:77]
	v_sub_u32_e32 v26, 0x4fe, v0
	s_waitcnt vmcnt(0)
	v_mov_b32_e32 v18, v201
	v_fmac_f32_e32 v38, v27, v18
	v_sub_u32_e32 v18, 0x1fe, v0
	v_ashrrev_i32_e32 v19, 31, v18
	v_lshl_add_u64 v[18:19], v[18:19], 2, s[76:77]
	v_ashrrev_i32_e32 v27, 31, v26
	v_lshl_add_u64 v[26:27], v[26:27], 2, s[76:77]
	s_waitcnt vmcnt(0)
	v_mov_b32_e32 v18, v202
	v_fmac_f32_e32 v38, v28, v18
	v_sub_u32_e32 v18, 0x2fe, v0
	v_ashrrev_i32_e32 v19, 31, v18
	v_lshl_add_u64 v[18:19], v[18:19], 2, s[76:77]
	s_waitcnt vmcnt(0)
	v_mov_b32_e32 v18, v203
	v_fmac_f32_e32 v38, v29, v18
	v_sub_u32_e32 v18, 0x3fe, v0
	v_ashrrev_i32_e32 v19, 31, v18
	v_lshl_add_u64 v[18:19], v[18:19], 2, s[76:77]
	s_nop 0
	v_sub_u32_e32 v26, 0x6fe, v0
	v_ashrrev_i32_e32 v27, 31, v26
	v_lshl_add_u64 v[26:27], v[26:27], 2, s[76:77]
	s_waitcnt vmcnt(0)
	v_mov_b32_e32 v18, v204
	v_mov_b32_e32 v19, v205
	v_pk_mul_f32 v[18:19], v[34:35], v[18:19]
	s_nop 0
	v_add_f32_e32 v18, v38, v18
	v_add_f32_e32 v28, v18, v19
	v_sub_u32_e32 v18, 0x5fe, v0
	v_ashrrev_i32_e32 v19, 31, v18
	v_lshl_add_u64 v[18:19], v[18:19], 2, s[76:77]
	s_nop 0
	v_sub_u32_e32 v26, 0x8fe, v0
	v_ashrrev_i32_e32 v27, 31, v26
	v_lshl_add_u64 v[26:27], v[26:27], 2, s[76:77]
	s_waitcnt vmcnt(0)
	v_mov_b32_e32 v18, v206
	v_mov_b32_e32 v19, v207
	v_pk_mul_f32 v[18:19], v[36:37], v[18:19]
	s_nop 0
	v_add_f32_e32 v18, v28, v18
	v_add_f32_e32 v28, v18, v19
	v_sub_u32_e32 v18, 0x7fe, v0
	v_ashrrev_i32_e32 v19, 31, v18
	v_lshl_add_u64 v[18:19], v[18:19], 2, s[76:77]
	s_nop 0
	v_sub_u32_e32 v26, 0xafe, v0
	v_ashrrev_i32_e32 v27, 31, v26
	v_lshl_add_u64 v[26:27], v[26:27], 2, s[76:77]
	s_waitcnt vmcnt(0)
	v_mov_b32_e32 v18, v208
	v_mov_b32_e32 v19, v209
	v_pk_mul_f32 v[18:19], v[30:31], v[18:19]
	s_nop 0
	v_add_f32_e32 v18, v28, v18
	v_add_f32_e32 v28, v18, v19
	v_sub_u32_e32 v18, 0x9fe, v0
	v_ashrrev_i32_e32 v19, 31, v18
	v_lshl_add_u64 v[18:19], v[18:19], 2, s[76:77]
	s_nop 0
	v_sub_u32_e32 v26, 0xcfe, v0
	v_ashrrev_i32_e32 v27, 31, v26
	v_lshl_add_u64 v[26:27], v[26:27], 2, s[76:77]
	s_waitcnt vmcnt(0)
	v_mov_b32_e32 v18, v210
	v_mov_b32_e32 v19, v211
	v_pk_mul_f32 v[18:19], v[32:33], v[18:19]
	s_nop 0
	v_add_f32_e32 v18, v28, v18
	v_add_f32_e32 v28, v18, v19
	v_sub_u32_e32 v18, 0xbfe, v0
	v_ashrrev_i32_e32 v19, 31, v18
	v_lshl_add_u64 v[18:19], v[18:19], 2, s[76:77]
	s_nop 0
	s_waitcnt vmcnt(0)
	v_mov_b32_e32 v18, v212
	v_mov_b32_e32 v19, v213
	v_pk_mul_f32 v[14:15], v[14:15], v[18:19]
	s_nop 0
	v_add_f32_e32 v14, v28, v14
	v_add_f32_e32 v26, v14, v15
	v_sub_u32_e32 v14, 0xdfe, v0
	v_sub_u32_e32 v18, 0xefe, v0
	v_ashrrev_i32_e32 v15, 31, v14
	v_ashrrev_i32_e32 v19, 31, v18
	v_lshl_add_u64 v[14:15], v[14:15], 2, s[76:77]
	v_lshl_add_u64 v[18:19], v[18:19], 2, s[76:77]
	s_nop 0
	s_waitcnt vmcnt(0)
	v_mov_b32_e32 v14, v214
	v_mov_b32_e32 v15, v215
	v_pk_mul_f32 v[14:15], v[16:17], v[14:15]
	s_nop 0
	v_add_f32_e32 v14, v26, v14
	v_add_f32_e32 v14, v14, v15

.LBB0_1265:
	v_mov_b32_e32 v15, 0
	s_and_saveexec_b64 s[58:59], s[40:41]
	s_cbranch_execz .LBB0_1267
	v_mad_i64_i32 v[16:17], s[28:29], v16, s91, 0
	v_lshl_add_u64 v[16:17], v[16:17], 2, s[0:1]
	s_mov_b64 s[28:29], 0x1000
	v_lshl_add_u64 v[34:35], v[16:17], 0, s[28:29]
	v_add_co_u32_e32 v16, vcc, 0x1000, v16
	v_sub_u32_e32 v38, -2, v0
	v_mov_b32_e32 v39, v1
	v_addc_co_u32_e32 v17, vcc, 0, v17, vcc
	v_lshl_add_u64 v[38:39], v[38:39], 2, s[76:77]
	v_sub_u32_e32 v216, -2, v0
	v_mov_b32_e32 v217, v1
	v_lshl_add_u64 v[216:217], v[216:217], 2, s[76:77]
	s_mov_b64 s[98:99], 0x1000
	global_load_dword v200, v[216:217], off
	global_load_dword v201, v[216:217], off offset:1024
	global_load_dword v202, v[216:217], off offset:2048
	global_load_dword v203, v[216:217], off offset:3072
	v_lshl_add_u64 v[216:217], v[216:217], 0, s[98:99]
	global_load_dword v204, v[216:217], off
	global_load_dword v205, v[216:217], off offset:1024
	global_load_dword v206, v[216:217], off offset:2048
	global_load_dword v207, v[216:217], off offset:3072
	v_lshl_add_u64 v[216:217], v[216:217], 0, s[98:99]
	global_load_dword v208, v[216:217], off
	global_load_dword v209, v[216:217], off offset:1024
	global_load_dword v210, v[216:217], off offset:2048
	global_load_dword v211, v[216:217], off offset:3072
	v_lshl_add_u64 v[216:217], v[216:217], 0, s[98:99]
	global_load_dword v212, v[216:217], off
	global_load_dword v213, v[216:217], off offset:1024
	global_load_dword v214, v[216:217], off offset:2048
	global_load_dword v215, v[216:217], off offset:3072
	global_load_dwordx4 v[26:29], v[16:17], off
	s_nop 0
	global_load_dwordx4 v[16:19], v[34:35], off offset:48
	global_load_dwordx4 v[30:33], v[34:35], off offset:32
	s_nop 0
	global_load_dwordx4 v[34:37], v[34:35], off offset:16
	s_nop 0
	v_sub_u32_e32 v38, 0xfe, v0
	v_ashrrev_i32_e32 v39, 31, v38
	v_lshl_add_u64 v[38:39], v[38:39], 2, s[76:77]
	s_waitcnt vmcnt(0)
	v_mov_b32_e32 v15, v200
	v_fma_f32 v15, v26, v15, 0
	s_waitcnt vmcnt(0)
	v_mov_b32_e32 v26, v201
	v_fmac_f32_e32 v15, v27, v26
	v_sub_u32_e32 v26, 0x1fe, v0
	v_ashrrev_i32_e32 v27, 31, v26
	v_lshl_add_u64 v[26:27], v[26:27], 2, s[76:77]
	s_waitcnt vmcnt(0)
	v_mov_b32_e32 v26, v202
	v_fmac_f32_e32 v15, v28, v26
	v_sub_u32_e32 v26, 0x2fe, v0
	v_ashrrev_i32_e32 v27, 31, v26
	v_lshl_add_u64 v[26:27], v[26:27], 2, s[76:77]
	v_sub_u32_e32 v28, 0x4fe, v0
	s_waitcnt vmcnt(0)
	v_mov_b32_e32 v26, v203
	v_fmac_f32_e32 v15, v29, v26
	v_sub_u32_e32 v26, 0x3fe, v0
	v_ashrrev_i32_e32 v27, 31, v26
	v_ashrrev_i32_e32 v29, 31, v28
	v_lshl_add_u64 v[26:27], v[26:27], 2, s[76:77]
	v_lshl_add_u64 v[28:29], v[28:29], 2, s[76:77]
	s_nop 0
	v_sub_u32_e32 v28, 0x6fe, v0
	v_ashrrev_i32_e32 v29, 31, v28
	v_lshl_add_u64 v[28:29], v[28:29], 2, s[76:77]
	s_waitcnt vmcnt(0)
	v_mov_b32_e32 v26, v204
	v_mov_b32_e32 v27, v205
	v_pk_mul_f32 v[26:27], v[34:35], v[26:27]
	s_nop 0
	v_add_f32_e32 v15, v15, v26
	v_sub_u32_e32 v26, 0x5fe, v0
	v_add_f32_e32 v15, v15, v27
	v_ashrrev_i32_e32 v27, 31, v26
	v_lshl_add_u64 v[26:27], v[26:27], 2, s[76:77]
	s_nop 0
	v_sub_u32_e32 v28, 0x8fe, v0
	v_ashrrev_i32_e32 v29, 31, v28
	v_lshl_add_u64 v[28:29], v[28:29], 2, s[76:77]
	s_waitcnt vmcnt(0)
	v_mov_b32_e32 v26, v206
	v_mov_b32_e32 v27, v207
	v_pk_mul_f32 v[26:27], v[36:37], v[26:27]
	s_nop 0
	v_add_f32_e32 v15, v15, v26
	v_sub_u32_e32 v26, 0x7fe, v0
	v_add_f32_e32 v15, v15, v27
	v_ashrrev_i32_e32 v27, 31, v26
	v_lshl_add_u64 v[26:27], v[26:27], 2, s[76:77]
	s_nop 0
	v_sub_u32_e32 v28, 0xafe, v0
	v_ashrrev_i32_e32 v29, 31, v28
	v_lshl_add_u64 v[28:29], v[28:29], 2, s[76:77]
	s_waitcnt vmcnt(0)
	v_mov_b32_e32 v26, v208
	v_mov_b32_e32 v27, v209
	v_pk_mul_f32 v[26:27], v[30:31], v[26:27]
	s_nop 0
	v_add_f32_e32 v15, v15, v26
	v_sub_u32_e32 v26, 0x9fe, v0
	v_add_f32_e32 v15, v15, v27
	v_ashrrev_i32_e32 v27, 31, v26
	v_lshl_add_u64 v[26:27], v[26:27], 2, s[76:77]
	s_nop 0
	v_sub_u32_e32 v28, 0xcfe, v0
	v_ashrrev_i32_e32 v29, 31, v28
	v_lshl_add_u64 v[28:29], v[28:29], 2, s[76:77]
	s_waitcnt vmcnt(0)
	v_mov_b32_e32 v26, v210
	v_mov_b32_e32 v27, v211
	v_pk_mul_f32 v[26:27], v[32:33], v[26:27]
	s_nop 0
	v_add_f32_e32 v15, v15, v26
	v_sub_u32_e32 v26, 0xbfe, v0
	v_add_f32_e32 v15, v15, v27
	v_ashrrev_i32_e32 v27, 31, v26
	v_lshl_add_u64 v[26:27], v[26:27], 2, s[76:77]
	s_nop 0
	s_waitcnt vmcnt(0)
	v_mov_b32_e32 v26, v212
	v_mov_b32_e32 v27, v213
	v_pk_mul_f32 v[16:17], v[16:17], v[26:27]
	s_nop 0
	v_add_f32_e32 v15, v15, v16
	v_sub_u32_e32 v16, 0xdfe, v0
	v_sub_u32_e32 v26, 0xefe, v0
	v_add_f32_e32 v15, v15, v17
	v_ashrrev_i32_e32 v17, 31, v16
	v_ashrrev_i32_e32 v27, 31, v26
	v_lshl_add_u64 v[16:17], v[16:17], 2, s[76:77]
	v_lshl_add_u64 v[26:27], v[26:27], 2, s[76:77]
	s_nop 0
	s_waitcnt vmcnt(0)
	v_mov_b32_e32 v16, v214
	v_mov_b32_e32 v17, v215
	v_pk_mul_f32 v[16:17], v[18:19], v[16:17]
	s_nop 0
	v_add_f32_e32 v15, v15, v16
	v_add_f32_e32 v15, v15, v17

.LBB0_1269:
	v_mov_b32_e32 v16, 0
	s_and_saveexec_b64 s[58:59], s[40:41]
	s_cbranch_execz .LBB0_1271
	v_mad_i64_i32 v[16:17], s[28:29], v17, s91, 0
	v_lshl_add_u64 v[16:17], v[16:17], 2, s[0:1]
	s_mov_b64 s[28:29], 0x1000
	v_lshl_add_u64 v[34:35], v[16:17], 0, s[28:29]
	v_add_co_u32_e32 v16, vcc, 0x1000, v16
	v_sub_u32_e32 v38, -2, v0
	v_mov_b32_e32 v39, v1
	v_addc_co_u32_e32 v17, vcc, 0, v17, vcc
	v_lshl_add_u64 v[38:39], v[38:39], 2, s[76:77]
	v_sub_u32_e32 v216, -2, v0
	v_mov_b32_e32 v217, v1
	v_lshl_add_u64 v[216:217], v[216:217], 2, s[76:77]
	s_mov_b64 s[98:99], 0x1000
	global_load_dword v200, v[216:217], off
	global_load_dword v201, v[216:217], off offset:1024
	global_load_dword v202, v[216:217], off offset:2048
	global_load_dword v203, v[216:217], off offset:3072
	v_lshl_add_u64 v[216:217], v[216:217], 0, s[98:99]
	global_load_dword v204, v[216:217], off
	global_load_dword v205, v[216:217], off offset:1024
	global_load_dword v206, v[216:217], off offset:2048
	global_load_dword v207, v[216:217], off offset:3072
	v_lshl_add_u64 v[216:217], v[216:217], 0, s[98:99]
	global_load_dword v208, v[216:217], off
	global_load_dword v209, v[216:217], off offset:1024
	global_load_dword v210, v[216:217], off offset:2048
	global_load_dword v211, v[216:217], off offset:3072
	v_lshl_add_u64 v[216:217], v[216:217], 0, s[98:99]
	global_load_dword v212, v[216:217], off
	global_load_dword v213, v[216:217], off offset:1024
	global_load_dword v214, v[216:217], off offset:2048
	global_load_dword v215, v[216:217], off offset:3072
	global_load_dwordx4 v[26:29], v[16:17], off
	s_nop 0
	global_load_dwordx4 v[16:19], v[34:35], off offset:48
	global_load_dwordx4 v[30:33], v[34:35], off offset:32
	s_nop 0
	global_load_dwordx4 v[34:37], v[34:35], off offset:16
	s_nop 0
	s_waitcnt vmcnt(0)
	v_mov_b32_e32 v38, v200
	v_fma_f32 v40, v26, v38, 0
	v_sub_u32_e32 v38, 0xfe, v0
	v_ashrrev_i32_e32 v39, 31, v38
	v_lshl_add_u64 v[38:39], v[38:39], 2, s[76:77]
	s_waitcnt vmcnt(0)
	v_mov_b32_e32 v26, v201
	v_fmac_f32_e32 v40, v27, v26
	v_sub_u32_e32 v26, 0x1fe, v0
	v_ashrrev_i32_e32 v27, 31, v26
	v_lshl_add_u64 v[26:27], v[26:27], 2, s[76:77]
	s_waitcnt vmcnt(0)
	v_mov_b32_e32 v26, v202
	v_fmac_f32_e32 v40, v28, v26
	v_sub_u32_e32 v26, 0x2fe, v0
	v_ashrrev_i32_e32 v27, 31, v26
	v_lshl_add_u64 v[26:27], v[26:27], 2, s[76:77]
	v_sub_u32_e32 v28, 0x4fe, v0
	s_waitcnt vmcnt(0)
	v_mov_b32_e32 v26, v203
	v_fmac_f32_e32 v40, v29, v26
	v_sub_u32_e32 v26, 0x3fe, v0
	v_ashrrev_i32_e32 v27, 31, v26
	v_ashrrev_i32_e32 v29, 31, v28
	v_lshl_add_u64 v[26:27], v[26:27], 2, s[76:77]
	v_lshl_add_u64 v[28:29], v[28:29], 2, s[76:77]
	s_nop 0
	v_sub_u32_e32 v28, 0x6fe, v0
	v_ashrrev_i32_e32 v29, 31, v28
	v_lshl_add_u64 v[28:29], v[28:29], 2, s[76:77]
	s_waitcnt vmcnt(0)
	v_mov_b32_e32 v26, v204
	v_mov_b32_e32 v27, v205
	v_pk_mul_f32 v[26:27], v[34:35], v[26:27]
	s_nop 0
	v_add_f32_e32 v26, v40, v26
	v_add_f32_e32 v34, v26, v27
	v_sub_u32_e32 v26, 0x5fe, v0
	v_ashrrev_i32_e32 v27, 31, v26
	v_lshl_add_u64 v[26:27], v[26:27], 2, s[76:77]
	s_nop 0
	v_sub_u32_e32 v28, 0x8fe, v0
	v_ashrrev_i32_e32 v29, 31, v28
	v_lshl_add_u64 v[28:29], v[28:29], 2, s[76:77]
	s_waitcnt vmcnt(0)
	v_mov_b32_e32 v26, v206
	v_mov_b32_e32 v27, v207
	v_pk_mul_f32 v[26:27], v[36:37], v[26:27]
	s_nop 0
	v_add_f32_e32 v26, v34, v26
	v_add_f32_e32 v34, v26, v27
	v_sub_u32_e32 v26, 0x7fe, v0
	v_ashrrev_i32_e32 v27, 31, v26
	v_lshl_add_u64 v[26:27], v[26:27], 2, s[76:77]
	s_nop 0
	v_sub_u32_e32 v28, 0xafe, v0
	v_ashrrev_i32_e32 v29, 31, v28
	v_lshl_add_u64 v[28:29], v[28:29], 2, s[76:77]
	s_waitcnt vmcnt(0)
	v_mov_b32_e32 v26, v208
	v_mov_b32_e32 v27, v209
	v_pk_mul_f32 v[26:27], v[30:31], v[26:27]
	s_nop 0
	v_add_f32_e32 v26, v34, v26
	v_add_f32_e32 v30, v26, v27
	v_sub_u32_e32 v26, 0x9fe, v0
	v_ashrrev_i32_e32 v27, 31, v26
	v_lshl_add_u64 v[26:27], v[26:27], 2, s[76:77]
	s_nop 0
	v_sub_u32_e32 v28, 0xcfe, v0
	v_ashrrev_i32_e32 v29, 31, v28
	v_lshl_add_u64 v[28:29], v[28:29], 2, s[76:77]
	s_waitcnt vmcnt(0)
	v_mov_b32_e32 v26, v210
	v_mov_b32_e32 v27, v211
	v_pk_mul_f32 v[26:27], v[32:33], v[26:27]
	s_nop 0
	v_add_f32_e32 v26, v30, v26
	v_add_f32_e32 v30, v26, v27
	v_sub_u32_e32 v26, 0xbfe, v0
	v_ashrrev_i32_e32 v27, 31, v26
	v_lshl_add_u64 v[26:27], v[26:27], 2, s[76:77]
	s_nop 0
	s_waitcnt vmcnt(0)
	v_mov_b32_e32 v26, v212
	v_mov_b32_e32 v27, v213
	v_pk_mul_f32 v[16:17], v[16:17], v[26:27]
	s_nop 0
	v_add_f32_e32 v16, v30, v16
	v_add_f32_e32 v28, v16, v17
	v_sub_u32_e32 v16, 0xdfe, v0
	v_sub_u32_e32 v26, 0xefe, v0
	v_ashrrev_i32_e32 v17, 31, v16
	v_ashrrev_i32_e32 v27, 31, v26
	v_lshl_add_u64 v[16:17], v[16:17], 2, s[76:77]
	v_lshl_add_u64 v[26:27], v[26:27], 2, s[76:77]
	s_nop 0
	s_waitcnt vmcnt(0)
	v_mov_b32_e32 v16, v214
	v_mov_b32_e32 v17, v215
	v_pk_mul_f32 v[16:17], v[18:19], v[16:17]
	s_nop 0
	v_add_f32_e32 v16, v28, v16
	v_add_f32_e32 v16, v16, v17

.LBB0_1273:
	v_mov_b32_e32 v17, 0
	s_and_saveexec_b64 s[42:43], s[40:41]
	s_cbranch_execz .LBB0_1275
	v_mad_i64_i32 v[18:19], s[28:29], v18, s91, 0
	v_lshl_add_u64 v[18:19], v[18:19], 2, s[0:1]
	s_mov_b64 s[28:29], 0x1000
	v_lshl_add_u64 v[34:35], v[18:19], 0, s[28:29]
	v_add_co_u32_e32 v18, vcc, 0x1000, v18
	v_sub_u32_e32 v38, -2, v0
	v_mov_b32_e32 v39, v1
	v_addc_co_u32_e32 v19, vcc, 0, v19, vcc
	v_lshl_add_u64 v[38:39], v[38:39], 2, s[76:77]
	v_sub_u32_e32 v216, -2, v0
	v_mov_b32_e32 v217, v1
	v_lshl_add_u64 v[216:217], v[216:217], 2, s[76:77]
	s_mov_b64 s[98:99], 0x1000
	global_load_dword v200, v[216:217], off
	global_load_dword v201, v[216:217], off offset:1024
	global_load_dword v202, v[216:217], off offset:2048
	global_load_dword v203, v[216:217], off offset:3072
	v_lshl_add_u64 v[216:217], v[216:217], 0, s[98:99]
	global_load_dword v204, v[216:217], off
	global_load_dword v205, v[216:217], off offset:1024
	global_load_dword v206, v[216:217], off offset:2048
	global_load_dword v207, v[216:217], off offset:3072
	v_lshl_add_u64 v[216:217], v[216:217], 0, s[98:99]
	global_load_dword v208, v[216:217], off
	global_load_dword v209, v[216:217], off offset:1024
	global_load_dword v210, v[216:217], off offset:2048
	global_load_dword v211, v[216:217], off offset:3072
	v_lshl_add_u64 v[216:217], v[216:217], 0, s[98:99]
	global_load_dword v212, v[216:217], off
	global_load_dword v213, v[216:217], off offset:1024
	global_load_dword v214, v[216:217], off offset:2048
	global_load_dword v215, v[216:217], off offset:3072
	global_load_dwordx4 v[26:29], v[18:19], off
	s_nop 0
	global_load_dwordx4 v[18:21], v[34:35], off offset:48
	global_load_dwordx4 v[30:33], v[34:35], off offset:32
	s_nop 0
	global_load_dwordx4 v[34:37], v[34:35], off offset:16
	s_nop 0
	v_sub_u32_e32 v38, 0xfe, v0
	v_ashrrev_i32_e32 v39, 31, v38
	v_lshl_add_u64 v[38:39], v[38:39], 2, s[76:77]
	s_waitcnt vmcnt(0)
	v_mov_b32_e32 v17, v200
	v_fma_f32 v17, v26, v17, 0
	s_waitcnt vmcnt(0)
	v_mov_b32_e32 v26, v201
	v_fmac_f32_e32 v17, v27, v26
	v_sub_u32_e32 v26, 0x1fe, v0
	v_ashrrev_i32_e32 v27, 31, v26
	v_lshl_add_u64 v[26:27], v[26:27], 2, s[76:77]
	s_waitcnt vmcnt(0)
	v_mov_b32_e32 v26, v202
	v_fmac_f32_e32 v17, v28, v26
	v_sub_u32_e32 v26, 0x2fe, v0
	v_ashrrev_i32_e32 v27, 31, v26
	v_lshl_add_u64 v[26:27], v[26:27], 2, s[76:77]
	v_sub_u32_e32 v28, 0x4fe, v0
	s_waitcnt vmcnt(0)
	v_mov_b32_e32 v26, v203
	v_fmac_f32_e32 v17, v29, v26
	v_sub_u32_e32 v26, 0x3fe, v0
	v_ashrrev_i32_e32 v27, 31, v26
	v_ashrrev_i32_e32 v29, 31, v28
	v_lshl_add_u64 v[26:27], v[26:27], 2, s[76:77]
	v_lshl_add_u64 v[28:29], v[28:29], 2, s[76:77]
	s_nop 0
	v_sub_u32_e32 v28, 0x6fe, v0
	v_ashrrev_i32_e32 v29, 31, v28
	v_lshl_add_u64 v[28:29], v[28:29], 2, s[76:77]
	s_waitcnt vmcnt(0)
	v_mov_b32_e32 v26, v204
	v_mov_b32_e32 v27, v205
	v_pk_mul_f32 v[26:27], v[34:35], v[26:27]
	s_nop 0
	v_add_f32_e32 v17, v17, v26
	v_sub_u32_e32 v26, 0x5fe, v0
	v_add_f32_e32 v17, v17, v27
	v_ashrrev_i32_e32 v27, 31, v26
	v_lshl_add_u64 v[26:27], v[26:27], 2, s[76:77]
	s_nop 0
	v_sub_u32_e32 v28, 0x8fe, v0
	v_ashrrev_i32_e32 v29, 31, v28
	v_lshl_add_u64 v[28:29], v[28:29], 2, s[76:77]
	s_waitcnt vmcnt(0)
	v_mov_b32_e32 v26, v206
	v_mov_b32_e32 v27, v207
	v_pk_mul_f32 v[26:27], v[36:37], v[26:27]
	s_nop 0
	v_add_f32_e32 v17, v17, v26
	v_sub_u32_e32 v26, 0x7fe, v0
	v_add_f32_e32 v17, v17, v27
	v_ashrrev_i32_e32 v27, 31, v26
	v_lshl_add_u64 v[26:27], v[26:27], 2, s[76:77]
	s_nop 0
	v_sub_u32_e32 v28, 0xafe, v0
	v_ashrrev_i32_e32 v29, 31, v28
	v_lshl_add_u64 v[28:29], v[28:29], 2, s[76:77]
	s_waitcnt vmcnt(0)
	v_mov_b32_e32 v26, v208
	v_mov_b32_e32 v27, v209
	v_pk_mul_f32 v[26:27], v[30:31], v[26:27]
	s_nop 0
	v_add_f32_e32 v17, v17, v26
	v_sub_u32_e32 v26, 0x9fe, v0
	v_add_f32_e32 v17, v17, v27
	v_ashrrev_i32_e32 v27, 31, v26
	v_lshl_add_u64 v[26:27], v[26:27], 2, s[76:77]
	s_nop 0
	v_sub_u32_e32 v28, 0xcfe, v0
	v_ashrrev_i32_e32 v29, 31, v28
	v_lshl_add_u64 v[28:29], v[28:29], 2, s[76:77]
	s_waitcnt vmcnt(0)
	v_mov_b32_e32 v26, v210
	v_mov_b32_e32 v27, v211
	v_pk_mul_f32 v[26:27], v[32:33], v[26:27]
	s_nop 0
	v_add_f32_e32 v17, v17, v26
	v_sub_u32_e32 v26, 0xbfe, v0
	v_add_f32_e32 v17, v17, v27
	v_ashrrev_i32_e32 v27, 31, v26
	v_lshl_add_u64 v[26:27], v[26:27], 2, s[76:77]
	s_nop 0
	s_waitcnt vmcnt(0)
	v_mov_b32_e32 v26, v212
	v_mov_b32_e32 v27, v213
	v_pk_mul_f32 v[18:19], v[18:19], v[26:27]
	s_nop 0
	v_add_f32_e32 v17, v17, v18
	v_sub_u32_e32 v18, 0xdfe, v0
	v_sub_u32_e32 v26, 0xefe, v0
	v_add_f32_e32 v17, v17, v19
	v_ashrrev_i32_e32 v19, 31, v18
	v_ashrrev_i32_e32 v27, 31, v26
	v_lshl_add_u64 v[18:19], v[18:19], 2, s[76:77]
	v_lshl_add_u64 v[26:27], v[26:27], 2, s[76:77]
	s_nop 0
	s_waitcnt vmcnt(0)
	v_mov_b32_e32 v18, v214
	v_mov_b32_e32 v19, v215
	v_pk_mul_f32 v[18:19], v[20:21], v[18:19]
	s_nop 0
	v_add_f32_e32 v0, v17, v18
	v_add_f32_e32 v17, v0, v19
